# v066: v064 with all per-segment s_setprio toggles removed from the K-loops (no priority)
# speedup vs baseline: 1.0012x; 1.0012x over previous
; #define PG8_STAGE(bufoff, gbase, voff) do { _Pragma("unroll") for (int _i = 0; _i < 2; ++_i) \
;         __builtin_amdgcn_global_load_lds((const unsigned*)((const char*)(gbase) + (voff)[_i]), (PG8_LAS unsigned*)(lds + (bufoff) + ldsw + _i * 8192), 16, 0, 0); } while (0)
; #define PG8_WAIT_V(n) asm volatile("s_waitcnt vmcnt(" #n ")" ::: "memory")
; #define PG8_WAIT_L(n) asm volatile("s_waitcnt lgkmcnt(" #n ")" ::: "memory")
; template <class Epi, class Sched, bool ALIGN_EPI = false, bool SP2 = false, bool PAIR_ACC = false>
; __device__ __forceinline__ void gemm_phase(PG8_LAS unsigned char* lds, const Gemm g, const Sched& S, const Epi& E) {
;     ...
;         const bool has_next = S.next(ui + 1, nxt);
;         const char* nA = has_next ? (const char*)g.A + (size_t)nxt.pm * tstep + (size_t)(nxt.pn / g.a_div) * g.a_sel : cA; const char* nB = has_next ? (const char*)g.Bt + (size_t)nxt.pn * tstep : cB;
;         for (int t = 0; t < nt; t += 2) {
;             const bool last = (t == nt - 2);
;             const char* a1 = cA + (size_t)(t + 1) * kstep;
;             const char* a2 = last ? nA : cA + (size_t)(t + 2) * kstep; const char* b2 = last ? nB : cB + (size_t)(t + 2) * kstep;
;             const char* a3 = a2 + kstep; const char* b3 = b2 + kstep;
;             if (last && has_next) S.a_ready(nxt);
;             if constexpr (SP2) {
;             PG8_LDB(B0, 0, 0); PG8_LDB(B1, 0, 1); PG8_SCHED; PG8_LDA(At, 0, 0); PG8_STAGE(PG8_SA(1, 1), a1 + hstep, voffA);
;             PG8_WAIT_V(8); PG8_WAIT_L(0); PG8_BAR; PG8_MMA(0, 0, At, B0); PG8_MMA(0, 1, At, B1); PG8_BAR; PG8_SCHED;
;             PG8_LDA(At, 0, 1); PG8_STAGE(PG8_SB(0, 0), b2, voffB); PG8_STAGE(PG8_SB(0, 1), b2 + hstep, voffB); PG8_STAGE(PG8_SA(0, 0), a2, voffA);
;             PG8_WAIT_V(8); PG8_WAIT_L(0); PG8_BAR; PG8_MMA(1, 0, At, B0); PG8_MMA(1, 1, At, B1); PG8_BAR; PG8_SCHED;
;             PG8_LDB(B0, 1, 0); PG8_LDB(B1, 1, 1); PG8_SCHED; PG8_LDA(At, 1, 0); PG8_STAGE(PG8_SA(0, 1), a2 + hstep, voffA);
;             PG8_WAIT_V(8); PG8_WAIT_L(0); PG8_BAR; PG8_MMA(0, 0, At, B0); PG8_MMA(0, 1, At, B1); PG8_BAR; PG8_SCHED;
;             PG8_LDA(At, 1, 1); PG8_STAGE(PG8_SB(1, 0), b3, voffB); PG8_STAGE(PG8_SB(1, 1), b3 + hstep, voffB); PG8_STAGE(PG8_SA(1, 0), a3, voffA);
;             PG8_WAIT_V(8); PG8_WAIT_L(0); PG8_BAR; PG8_MMA(1, 0, At, B0); PG8_MMA(1, 1, At, B1); PG8_BAR; PG8_SCHED;
.LBB0_189:
	s_mov_b32 s80, s21
	s_ashr_i32 s81, s21, 31
	s_lshl_b64 s[18:19], s[80:81], 19
	s_add_u32 s84, s23, s18
	s_addc_u32 s85, s61, s19
	s_mov_b32 s78, s17
	s_and_b64 s[18:19], s[82:83], exec
	s_cselect_b32 s13, s85, s11
	s_cselect_b32 s17, s84, s10
	s_ashr_i32 s79, s78, 31
	s_lshl_b64 s[18:19], s[78:79], 19
	s_add_u32 s86, s63, s18
	s_addc_u32 s87, s65, s19
	s_and_b64 s[18:19], s[82:83], exec
	s_cselect_b32 s20, s87, s15
	s_cselect_b32 s21, s86, s14
	s_add_u32 s10, s10, 0x40080
	s_addc_u32 s11, s11, 0
	s_add_u32 s30, s14, 0x100
	s_addc_u32 s38, s15, 0
	s_mov_b32 s39, -2
	s_waitcnt lgkmcnt(0)
	ds_read_b128 v[130:133], v196
	ds_read_b128 v[134:137], v196 offset:1024
	ds_read_b128 v[138:141], v196 offset:2048
	ds_read_b128 v[142:145], v196 offset:3072
	ds_read_b128 v[178:181], v197
	ds_read_b128 v[182:185], v197 offset:1024
	ds_read_b128 v[186:189], v197 offset:2048
	ds_read_b128 v[190:193], v197 offset:3072
	s_add_u32 s14, s10, 0xfffc0080
	s_addc_u32 s15, s11, -1
	s_cmp_eq_u32 s39, 12
	s_cselect_b32 s19, s13, s15
	s_cselect_b32 s18, s17, s14
	s_cselect_b32 s15, s20, s38
	s_cselect_b32 s14, s21, s30
	v_lshl_add_u64 v[194:195], s[10:11], 0, v[170:171]
	s_add_i32 m0, s69, 0xc000
	ds_read_b128 v[206:209], v198
	ds_read_b128 v[210:213], v198 offset:1024
	ds_read_b128 v[214:217], v198 offset:2048
	ds_read_b128 v[218:221], v198 offset:3072
	ds_read_b128 v[222:225], v198 offset:4096
	ds_read_b128 v[226:229], v198 offset:5120
	ds_read_b128 v[230:233], v198 offset:6144
	ds_read_b128 v[234:237], v198 offset:7168
	global_load_lds_dwordx4 v[194:195], off
	v_lshl_add_u64 v[194:195], s[10:11], 0, v[174:175]
	s_add_i32 m0, s69, 0xe000
	s_nop 0
	global_load_lds_dwordx4 v[194:195], off
	s_waitcnt vmcnt(8)
	s_waitcnt lgkmcnt(0)
	s_barrier
	v_mfma_f32_16x16x32_bf16 v[126:129], v[130:133], v[206:209], 0
	v_mfma_f32_16x16x32_bf16 v[122:125], v[138:141], v[206:209], 0
	v_mfma_f32_16x16x32_bf16 v[110:113], v[130:133], v[214:217], 0
	v_mfma_f32_16x16x32_bf16 v[106:109], v[138:141], v[214:217], 0
	v_mfma_f32_16x16x32_bf16 v[94:97], v[130:133], v[222:225], 0
	v_mfma_f32_16x16x32_bf16 v[90:93], v[138:141], v[222:225], 0
	v_mfma_f32_16x16x32_bf16 v[78:81], v[130:133], v[230:233], 0
	v_mfma_f32_16x16x32_bf16 v[74:77], v[138:141], v[230:233], 0
	v_mfma_f32_16x16x32_bf16 v[126:129], v[134:137], v[210:213], v[126:129]
	v_mfma_f32_16x16x32_bf16 v[122:125], v[142:145], v[210:213], v[122:125]
	v_mfma_f32_16x16x32_bf16 v[110:113], v[134:137], v[218:221], v[110:113]
	v_mfma_f32_16x16x32_bf16 v[106:109], v[142:145], v[218:221], v[106:109]
	v_mfma_f32_16x16x32_bf16 v[94:97], v[134:137], v[226:229], v[94:97]
	v_mfma_f32_16x16x32_bf16 v[90:93], v[142:145], v[226:229], v[90:93]
	v_mfma_f32_16x16x32_bf16 v[78:81], v[134:137], v[234:237], v[78:81]
	v_mfma_f32_16x16x32_bf16 v[74:77], v[142:145], v[234:237], v[74:77]
	v_mfma_f32_16x16x32_bf16 v[118:121], v[178:181], v[206:209], 0
	v_mfma_f32_16x16x32_bf16 v[114:117], v[186:189], v[206:209], 0
	v_mfma_f32_16x16x32_bf16 v[102:105], v[178:181], v[214:217], 0
	v_mfma_f32_16x16x32_bf16 v[98:101], v[186:189], v[214:217], 0
	v_mfma_f32_16x16x32_bf16 v[86:89], v[178:181], v[222:225], 0
	v_mfma_f32_16x16x32_bf16 v[82:85], v[186:189], v[222:225], 0
	v_mfma_f32_16x16x32_bf16 v[70:73], v[178:181], v[230:233], 0
	v_mfma_f32_16x16x32_bf16 v[66:69], v[186:189], v[230:233], 0
	v_mfma_f32_16x16x32_bf16 v[118:121], v[182:185], v[210:213], v[118:121]
	v_mfma_f32_16x16x32_bf16 v[114:117], v[190:193], v[210:213], v[114:117]
	v_mfma_f32_16x16x32_bf16 v[102:105], v[182:185], v[218:221], v[102:105]
	v_mfma_f32_16x16x32_bf16 v[98:101], v[190:193], v[218:221], v[98:101]
	v_mfma_f32_16x16x32_bf16 v[86:89], v[182:185], v[226:229], v[86:89]
	v_mfma_f32_16x16x32_bf16 v[82:85], v[190:193], v[226:229], v[82:85]
	v_mfma_f32_16x16x32_bf16 v[70:73], v[182:185], v[234:237], v[70:73]
	v_mfma_f32_16x16x32_bf16 v[66:69], v[190:193], v[234:237], v[66:69]
	s_barrier
	s_add_i32 s40, s25, s67
	v_lshl_add_u64 v[194:195], s[14:15], 0, v[148:149]
	s_mov_b32 m0, s40
	ds_read_b128 v[206:209], v198 offset:16384
	ds_read_b128 v[210:213], v198 offset:17408
	ds_read_b128 v[214:217], v198 offset:18432
	ds_read_b128 v[218:221], v198 offset:19456
	ds_read_b128 v[222:225], v198 offset:20480
	ds_read_b128 v[226:229], v198 offset:21504
	ds_read_b128 v[230:233], v198 offset:22528
	ds_read_b128 v[234:237], v198 offset:23552
	global_load_lds_dwordx4 v[194:195], off
	s_add_i32 m0, s40, 0x2000
	s_add_u32 s40, s14, 0x40000
	v_lshl_add_u64 v[238:239], s[14:15], 0, v[152:153]
	s_addc_u32 s41, s15, 0
	s_add_i32 s79, s35, s67
	global_load_lds_dwordx4 v[238:239], off
	v_lshl_add_u64 v[240:241], s[40:41], 0, v[148:149]
	s_mov_b32 m0, s79
	v_lshl_add_u64 v[242:243], s[18:19], 0, v[150:151]
	global_load_lds_dwordx4 v[240:241], off
	v_lshl_add_u64 v[240:241], s[40:41], 0, v[152:153]
	s_add_i32 m0, s79, 0x2000
	s_nop 0
	global_load_lds_dwordx4 v[240:241], off
	v_lshl_add_u64 v[240:241], s[18:19], 0, v[146:147]
	s_mov_b32 m0, s69
	s_nop 0
	global_load_lds_dwordx4 v[240:241], off
	s_mov_b32 m0, s71
	s_nop 0
	global_load_lds_dwordx4 v[242:243], off
	s_waitcnt vmcnt(8)
	s_waitcnt lgkmcnt(0)
	s_barrier
; #define PG8_STAGE(bufoff, gbase, voff) do { _Pragma("unroll") for (int _i = 0; _i < 2; ++_i) \
;         __builtin_amdgcn_global_load_lds((const unsigned*)((const char*)(gbase) + (voff)[_i]), (PG8_LAS unsigned*)(lds + (bufoff) + ldsw + _i * 8192), 16, 0, 0); } while (0)
; #define PG8_LDA(dst, b, h) do { _Pragma("unroll") for (int m = 0; m < 4; ++m) _Pragma("unroll") for (int k = 0; k < 2; ++k) dst[m][k] = *(const PG8_LAS bf16x8*)(lds + PG8_SA(b, h) + aoff + m * 2048 + k * 1024); } while (0)
; #define PG8_LDB(dst, b, h) do { _Pragma("unroll") for (int n = 0; n < 2; ++n) _Pragma("unroll") for (int k = 0; k < 2; ++k) dst[n][k] = *(const PG8_LAS bf16x8*)(lds + PG8_SB(b, h) + boff + n * 2048 + k * 1024); } while (0)
; #define PG8_MMA(ai, bj, At, Bt) do { __builtin_amdgcn_s_setprio(1); _Pragma("unroll") for (int m = 0; m < 4; ++m) _Pragma("unroll") for (int n = 0; n < 2; ++n) _Pragma("unroll") for (int k = 0; k < 2; ++k) \
;         acc[ai][bj][m][n] = __builtin_amdgcn_mfma_f32_16x16x32_bf16(Bt[n][k], At[m][k], acc[ai][bj][m][n], 0, 0, 0); __builtin_amdgcn_s_setprio(0); } while (0)
; template <class Epi, class Sched, bool ALIGN_EPI = false, bool SP2 = false, bool PAIR_ACC = false>
; __device__ __forceinline__ void gemm_phase(PG8_LAS unsigned char* lds, const Gemm g, const Sched& S, const Epi& E) {
;     ...
;             if constexpr (SP2) {
;             PG8_LDB(B0, 0, 0); PG8_LDB(B1, 0, 1); PG8_SCHED; PG8_LDA(At, 0, 0); PG8_STAGE(PG8_SA(1, 1), a1 + hstep, voffA);
;             PG8_WAIT_V(8); PG8_WAIT_L(0); PG8_BAR; PG8_MMA(0, 0, At, B0); PG8_MMA(0, 1, At, B1); PG8_BAR; PG8_SCHED;
;             PG8_LDA(At, 0, 1); PG8_STAGE(PG8_SB(0, 0), b2, voffB); PG8_STAGE(PG8_SB(0, 1), b2 + hstep, voffB); PG8_STAGE(PG8_SA(0, 0), a2, voffA);
;             PG8_WAIT_V(8); PG8_WAIT_L(0); PG8_BAR; PG8_MMA(1, 0, At, B0); PG8_MMA(1, 1, At, B1); PG8_BAR; PG8_SCHED;
;             PG8_LDB(B0, 1, 0); PG8_LDB(B1, 1, 1); PG8_SCHED; PG8_LDA(At, 1, 0); PG8_STAGE(PG8_SA(0, 1), a2 + hstep, voffA);
;             PG8_WAIT_V(8); PG8_WAIT_L(0); PG8_BAR; PG8_MMA(0, 0, At, B0); PG8_MMA(0, 1, At, B1); PG8_BAR; PG8_SCHED;
;             PG8_LDA(At, 1, 1); PG8_STAGE(PG8_SB(1, 0), b3, voffB); PG8_STAGE(PG8_SB(1, 1), b3 + hstep, voffB); PG8_STAGE(PG8_SA(1, 0), a3, voffA);
;             PG8_WAIT_V(8); PG8_WAIT_L(0); PG8_BAR; PG8_MMA(1, 0, At, B0); PG8_MMA(1, 1, At, B1); PG8_BAR; PG8_SCHED;
	v_mfma_f32_16x16x32_bf16 v[62:65], v[130:133], v[206:209], 0
	v_mfma_f32_16x16x32_bf16 v[58:61], v[138:141], v[206:209], 0
	v_mfma_f32_16x16x32_bf16 v[46:49], v[130:133], v[214:217], 0
	v_mfma_f32_16x16x32_bf16 v[42:45], v[138:141], v[214:217], 0
	v_mfma_f32_16x16x32_bf16 v[30:33], v[130:133], v[222:225], 0
	v_mfma_f32_16x16x32_bf16 v[26:29], v[138:141], v[222:225], 0
	v_mfma_f32_16x16x32_bf16 v[14:17], v[130:133], v[230:233], 0
	v_mfma_f32_16x16x32_bf16 v[10:13], v[138:141], v[230:233], 0
	v_mfma_f32_16x16x32_bf16 v[62:65], v[134:137], v[210:213], v[62:65]
	v_mfma_f32_16x16x32_bf16 v[58:61], v[142:145], v[210:213], v[58:61]
	v_mfma_f32_16x16x32_bf16 v[46:49], v[134:137], v[218:221], v[46:49]
	v_mfma_f32_16x16x32_bf16 v[42:45], v[142:145], v[218:221], v[42:45]
	v_mfma_f32_16x16x32_bf16 v[30:33], v[134:137], v[226:229], v[30:33]
	v_mfma_f32_16x16x32_bf16 v[26:29], v[142:145], v[226:229], v[26:29]
	v_mfma_f32_16x16x32_bf16 v[14:17], v[134:137], v[234:237], v[14:17]
	v_mfma_f32_16x16x32_bf16 v[10:13], v[142:145], v[234:237], v[10:13]
	v_mfma_f32_16x16x32_bf16 v[54:57], v[178:181], v[206:209], 0
	v_mfma_f32_16x16x32_bf16 v[50:53], v[186:189], v[206:209], 0
	v_mfma_f32_16x16x32_bf16 v[38:41], v[178:181], v[214:217], 0
	v_mfma_f32_16x16x32_bf16 v[34:37], v[186:189], v[214:217], 0
	v_mfma_f32_16x16x32_bf16 v[22:25], v[178:181], v[222:225], 0
	v_mfma_f32_16x16x32_bf16 v[18:21], v[186:189], v[222:225], 0
	v_mfma_f32_16x16x32_bf16 v[6:9], v[178:181], v[230:233], 0
	v_mfma_f32_16x16x32_bf16 v[2:5], v[186:189], v[230:233], 0
	v_mfma_f32_16x16x32_bf16 v[54:57], v[182:185], v[210:213], v[54:57]
	v_mfma_f32_16x16x32_bf16 v[50:53], v[190:193], v[210:213], v[50:53]
	v_mfma_f32_16x16x32_bf16 v[38:41], v[182:185], v[218:221], v[38:41]
	v_mfma_f32_16x16x32_bf16 v[34:37], v[190:193], v[218:221], v[34:37]
	v_mfma_f32_16x16x32_bf16 v[22:25], v[182:185], v[226:229], v[22:25]
	v_mfma_f32_16x16x32_bf16 v[18:21], v[190:193], v[226:229], v[18:21]
	v_mfma_f32_16x16x32_bf16 v[6:9], v[182:185], v[234:237], v[6:9]
	v_mfma_f32_16x16x32_bf16 v[2:5], v[190:193], v[234:237], v[2:5]
	s_barrier
	s_branch .Lpeel_mid_190
.LBB0_190:
	ds_read_b128 v[130:133], v196
	ds_read_b128 v[134:137], v196 offset:1024
	ds_read_b128 v[138:141], v196 offset:2048
	ds_read_b128 v[142:145], v196 offset:3072
	ds_read_b128 v[178:181], v197
	ds_read_b128 v[182:185], v197 offset:1024
	ds_read_b128 v[186:189], v197 offset:2048
	ds_read_b128 v[190:193], v197 offset:3072
	s_add_u32 s14, s10, 0xfffc0080
	s_addc_u32 s15, s11, -1
	s_cmp_eq_u32 s39, 12
	s_cselect_b32 s19, s13, s15
	s_cselect_b32 s18, s17, s14
	s_cselect_b32 s15, s20, s38
	s_cselect_b32 s14, s21, s30
	v_lshl_add_u64 v[194:195], s[10:11], 0, v[170:171]
	s_add_i32 m0, s69, 0xc000
	ds_read_b128 v[206:209], v198
	ds_read_b128 v[210:213], v198 offset:1024
	ds_read_b128 v[214:217], v198 offset:2048
	ds_read_b128 v[218:221], v198 offset:3072
	ds_read_b128 v[222:225], v198 offset:4096
	ds_read_b128 v[226:229], v198 offset:5120
	ds_read_b128 v[230:233], v198 offset:6144
	ds_read_b128 v[234:237], v198 offset:7168
	global_load_lds_dwordx4 v[194:195], off
	v_lshl_add_u64 v[194:195], s[10:11], 0, v[174:175]
	s_add_i32 m0, s69, 0xe000
	s_nop 0
	global_load_lds_dwordx4 v[194:195], off
	s_waitcnt vmcnt(8)
	s_waitcnt lgkmcnt(0)
	s_barrier
	v_mfma_f32_16x16x32_bf16 v[126:129], v[130:133], v[206:209], v[126:129]
	v_mfma_f32_16x16x32_bf16 v[122:125], v[138:141], v[206:209], v[122:125]
	v_mfma_f32_16x16x32_bf16 v[110:113], v[130:133], v[214:217], v[110:113]
	v_mfma_f32_16x16x32_bf16 v[106:109], v[138:141], v[214:217], v[106:109]
	v_mfma_f32_16x16x32_bf16 v[94:97], v[130:133], v[222:225], v[94:97]
	v_mfma_f32_16x16x32_bf16 v[90:93], v[138:141], v[222:225], v[90:93]
	v_mfma_f32_16x16x32_bf16 v[78:81], v[130:133], v[230:233], v[78:81]
	v_mfma_f32_16x16x32_bf16 v[74:77], v[138:141], v[230:233], v[74:77]
	v_mfma_f32_16x16x32_bf16 v[126:129], v[134:137], v[210:213], v[126:129]
	v_mfma_f32_16x16x32_bf16 v[122:125], v[142:145], v[210:213], v[122:125]
	v_mfma_f32_16x16x32_bf16 v[110:113], v[134:137], v[218:221], v[110:113]
	v_mfma_f32_16x16x32_bf16 v[106:109], v[142:145], v[218:221], v[106:109]
	v_mfma_f32_16x16x32_bf16 v[94:97], v[134:137], v[226:229], v[94:97]
	v_mfma_f32_16x16x32_bf16 v[90:93], v[142:145], v[226:229], v[90:93]
	v_mfma_f32_16x16x32_bf16 v[78:81], v[134:137], v[234:237], v[78:81]
	v_mfma_f32_16x16x32_bf16 v[74:77], v[142:145], v[234:237], v[74:77]
	v_mfma_f32_16x16x32_bf16 v[118:121], v[178:181], v[206:209], v[118:121]
	v_mfma_f32_16x16x32_bf16 v[114:117], v[186:189], v[206:209], v[114:117]
	v_mfma_f32_16x16x32_bf16 v[102:105], v[178:181], v[214:217], v[102:105]
	v_mfma_f32_16x16x32_bf16 v[98:101], v[186:189], v[214:217], v[98:101]
	v_mfma_f32_16x16x32_bf16 v[86:89], v[178:181], v[222:225], v[86:89]
	v_mfma_f32_16x16x32_bf16 v[82:85], v[186:189], v[222:225], v[82:85]
	v_mfma_f32_16x16x32_bf16 v[70:73], v[178:181], v[230:233], v[70:73]
	v_mfma_f32_16x16x32_bf16 v[66:69], v[186:189], v[230:233], v[66:69]
	v_mfma_f32_16x16x32_bf16 v[118:121], v[182:185], v[210:213], v[118:121]
	v_mfma_f32_16x16x32_bf16 v[114:117], v[190:193], v[210:213], v[114:117]
	v_mfma_f32_16x16x32_bf16 v[102:105], v[182:185], v[218:221], v[102:105]
	v_mfma_f32_16x16x32_bf16 v[98:101], v[190:193], v[218:221], v[98:101]
	v_mfma_f32_16x16x32_bf16 v[86:89], v[182:185], v[226:229], v[86:89]
	v_mfma_f32_16x16x32_bf16 v[82:85], v[190:193], v[226:229], v[82:85]
	v_mfma_f32_16x16x32_bf16 v[70:73], v[182:185], v[234:237], v[70:73]
	v_mfma_f32_16x16x32_bf16 v[66:69], v[190:193], v[234:237], v[66:69]
	s_barrier
; #define PG8_STAGE(bufoff, gbase, voff) do { _Pragma("unroll") for (int _i = 0; _i < 2; ++_i) \
;         __builtin_amdgcn_global_load_lds((const unsigned*)((const char*)(gbase) + (voff)[_i]), (PG8_LAS unsigned*)(lds + (bufoff) + ldsw + _i * 8192), 16, 0, 0); } while (0)
; #define PG8_LDA(dst, b, h) do { _Pragma("unroll") for (int m = 0; m < 4; ++m) _Pragma("unroll") for (int k = 0; k < 2; ++k) dst[m][k] = *(const PG8_LAS bf16x8*)(lds + PG8_SA(b, h) + aoff + m * 2048 + k * 1024); } while (0)
; #define PG8_LDB(dst, b, h) do { _Pragma("unroll") for (int n = 0; n < 2; ++n) _Pragma("unroll") for (int k = 0; k < 2; ++k) dst[n][k] = *(const PG8_LAS bf16x8*)(lds + PG8_SB(b, h) + boff + n * 2048 + k * 1024); } while (0)
; #define PG8_MMA(ai, bj, At, Bt) do { __builtin_amdgcn_s_setprio(1); _Pragma("unroll") for (int m = 0; m < 4; ++m) _Pragma("unroll") for (int n = 0; n < 2; ++n) _Pragma("unroll") for (int k = 0; k < 2; ++k) \
;         acc[ai][bj][m][n] = __builtin_amdgcn_mfma_f32_16x16x32_bf16(Bt[n][k], At[m][k], acc[ai][bj][m][n], 0, 0, 0); __builtin_amdgcn_s_setprio(0); } while (0)
; template <class Epi, class Sched, bool ALIGN_EPI = false, bool SP2 = false, bool PAIR_ACC = false>
; __device__ __forceinline__ void gemm_phase(PG8_LAS unsigned char* lds, const Gemm g, const Sched& S, const Epi& E) {
;     ...
;             if constexpr (SP2) {
;             PG8_LDB(B0, 0, 0); PG8_LDB(B1, 0, 1); PG8_SCHED; PG8_LDA(At, 0, 0); PG8_STAGE(PG8_SA(1, 1), a1 + hstep, voffA);
;             PG8_WAIT_V(8); PG8_WAIT_L(0); PG8_BAR; PG8_MMA(0, 0, At, B0); PG8_MMA(0, 1, At, B1); PG8_BAR; PG8_SCHED;
;             PG8_LDA(At, 0, 1); PG8_STAGE(PG8_SB(0, 0), b2, voffB); PG8_STAGE(PG8_SB(0, 1), b2 + hstep, voffB); PG8_STAGE(PG8_SA(0, 0), a2, voffA);
;             PG8_WAIT_V(8); PG8_WAIT_L(0); PG8_BAR; PG8_MMA(1, 0, At, B0); PG8_MMA(1, 1, At, B1); PG8_BAR; PG8_SCHED;
;             PG8_LDB(B0, 1, 0); PG8_LDB(B1, 1, 1); PG8_SCHED; PG8_LDA(At, 1, 0); PG8_STAGE(PG8_SA(0, 1), a2 + hstep, voffA);
;             PG8_WAIT_V(8); PG8_WAIT_L(0); PG8_BAR; PG8_MMA(0, 0, At, B0); PG8_MMA(0, 1, At, B1); PG8_BAR; PG8_SCHED;
;             PG8_LDA(At, 1, 1); PG8_STAGE(PG8_SB(1, 0), b3, voffB); PG8_STAGE(PG8_SB(1, 1), b3 + hstep, voffB); PG8_STAGE(PG8_SA(1, 0), a3, voffA);
;             PG8_WAIT_V(8); PG8_WAIT_L(0); PG8_BAR; PG8_MMA(1, 0, At, B0); PG8_MMA(1, 1, At, B1); PG8_BAR; PG8_SCHED;
	s_add_i32 s40, s25, s67
	v_lshl_add_u64 v[194:195], s[14:15], 0, v[148:149]
	s_mov_b32 m0, s40
	ds_read_b128 v[206:209], v198 offset:16384
	ds_read_b128 v[210:213], v198 offset:17408
	ds_read_b128 v[214:217], v198 offset:18432
	ds_read_b128 v[218:221], v198 offset:19456
	ds_read_b128 v[222:225], v198 offset:20480
	ds_read_b128 v[226:229], v198 offset:21504
	ds_read_b128 v[230:233], v198 offset:22528
	ds_read_b128 v[234:237], v198 offset:23552
	global_load_lds_dwordx4 v[194:195], off
	s_add_i32 m0, s40, 0x2000
	s_add_u32 s40, s14, 0x40000
	v_lshl_add_u64 v[238:239], s[14:15], 0, v[152:153]
	s_addc_u32 s41, s15, 0
	s_add_i32 s79, s35, s67
	global_load_lds_dwordx4 v[238:239], off
	v_lshl_add_u64 v[240:241], s[40:41], 0, v[148:149]
	s_mov_b32 m0, s79
	v_lshl_add_u64 v[242:243], s[18:19], 0, v[150:151]
	global_load_lds_dwordx4 v[240:241], off
	v_lshl_add_u64 v[240:241], s[40:41], 0, v[152:153]
	s_add_i32 m0, s79, 0x2000
	s_nop 0
	global_load_lds_dwordx4 v[240:241], off
	v_lshl_add_u64 v[240:241], s[18:19], 0, v[146:147]
	s_mov_b32 m0, s69
	s_nop 0
	global_load_lds_dwordx4 v[240:241], off
	s_mov_b32 m0, s71
	s_nop 0
	global_load_lds_dwordx4 v[242:243], off
	s_waitcnt vmcnt(8)
	s_waitcnt lgkmcnt(0)
	s_barrier
	v_mfma_f32_16x16x32_bf16 v[62:65], v[130:133], v[206:209], v[62:65]
	v_mfma_f32_16x16x32_bf16 v[58:61], v[138:141], v[206:209], v[58:61]
	v_mfma_f32_16x16x32_bf16 v[46:49], v[130:133], v[214:217], v[46:49]
	v_mfma_f32_16x16x32_bf16 v[42:45], v[138:141], v[214:217], v[42:45]
	v_mfma_f32_16x16x32_bf16 v[30:33], v[130:133], v[222:225], v[30:33]
	v_mfma_f32_16x16x32_bf16 v[26:29], v[138:141], v[222:225], v[26:29]
	v_mfma_f32_16x16x32_bf16 v[14:17], v[130:133], v[230:233], v[14:17]
	v_mfma_f32_16x16x32_bf16 v[10:13], v[138:141], v[230:233], v[10:13]
	v_mfma_f32_16x16x32_bf16 v[62:65], v[134:137], v[210:213], v[62:65]
	v_mfma_f32_16x16x32_bf16 v[58:61], v[142:145], v[210:213], v[58:61]
	v_mfma_f32_16x16x32_bf16 v[46:49], v[134:137], v[218:221], v[46:49]
	v_mfma_f32_16x16x32_bf16 v[42:45], v[142:145], v[218:221], v[42:45]
	v_mfma_f32_16x16x32_bf16 v[30:33], v[134:137], v[226:229], v[30:33]
	v_mfma_f32_16x16x32_bf16 v[26:29], v[142:145], v[226:229], v[26:29]
	v_mfma_f32_16x16x32_bf16 v[14:17], v[134:137], v[234:237], v[14:17]
	v_mfma_f32_16x16x32_bf16 v[10:13], v[142:145], v[234:237], v[10:13]
	v_mfma_f32_16x16x32_bf16 v[54:57], v[178:181], v[206:209], v[54:57]
	v_mfma_f32_16x16x32_bf16 v[50:53], v[186:189], v[206:209], v[50:53]
	v_mfma_f32_16x16x32_bf16 v[38:41], v[178:181], v[214:217], v[38:41]
	v_mfma_f32_16x16x32_bf16 v[34:37], v[186:189], v[214:217], v[34:37]
	v_mfma_f32_16x16x32_bf16 v[22:25], v[178:181], v[222:225], v[22:25]
	v_mfma_f32_16x16x32_bf16 v[18:21], v[186:189], v[222:225], v[18:21]
	v_mfma_f32_16x16x32_bf16 v[6:9], v[178:181], v[230:233], v[6:9]
	v_mfma_f32_16x16x32_bf16 v[2:5], v[186:189], v[230:233], v[2:5]
	v_mfma_f32_16x16x32_bf16 v[54:57], v[182:185], v[210:213], v[54:57]
	v_mfma_f32_16x16x32_bf16 v[50:53], v[190:193], v[210:213], v[50:53]
	v_mfma_f32_16x16x32_bf16 v[38:41], v[182:185], v[218:221], v[38:41]
	v_mfma_f32_16x16x32_bf16 v[34:37], v[190:193], v[218:221], v[34:37]
	v_mfma_f32_16x16x32_bf16 v[22:25], v[182:185], v[226:229], v[22:25]
	v_mfma_f32_16x16x32_bf16 v[18:21], v[190:193], v[226:229], v[18:21]
	v_mfma_f32_16x16x32_bf16 v[6:9], v[182:185], v[234:237], v[6:9]
	v_mfma_f32_16x16x32_bf16 v[2:5], v[190:193], v[234:237], v[2:5]
	s_barrier
.Lpeel_mid_190:
	s_add_i32 s40, 0, 0x18000
	s_add_i32 s41, 0, 0x1c000
	v_add_u32_e32 v142, s40, v173
	v_add_u32_e32 v154, s41, v173
	ds_read_b128 v[130:133], v142
	ds_read_b128 v[134:137], v142 offset:1024
	ds_read_b128 v[138:141], v142 offset:2048
	ds_read_b128 v[142:145], v142 offset:3072
	ds_read_b128 v[178:181], v154
	ds_read_b128 v[182:185], v154 offset:1024
	ds_read_b128 v[186:189], v154 offset:2048
	ds_read_b128 v[190:193], v154 offset:3072
	s_add_u32 s18, s18, 0x40000
	s_addc_u32 s19, s19, 0
	s_mov_b32 m0, s73
	v_lshl_add_u64 v[244:245], s[18:19], 0, v[146:147]
	ds_read_b128 v[206:209], v198 offset:32768
	ds_read_b128 v[210:213], v198 offset:33792
	ds_read_b128 v[214:217], v198 offset:34816
	ds_read_b128 v[218:221], v198 offset:35840
	ds_read_b128 v[222:225], v198 offset:36864
	ds_read_b128 v[226:229], v198 offset:37888
	ds_read_b128 v[230:233], v198 offset:38912
	ds_read_b128 v[234:237], v198 offset:39936
	global_load_lds_dwordx4 v[244:245], off
	v_lshl_add_u64 v[244:245], s[18:19], 0, v[150:151]
	s_mov_b32 m0, s36
	s_nop 0
	global_load_lds_dwordx4 v[244:245], off
	s_waitcnt vmcnt(8)
	s_waitcnt lgkmcnt(0)
	s_barrier
; #define PG8_STAGE(bufoff, gbase, voff) do { _Pragma("unroll") for (int _i = 0; _i < 2; ++_i) \
;         __builtin_amdgcn_global_load_lds((const unsigned*)((const char*)(gbase) + (voff)[_i]), (PG8_LAS unsigned*)(lds + (bufoff) + ldsw + _i * 8192), 16, 0, 0); } while (0)
; #define PG8_LDA(dst, b, h) do { _Pragma("unroll") for (int m = 0; m < 4; ++m) _Pragma("unroll") for (int k = 0; k < 2; ++k) dst[m][k] = *(const PG8_LAS bf16x8*)(lds + PG8_SA(b, h) + aoff + m * 2048 + k * 1024); } while (0)
; #define PG8_LDB(dst, b, h) do { _Pragma("unroll") for (int n = 0; n < 2; ++n) _Pragma("unroll") for (int k = 0; k < 2; ++k) dst[n][k] = *(const PG8_LAS bf16x8*)(lds + PG8_SB(b, h) + boff + n * 2048 + k * 1024); } while (0)
; #define PG8_MMA(ai, bj, At, Bt) do { __builtin_amdgcn_s_setprio(1); _Pragma("unroll") for (int m = 0; m < 4; ++m) _Pragma("unroll") for (int n = 0; n < 2; ++n) _Pragma("unroll") for (int k = 0; k < 2; ++k) \
;         acc[ai][bj][m][n] = __builtin_amdgcn_mfma_f32_16x16x32_bf16(Bt[n][k], At[m][k], acc[ai][bj][m][n], 0, 0, 0); __builtin_amdgcn_s_setprio(0); } while (0)
; template <class Epi, class Sched, bool ALIGN_EPI = false, bool SP2 = false, bool PAIR_ACC = false>
; __device__ __forceinline__ void gemm_phase(PG8_LAS unsigned char* lds, const Gemm g, const Sched& S, const Epi& E) {
;     ...
;             if constexpr (SP2) {
;             PG8_LDB(B0, 0, 0); PG8_LDB(B1, 0, 1); PG8_SCHED; PG8_LDA(At, 0, 0); PG8_STAGE(PG8_SA(1, 1), a1 + hstep, voffA);
;             PG8_WAIT_V(8); PG8_WAIT_L(0); PG8_BAR; PG8_MMA(0, 0, At, B0); PG8_MMA(0, 1, At, B1); PG8_BAR; PG8_SCHED;
;             PG8_LDA(At, 0, 1); PG8_STAGE(PG8_SB(0, 0), b2, voffB); PG8_STAGE(PG8_SB(0, 1), b2 + hstep, voffB); PG8_STAGE(PG8_SA(0, 0), a2, voffA);
;             PG8_WAIT_V(8); PG8_WAIT_L(0); PG8_BAR; PG8_MMA(1, 0, At, B0); PG8_MMA(1, 1, At, B1); PG8_BAR; PG8_SCHED;
;             PG8_LDB(B0, 1, 0); PG8_LDB(B1, 1, 1); PG8_SCHED; PG8_LDA(At, 1, 0); PG8_STAGE(PG8_SA(0, 1), a2 + hstep, voffA);
;             PG8_WAIT_V(8); PG8_WAIT_L(0); PG8_BAR; PG8_MMA(0, 0, At, B0); PG8_MMA(0, 1, At, B1); PG8_BAR; PG8_SCHED;
;             PG8_LDA(At, 1, 1); PG8_STAGE(PG8_SB(1, 0), b3, voffB); PG8_STAGE(PG8_SB(1, 1), b3 + hstep, voffB); PG8_STAGE(PG8_SA(1, 0), a3, voffA);
;             PG8_WAIT_V(8); PG8_WAIT_L(0); PG8_BAR; PG8_MMA(1, 0, At, B0); PG8_MMA(1, 1, At, B1); PG8_BAR; PG8_SCHED;
	v_mfma_f32_16x16x32_bf16 v[126:129], v[130:133], v[206:209], v[126:129]
	v_mfma_f32_16x16x32_bf16 v[122:125], v[138:141], v[206:209], v[122:125]
	v_mfma_f32_16x16x32_bf16 v[110:113], v[130:133], v[214:217], v[110:113]
	v_mfma_f32_16x16x32_bf16 v[106:109], v[138:141], v[214:217], v[106:109]
	v_mfma_f32_16x16x32_bf16 v[94:97], v[130:133], v[222:225], v[94:97]
	v_mfma_f32_16x16x32_bf16 v[90:93], v[138:141], v[222:225], v[90:93]
	v_mfma_f32_16x16x32_bf16 v[78:81], v[130:133], v[230:233], v[78:81]
	v_mfma_f32_16x16x32_bf16 v[74:77], v[138:141], v[230:233], v[74:77]
	v_mfma_f32_16x16x32_bf16 v[126:129], v[134:137], v[210:213], v[126:129]
	v_mfma_f32_16x16x32_bf16 v[122:125], v[142:145], v[210:213], v[122:125]
	v_mfma_f32_16x16x32_bf16 v[110:113], v[134:137], v[218:221], v[110:113]
	v_mfma_f32_16x16x32_bf16 v[106:109], v[142:145], v[218:221], v[106:109]
	v_mfma_f32_16x16x32_bf16 v[94:97], v[134:137], v[226:229], v[94:97]
	v_mfma_f32_16x16x32_bf16 v[90:93], v[142:145], v[226:229], v[90:93]
	v_mfma_f32_16x16x32_bf16 v[78:81], v[134:137], v[234:237], v[78:81]
	v_mfma_f32_16x16x32_bf16 v[74:77], v[142:145], v[234:237], v[74:77]
	v_mfma_f32_16x16x32_bf16 v[118:121], v[178:181], v[206:209], v[118:121]
	v_mfma_f32_16x16x32_bf16 v[114:117], v[186:189], v[206:209], v[114:117]
	v_mfma_f32_16x16x32_bf16 v[102:105], v[178:181], v[214:217], v[102:105]
	v_mfma_f32_16x16x32_bf16 v[98:101], v[186:189], v[214:217], v[98:101]
	v_mfma_f32_16x16x32_bf16 v[86:89], v[178:181], v[222:225], v[86:89]
	v_mfma_f32_16x16x32_bf16 v[82:85], v[186:189], v[222:225], v[82:85]
	v_mfma_f32_16x16x32_bf16 v[70:73], v[178:181], v[230:233], v[70:73]
	v_mfma_f32_16x16x32_bf16 v[66:69], v[186:189], v[230:233], v[66:69]
	v_mfma_f32_16x16x32_bf16 v[118:121], v[182:185], v[210:213], v[118:121]
	v_mfma_f32_16x16x32_bf16 v[114:117], v[190:193], v[210:213], v[114:117]
	v_mfma_f32_16x16x32_bf16 v[102:105], v[182:185], v[218:221], v[102:105]
	v_mfma_f32_16x16x32_bf16 v[98:101], v[190:193], v[218:221], v[98:101]
	v_mfma_f32_16x16x32_bf16 v[86:89], v[182:185], v[226:229], v[86:89]
	v_mfma_f32_16x16x32_bf16 v[82:85], v[190:193], v[226:229], v[82:85]
	v_mfma_f32_16x16x32_bf16 v[70:73], v[182:185], v[234:237], v[70:73]
	v_mfma_f32_16x16x32_bf16 v[66:69], v[190:193], v[234:237], v[66:69]
	s_barrier
	s_add_i32 s18, s40, s67
	v_lshl_add_u64 v[194:195], v[194:195], 0, s[50:51]
	s_mov_b32 m0, s18
	ds_read_b128 v[206:209], v198 offset:49152
	ds_read_b128 v[210:213], v198 offset:50176
	ds_read_b128 v[214:217], v198 offset:51200
	ds_read_b128 v[218:221], v198 offset:52224
	ds_read_b128 v[222:225], v198 offset:53248
	ds_read_b128 v[226:229], v198 offset:54272
	ds_read_b128 v[230:233], v198 offset:55296
	ds_read_b128 v[234:237], v198 offset:56320
	global_load_lds_dwordx4 v[194:195], off
	s_add_i32 m0, s18, 0x2000
	s_add_u32 s14, s14, 0x40080
	v_lshl_add_u64 v[194:195], v[238:239], 0, s[50:51]
	s_addc_u32 s15, s15, 0
	s_add_i32 s18, s41, s67
	global_load_lds_dwordx4 v[194:195], off
	v_lshl_add_u64 v[194:195], s[14:15], 0, v[148:149]
	s_mov_b32 m0, s18
	s_nop 0
	global_load_lds_dwordx4 v[194:195], off
	v_lshl_add_u64 v[194:195], s[14:15], 0, v[152:153]
	s_add_i32 m0, s18, 0x2000
	s_nop 0
	global_load_lds_dwordx4 v[194:195], off
	v_lshl_add_u64 v[194:195], v[240:241], 0, s[50:51]
	s_mov_b32 m0, s37
	s_nop 0
	global_load_lds_dwordx4 v[194:195], off
	v_lshl_add_u64 v[194:195], v[242:243], 0, s[50:51]
	s_mov_b32 m0, s75
	s_nop 0
	global_load_lds_dwordx4 v[194:195], off
	s_waitcnt vmcnt(8)
	s_waitcnt lgkmcnt(0)
	s_barrier
	v_mfma_f32_16x16x32_bf16 v[62:65], v[130:133], v[206:209], v[62:65]
	v_mfma_f32_16x16x32_bf16 v[58:61], v[138:141], v[206:209], v[58:61]
	v_mfma_f32_16x16x32_bf16 v[46:49], v[130:133], v[214:217], v[46:49]
	v_mfma_f32_16x16x32_bf16 v[42:45], v[138:141], v[214:217], v[42:45]
	v_mfma_f32_16x16x32_bf16 v[30:33], v[130:133], v[222:225], v[30:33]
	v_mfma_f32_16x16x32_bf16 v[26:29], v[138:141], v[222:225], v[26:29]
	v_mfma_f32_16x16x32_bf16 v[14:17], v[130:133], v[230:233], v[14:17]
	v_mfma_f32_16x16x32_bf16 v[10:13], v[138:141], v[230:233], v[10:13]
	v_mfma_f32_16x16x32_bf16 v[62:65], v[134:137], v[210:213], v[62:65]
	v_mfma_f32_16x16x32_bf16 v[58:61], v[142:145], v[210:213], v[58:61]
	v_mfma_f32_16x16x32_bf16 v[46:49], v[134:137], v[218:221], v[46:49]
	v_mfma_f32_16x16x32_bf16 v[42:45], v[142:145], v[218:221], v[42:45]
	v_mfma_f32_16x16x32_bf16 v[30:33], v[134:137], v[226:229], v[30:33]
	v_mfma_f32_16x16x32_bf16 v[26:29], v[142:145], v[226:229], v[26:29]
	v_mfma_f32_16x16x32_bf16 v[14:17], v[134:137], v[234:237], v[14:17]
	v_mfma_f32_16x16x32_bf16 v[10:13], v[142:145], v[234:237], v[10:13]
	v_mfma_f32_16x16x32_bf16 v[54:57], v[178:181], v[206:209], v[54:57]
	v_mfma_f32_16x16x32_bf16 v[50:53], v[186:189], v[206:209], v[50:53]
	v_mfma_f32_16x16x32_bf16 v[38:41], v[178:181], v[214:217], v[38:41]
	v_mfma_f32_16x16x32_bf16 v[34:37], v[186:189], v[214:217], v[34:37]
	v_mfma_f32_16x16x32_bf16 v[22:25], v[178:181], v[222:225], v[22:25]
	v_mfma_f32_16x16x32_bf16 v[18:21], v[186:189], v[222:225], v[18:21]
	v_mfma_f32_16x16x32_bf16 v[6:9], v[178:181], v[230:233], v[6:9]
	v_mfma_f32_16x16x32_bf16 v[2:5], v[186:189], v[230:233], v[2:5]
	v_mfma_f32_16x16x32_bf16 v[54:57], v[182:185], v[210:213], v[54:57]
	v_mfma_f32_16x16x32_bf16 v[50:53], v[190:193], v[210:213], v[50:53]
	v_mfma_f32_16x16x32_bf16 v[38:41], v[182:185], v[218:221], v[38:41]
	v_mfma_f32_16x16x32_bf16 v[34:37], v[190:193], v[218:221], v[34:37]
	v_mfma_f32_16x16x32_bf16 v[22:25], v[182:185], v[226:229], v[22:25]
	v_mfma_f32_16x16x32_bf16 v[18:21], v[190:193], v[226:229], v[18:21]
	v_mfma_f32_16x16x32_bf16 v[6:9], v[182:185], v[234:237], v[6:9]
	v_mfma_f32_16x16x32_bf16 v[2:5], v[190:193], v[234:237], v[2:5]
	s_barrier
	s_add_i32 s39, s39, 2
	s_add_u32 s10, s10, 0x100
	s_addc_u32 s11, s11, 0
	s_add_u32 s30, s30, 0x100
	s_addc_u32 s38, s38, 0
	s_cmp_gt_u32 s39, 13
	s_cbranch_scc0 .LBB0_190
	s_and_b64 vcc, exec, s[52:53]
	s_cbranch_vccz .LBB0_193
	s_barrier

; #define PG8_STAGE(bufoff, gbase, voff) do { _Pragma("unroll") for (int _i = 0; _i < 2; ++_i) \
;         __builtin_amdgcn_global_load_lds((const unsigned*)((const char*)(gbase) + (voff)[_i]), (PG8_LAS unsigned*)(lds + (bufoff) + ldsw + _i * 8192), 16, 0, 0); } while (0)
; #define PG8_LDA(dst, b, h) do { _Pragma("unroll") for (int m = 0; m < 4; ++m) _Pragma("unroll") for (int k = 0; k < 2; ++k) dst[m][k] = *(const PG8_LAS bf16x8*)(lds + PG8_SA(b, h) + aoff + m * 2048 + k * 1024); } while (0)
; #define PG8_WAIT_V(n) asm volatile("s_waitcnt vmcnt(" #n ")" ::: "memory")
; #define PG8_WAIT_L(n) asm volatile("s_waitcnt lgkmcnt(" #n ")" ::: "memory")
; #define PG8_BAR __builtin_amdgcn_s_barrier()
; template <class Epi, class Sched, bool ALIGN_EPI = false, bool SP2 = false, bool PAIR_ACC = false>
; __device__ __forceinline__ void gemm_phase(PG8_LAS unsigned char* lds, const Gemm g, const Sched& S, const Epi& E) {
;     ...
;         for (int t = 0; t < nt; t += 2) {
;             const bool last = (t == nt - 2);
;             const char* a1 = cA + (size_t)(t + 1) * kstep;
;             const char* a2 = last ? nA : cA + (size_t)(t + 2) * kstep; const char* b2 = last ? nB : cB + (size_t)(t + 2) * kstep;
;             const char* a3 = a2 + kstep; const char* b3 = b2 + kstep;
;             if (last && has_next) S.a_ready(nxt);
;             if constexpr (SP2) {
;             PG8_LDB(B0, 0, 0); PG8_LDB(B1, 0, 1); PG8_SCHED; PG8_LDA(At, 0, 0); PG8_STAGE(PG8_SA(1, 1), a1 + hstep, voffA);
;             PG8_WAIT_V(8); PG8_WAIT_L(0); PG8_BAR; PG8_MMA(0, 0, At, B0); PG8_MMA(0, 1, At, B1); PG8_BAR; PG8_SCHED;
;             PG8_LDA(At, 0, 1); PG8_STAGE(PG8_SB(0, 0), b2, voffB); PG8_STAGE(PG8_SB(0, 1), b2 + hstep, voffB); PG8_STAGE(PG8_SA(0, 0), a2, voffA);
;             PG8_WAIT_V(8); PG8_WAIT_L(0); PG8_BAR; PG8_MMA(1, 0, At, B0); PG8_MMA(1, 1, At, B1); PG8_BAR; PG8_SCHED;
;             PG8_LDB(B0, 1, 0); PG8_LDB(B1, 1, 1); PG8_SCHED; PG8_LDA(At, 1, 0); PG8_STAGE(PG8_SA(0, 1), a2 + hstep, voffA);
;             PG8_WAIT_V(8); PG8_WAIT_L(0); PG8_BAR; PG8_MMA(0, 0, At, B0); PG8_MMA(0, 1, At, B1); PG8_BAR; PG8_SCHED;
;             PG8_LDA(At, 1, 1); PG8_STAGE(PG8_SB(1, 0), b3, voffB); PG8_STAGE(PG8_SB(1, 1), b3 + hstep, voffB); PG8_STAGE(PG8_SA(1, 0), a3, voffA);
;             PG8_WAIT_V(8); PG8_WAIT_L(0); PG8_BAR; PG8_MMA(1, 0, At, B0); PG8_MMA(1, 1, At, B1); PG8_BAR; PG8_SCHED;
.LBB0_585:
	v_add_u32_e32 v142, s46, v206
	v_add_u32_e32 v166, s47, v206
	ds_read_b128 v[130:133], v142
	ds_read_b128 v[134:137], v142 offset:1024
	ds_read_b128 v[138:141], v142 offset:2048
	ds_read_b128 v[142:145], v142 offset:3072
	ds_read_b128 v[146:149], v166
	ds_read_b128 v[150:153], v166 offset:1024
	ds_read_b128 v[154:157], v166 offset:2048
	ds_read_b128 v[178:181], v166 offset:3072
	s_add_u32 s38, s8, 0xfffc0080
	s_addc_u32 s39, s9, -1
	s_cmp_eq_u32 s56, 12
	s_cselect_b32 s55, s43, s39
	s_cselect_b32 s54, s42, s38
	s_cselect_b32 s39, s29, s53
	s_cselect_b32 s38, s31, s51
	v_lshl_add_u64 v[198:199], s[8:9], 0, v[168:169]
	s_add_i32 m0, s34, 0xc000
	ds_read_b128 v[182:185], v208
	ds_read_b128 v[186:189], v208 offset:1024
	ds_read_b128 v[190:193], v208 offset:2048
	ds_read_b128 v[194:197], v208 offset:3072
	ds_read_b128 v[210:213], v208 offset:4096
	ds_read_b128 v[214:217], v208 offset:5120
	ds_read_b128 v[218:221], v208 offset:6144
	ds_read_b128 v[222:225], v208 offset:7168
	global_load_lds_dwordx4 v[198:199], off
	v_lshl_add_u64 v[198:199], s[8:9], 0, v[170:171]
	s_add_i32 m0, s34, 0xe000
	s_nop 0
	global_load_lds_dwordx4 v[198:199], off
	s_waitcnt vmcnt(8)
	s_waitcnt lgkmcnt(0)
	s_barrier
	v_mfma_f32_16x16x32_bf16 v[126:129], v[130:133], v[182:185], v[126:129]
	v_mfma_f32_16x16x32_bf16 v[122:125], v[138:141], v[182:185], v[122:125]
	v_mfma_f32_16x16x32_bf16 v[118:121], v[130:133], v[190:193], v[118:121]
	v_mfma_f32_16x16x32_bf16 v[114:117], v[138:141], v[190:193], v[114:117]
	v_mfma_f32_16x16x32_bf16 v[110:113], v[130:133], v[210:213], v[110:113]
	v_mfma_f32_16x16x32_bf16 v[106:109], v[138:141], v[210:213], v[106:109]
	v_mfma_f32_16x16x32_bf16 v[102:105], v[130:133], v[218:221], v[102:105]
	v_mfma_f32_16x16x32_bf16 v[98:101], v[138:141], v[218:221], v[98:101]
	v_mfma_f32_16x16x32_bf16 v[126:129], v[134:137], v[186:189], v[126:129]
	v_mfma_f32_16x16x32_bf16 v[122:125], v[142:145], v[186:189], v[122:125]
	v_mfma_f32_16x16x32_bf16 v[118:121], v[134:137], v[194:197], v[118:121]
	v_mfma_f32_16x16x32_bf16 v[114:117], v[142:145], v[194:197], v[114:117]
	v_mfma_f32_16x16x32_bf16 v[110:113], v[134:137], v[214:217], v[110:113]
	v_mfma_f32_16x16x32_bf16 v[106:109], v[142:145], v[214:217], v[106:109]
	v_mfma_f32_16x16x32_bf16 v[102:105], v[134:137], v[222:225], v[102:105]
	v_mfma_f32_16x16x32_bf16 v[98:101], v[142:145], v[222:225], v[98:101]
	v_mfma_f32_16x16x32_bf16 v[94:97], v[146:149], v[182:185], v[94:97]
	v_mfma_f32_16x16x32_bf16 v[90:93], v[154:157], v[182:185], v[90:93]
	v_mfma_f32_16x16x32_bf16 v[86:89], v[146:149], v[190:193], v[86:89]
	v_mfma_f32_16x16x32_bf16 v[82:85], v[154:157], v[190:193], v[82:85]
	v_mfma_f32_16x16x32_bf16 v[78:81], v[146:149], v[210:213], v[78:81]
	v_mfma_f32_16x16x32_bf16 v[74:77], v[154:157], v[210:213], v[74:77]
	v_mfma_f32_16x16x32_bf16 v[70:73], v[146:149], v[218:221], v[70:73]
	v_mfma_f32_16x16x32_bf16 v[66:69], v[154:157], v[218:221], v[66:69]
	v_mfma_f32_16x16x32_bf16 v[94:97], v[150:153], v[186:189], v[94:97]
	v_mfma_f32_16x16x32_bf16 v[90:93], v[178:181], v[186:189], v[90:93]
	v_mfma_f32_16x16x32_bf16 v[86:89], v[150:153], v[194:197], v[86:89]
	v_mfma_f32_16x16x32_bf16 v[82:85], v[178:181], v[194:197], v[82:85]
	v_mfma_f32_16x16x32_bf16 v[78:81], v[150:153], v[214:217], v[78:81]
	v_mfma_f32_16x16x32_bf16 v[74:77], v[178:181], v[214:217], v[74:77]
	v_mfma_f32_16x16x32_bf16 v[70:73], v[150:153], v[222:225], v[70:73]
	v_mfma_f32_16x16x32_bf16 v[66:69], v[178:181], v[222:225], v[66:69]
	s_barrier
	s_add_i32 s57, s46, s25
	v_lshl_add_u64 v[198:199], s[38:39], 0, v[160:161]
	s_mov_b32 m0, s57
	ds_read_b128 v[182:185], v208 offset:16384
	ds_read_b128 v[186:189], v208 offset:17408
	ds_read_b128 v[190:193], v208 offset:18432
	ds_read_b128 v[194:197], v208 offset:19456
	ds_read_b128 v[210:213], v208 offset:20480
	ds_read_b128 v[214:217], v208 offset:21504
	ds_read_b128 v[218:221], v208 offset:22528
	ds_read_b128 v[222:225], v208 offset:23552
	global_load_lds_dwordx4 v[198:199], off
	s_add_i32 m0, s57, 0x2000
	s_add_u32 s58, s38, 0x40000
	v_lshl_add_u64 v[226:227], s[38:39], 0, v[164:165]
	s_addc_u32 s59, s39, 0
	s_add_i32 s57, s47, s25
	global_load_lds_dwordx4 v[226:227], off
	v_lshl_add_u64 v[228:229], s[58:59], 0, v[160:161]
	s_mov_b32 m0, s57
	v_lshl_add_u64 v[230:231], s[54:55], 0, v[162:163]
	global_load_lds_dwordx4 v[228:229], off
	v_lshl_add_u64 v[228:229], s[58:59], 0, v[164:165]
	s_add_i32 m0, s57, 0x2000
	s_nop 0
	global_load_lds_dwordx4 v[228:229], off
	v_lshl_add_u64 v[228:229], s[54:55], 0, v[158:159]
	s_mov_b32 m0, s34
	s_nop 0
	global_load_lds_dwordx4 v[228:229], off
	s_mov_b32 m0, s35
	s_nop 0
	global_load_lds_dwordx4 v[230:231], off
	s_waitcnt vmcnt(8)
	s_waitcnt lgkmcnt(0)
	s_barrier
; #define PG8_STAGE(bufoff, gbase, voff) do { _Pragma("unroll") for (int _i = 0; _i < 2; ++_i) \
;         __builtin_amdgcn_global_load_lds((const unsigned*)((const char*)(gbase) + (voff)[_i]), (PG8_LAS unsigned*)(lds + (bufoff) + ldsw + _i * 8192), 16, 0, 0); } while (0)
; #define PG8_LDA(dst, b, h) do { _Pragma("unroll") for (int m = 0; m < 4; ++m) _Pragma("unroll") for (int k = 0; k < 2; ++k) dst[m][k] = *(const PG8_LAS bf16x8*)(lds + PG8_SA(b, h) + aoff + m * 2048 + k * 1024); } while (0)
; #define PG8_LDB(dst, b, h) do { _Pragma("unroll") for (int n = 0; n < 2; ++n) _Pragma("unroll") for (int k = 0; k < 2; ++k) dst[n][k] = *(const PG8_LAS bf16x8*)(lds + PG8_SB(b, h) + boff + n * 2048 + k * 1024); } while (0)
; #define PG8_MMA(ai, bj, At, Bt) do { __builtin_amdgcn_s_setprio(1); _Pragma("unroll") for (int m = 0; m < 4; ++m) _Pragma("unroll") for (int n = 0; n < 2; ++n) _Pragma("unroll") for (int k = 0; k < 2; ++k) \
;         acc[ai][bj][m][n] = __builtin_amdgcn_mfma_f32_16x16x32_bf16(Bt[n][k], At[m][k], acc[ai][bj][m][n], 0, 0, 0); __builtin_amdgcn_s_setprio(0); } while (0)
; template <class Epi, class Sched, bool ALIGN_EPI = false, bool SP2 = false, bool PAIR_ACC = false>
; __device__ __forceinline__ void gemm_phase(PG8_LAS unsigned char* lds, const Gemm g, const Sched& S, const Epi& E) {
;     ...
;             if constexpr (SP2) {
;             PG8_LDB(B0, 0, 0); PG8_LDB(B1, 0, 1); PG8_SCHED; PG8_LDA(At, 0, 0); PG8_STAGE(PG8_SA(1, 1), a1 + hstep, voffA);
;             PG8_WAIT_V(8); PG8_WAIT_L(0); PG8_BAR; PG8_MMA(0, 0, At, B0); PG8_MMA(0, 1, At, B1); PG8_BAR; PG8_SCHED;
;             PG8_LDA(At, 0, 1); PG8_STAGE(PG8_SB(0, 0), b2, voffB); PG8_STAGE(PG8_SB(0, 1), b2 + hstep, voffB); PG8_STAGE(PG8_SA(0, 0), a2, voffA);
;             PG8_WAIT_V(8); PG8_WAIT_L(0); PG8_BAR; PG8_MMA(1, 0, At, B0); PG8_MMA(1, 1, At, B1); PG8_BAR; PG8_SCHED;
;             PG8_LDB(B0, 1, 0); PG8_LDB(B1, 1, 1); PG8_SCHED; PG8_LDA(At, 1, 0); PG8_STAGE(PG8_SA(0, 1), a2 + hstep, voffA);
;             PG8_WAIT_V(8); PG8_WAIT_L(0); PG8_BAR; PG8_MMA(0, 0, At, B0); PG8_MMA(0, 1, At, B1); PG8_BAR; PG8_SCHED;
;             PG8_LDA(At, 1, 1); PG8_STAGE(PG8_SB(1, 0), b3, voffB); PG8_STAGE(PG8_SB(1, 1), b3 + hstep, voffB); PG8_STAGE(PG8_SA(1, 0), a3, voffA);
;             PG8_WAIT_V(8); PG8_WAIT_L(0); PG8_BAR; PG8_MMA(1, 0, At, B0); PG8_MMA(1, 1, At, B1); PG8_BAR; PG8_SCHED;
	v_mfma_f32_16x16x32_bf16 v[62:65], v[130:133], v[182:185], v[62:65]
	v_mfma_f32_16x16x32_bf16 v[58:61], v[138:141], v[182:185], v[58:61]
	v_mfma_f32_16x16x32_bf16 v[54:57], v[130:133], v[190:193], v[54:57]
	v_mfma_f32_16x16x32_bf16 v[50:53], v[138:141], v[190:193], v[50:53]
	v_mfma_f32_16x16x32_bf16 v[46:49], v[130:133], v[210:213], v[46:49]
	v_mfma_f32_16x16x32_bf16 v[42:45], v[138:141], v[210:213], v[42:45]
	v_mfma_f32_16x16x32_bf16 v[38:41], v[130:133], v[218:221], v[38:41]
	v_mfma_f32_16x16x32_bf16 v[34:37], v[138:141], v[218:221], v[34:37]
	v_mfma_f32_16x16x32_bf16 v[62:65], v[134:137], v[186:189], v[62:65]
	v_mfma_f32_16x16x32_bf16 v[58:61], v[142:145], v[186:189], v[58:61]
	v_mfma_f32_16x16x32_bf16 v[54:57], v[134:137], v[194:197], v[54:57]
	v_mfma_f32_16x16x32_bf16 v[50:53], v[142:145], v[194:197], v[50:53]
	v_mfma_f32_16x16x32_bf16 v[46:49], v[134:137], v[214:217], v[46:49]
	v_mfma_f32_16x16x32_bf16 v[42:45], v[142:145], v[214:217], v[42:45]
	v_mfma_f32_16x16x32_bf16 v[38:41], v[134:137], v[222:225], v[38:41]
	v_mfma_f32_16x16x32_bf16 v[34:37], v[142:145], v[222:225], v[34:37]
	v_mfma_f32_16x16x32_bf16 v[30:33], v[146:149], v[182:185], v[30:33]
	v_mfma_f32_16x16x32_bf16 v[26:29], v[154:157], v[182:185], v[26:29]
	v_mfma_f32_16x16x32_bf16 v[22:25], v[146:149], v[190:193], v[22:25]
	v_mfma_f32_16x16x32_bf16 v[18:21], v[154:157], v[190:193], v[18:21]
	v_mfma_f32_16x16x32_bf16 v[14:17], v[146:149], v[210:213], v[14:17]
	v_mfma_f32_16x16x32_bf16 v[10:13], v[154:157], v[210:213], v[10:13]
	v_mfma_f32_16x16x32_bf16 v[6:9], v[146:149], v[218:221], v[6:9]
	v_mfma_f32_16x16x32_bf16 v[2:5], v[154:157], v[218:221], v[2:5]
	v_mfma_f32_16x16x32_bf16 v[30:33], v[150:153], v[186:189], v[30:33]
	v_mfma_f32_16x16x32_bf16 v[26:29], v[178:181], v[186:189], v[26:29]
	v_mfma_f32_16x16x32_bf16 v[22:25], v[150:153], v[194:197], v[22:25]
	v_mfma_f32_16x16x32_bf16 v[18:21], v[178:181], v[194:197], v[18:21]
	v_mfma_f32_16x16x32_bf16 v[14:17], v[150:153], v[214:217], v[14:17]
	v_mfma_f32_16x16x32_bf16 v[10:13], v[178:181], v[214:217], v[10:13]
	v_mfma_f32_16x16x32_bf16 v[6:9], v[150:153], v[222:225], v[6:9]
	v_mfma_f32_16x16x32_bf16 v[2:5], v[178:181], v[222:225], v[2:5]
	s_barrier
	s_add_i32 s57, 0, 0x18000
	s_add_i32 s58, 0, 0x1c000
	v_add_u32_e32 v142, s57, v206
	v_add_u32_e32 v166, s58, v206
	ds_read_b128 v[130:133], v142
	ds_read_b128 v[134:137], v142 offset:1024
	ds_read_b128 v[138:141], v142 offset:2048
	ds_read_b128 v[142:145], v142 offset:3072
	ds_read_b128 v[146:149], v166
	ds_read_b128 v[150:153], v166 offset:1024
	ds_read_b128 v[154:157], v166 offset:2048
	ds_read_b128 v[178:181], v166 offset:3072
	s_add_u32 s54, s54, 0x40000
	s_addc_u32 s55, s55, 0
	s_mov_b32 m0, s36
	v_lshl_add_u64 v[232:233], s[54:55], 0, v[158:159]
	ds_read_b128 v[182:185], v208 offset:32768
	ds_read_b128 v[186:189], v208 offset:33792
	ds_read_b128 v[190:193], v208 offset:34816
	ds_read_b128 v[194:197], v208 offset:35840
	ds_read_b128 v[210:213], v208 offset:36864
	ds_read_b128 v[214:217], v208 offset:37888
	ds_read_b128 v[218:221], v208 offset:38912
	ds_read_b128 v[222:225], v208 offset:39936
	global_load_lds_dwordx4 v[232:233], off
	v_lshl_add_u64 v[232:233], s[54:55], 0, v[162:163]
	s_mov_b32 m0, s37
	s_nop 0
	global_load_lds_dwordx4 v[232:233], off
	s_waitcnt vmcnt(8)
	s_waitcnt lgkmcnt(0)
	s_barrier
	v_mfma_f32_16x16x32_bf16 v[126:129], v[130:133], v[182:185], v[126:129]
	v_mfma_f32_16x16x32_bf16 v[122:125], v[138:141], v[182:185], v[122:125]
	v_mfma_f32_16x16x32_bf16 v[118:121], v[130:133], v[190:193], v[118:121]
	v_mfma_f32_16x16x32_bf16 v[114:117], v[138:141], v[190:193], v[114:117]
	v_mfma_f32_16x16x32_bf16 v[110:113], v[130:133], v[210:213], v[110:113]
	v_mfma_f32_16x16x32_bf16 v[106:109], v[138:141], v[210:213], v[106:109]
	v_mfma_f32_16x16x32_bf16 v[102:105], v[130:133], v[218:221], v[102:105]
	v_mfma_f32_16x16x32_bf16 v[98:101], v[138:141], v[218:221], v[98:101]
	v_mfma_f32_16x16x32_bf16 v[126:129], v[134:137], v[186:189], v[126:129]
	v_mfma_f32_16x16x32_bf16 v[122:125], v[142:145], v[186:189], v[122:125]
	v_mfma_f32_16x16x32_bf16 v[118:121], v[134:137], v[194:197], v[118:121]
	v_mfma_f32_16x16x32_bf16 v[114:117], v[142:145], v[194:197], v[114:117]
	v_mfma_f32_16x16x32_bf16 v[110:113], v[134:137], v[214:217], v[110:113]
	v_mfma_f32_16x16x32_bf16 v[106:109], v[142:145], v[214:217], v[106:109]
	v_mfma_f32_16x16x32_bf16 v[102:105], v[134:137], v[222:225], v[102:105]
	v_mfma_f32_16x16x32_bf16 v[98:101], v[142:145], v[222:225], v[98:101]
	v_mfma_f32_16x16x32_bf16 v[94:97], v[146:149], v[182:185], v[94:97]
	v_mfma_f32_16x16x32_bf16 v[90:93], v[154:157], v[182:185], v[90:93]
	v_mfma_f32_16x16x32_bf16 v[86:89], v[146:149], v[190:193], v[86:89]
	v_mfma_f32_16x16x32_bf16 v[82:85], v[154:157], v[190:193], v[82:85]
	v_mfma_f32_16x16x32_bf16 v[78:81], v[146:149], v[210:213], v[78:81]
	v_mfma_f32_16x16x32_bf16 v[74:77], v[154:157], v[210:213], v[74:77]
	v_mfma_f32_16x16x32_bf16 v[70:73], v[146:149], v[218:221], v[70:73]
	v_mfma_f32_16x16x32_bf16 v[66:69], v[154:157], v[218:221], v[66:69]
	v_mfma_f32_16x16x32_bf16 v[94:97], v[150:153], v[186:189], v[94:97]
	v_mfma_f32_16x16x32_bf16 v[90:93], v[178:181], v[186:189], v[90:93]
	v_mfma_f32_16x16x32_bf16 v[86:89], v[150:153], v[194:197], v[86:89]
	v_mfma_f32_16x16x32_bf16 v[82:85], v[178:181], v[194:197], v[82:85]
	v_mfma_f32_16x16x32_bf16 v[78:81], v[150:153], v[214:217], v[78:81]
	v_mfma_f32_16x16x32_bf16 v[74:77], v[178:181], v[214:217], v[74:77]
	v_mfma_f32_16x16x32_bf16 v[70:73], v[150:153], v[222:225], v[70:73]
	v_mfma_f32_16x16x32_bf16 v[66:69], v[178:181], v[222:225], v[66:69]
	s_barrier
; #define PG8_STAGE(bufoff, gbase, voff) do { _Pragma("unroll") for (int _i = 0; _i < 2; ++_i) \
;         __builtin_amdgcn_global_load_lds((const unsigned*)((const char*)(gbase) + (voff)[_i]), (PG8_LAS unsigned*)(lds + (bufoff) + ldsw + _i * 8192), 16, 0, 0); } while (0)
; #define PG8_LDA(dst, b, h) do { _Pragma("unroll") for (int m = 0; m < 4; ++m) _Pragma("unroll") for (int k = 0; k < 2; ++k) dst[m][k] = *(const PG8_LAS bf16x8*)(lds + PG8_SA(b, h) + aoff + m * 2048 + k * 1024); } while (0)
; #define PG8_LDB(dst, b, h) do { _Pragma("unroll") for (int n = 0; n < 2; ++n) _Pragma("unroll") for (int k = 0; k < 2; ++k) dst[n][k] = *(const PG8_LAS bf16x8*)(lds + PG8_SB(b, h) + boff + n * 2048 + k * 1024); } while (0)
; #define PG8_MMA(ai, bj, At, Bt) do { __builtin_amdgcn_s_setprio(1); _Pragma("unroll") for (int m = 0; m < 4; ++m) _Pragma("unroll") for (int n = 0; n < 2; ++n) _Pragma("unroll") for (int k = 0; k < 2; ++k) \
;         acc[ai][bj][m][n] = __builtin_amdgcn_mfma_f32_16x16x32_bf16(Bt[n][k], At[m][k], acc[ai][bj][m][n], 0, 0, 0); __builtin_amdgcn_s_setprio(0); } while (0)
; template <class Epi, class Sched, bool ALIGN_EPI = false, bool SP2 = false, bool PAIR_ACC = false>
; __device__ __forceinline__ void gemm_phase(PG8_LAS unsigned char* lds, const Gemm g, const Sched& S, const Epi& E) {
;     ...
;             if constexpr (SP2) {
;             PG8_LDB(B0, 0, 0); PG8_LDB(B1, 0, 1); PG8_SCHED; PG8_LDA(At, 0, 0); PG8_STAGE(PG8_SA(1, 1), a1 + hstep, voffA);
;             PG8_WAIT_V(8); PG8_WAIT_L(0); PG8_BAR; PG8_MMA(0, 0, At, B0); PG8_MMA(0, 1, At, B1); PG8_BAR; PG8_SCHED;
;             PG8_LDA(At, 0, 1); PG8_STAGE(PG8_SB(0, 0), b2, voffB); PG8_STAGE(PG8_SB(0, 1), b2 + hstep, voffB); PG8_STAGE(PG8_SA(0, 0), a2, voffA);
;             PG8_WAIT_V(8); PG8_WAIT_L(0); PG8_BAR; PG8_MMA(1, 0, At, B0); PG8_MMA(1, 1, At, B1); PG8_BAR; PG8_SCHED;
;             PG8_LDB(B0, 1, 0); PG8_LDB(B1, 1, 1); PG8_SCHED; PG8_LDA(At, 1, 0); PG8_STAGE(PG8_SA(0, 1), a2 + hstep, voffA);
;             PG8_WAIT_V(8); PG8_WAIT_L(0); PG8_BAR; PG8_MMA(0, 0, At, B0); PG8_MMA(0, 1, At, B1); PG8_BAR; PG8_SCHED;
;             PG8_LDA(At, 1, 1); PG8_STAGE(PG8_SB(1, 0), b3, voffB); PG8_STAGE(PG8_SB(1, 1), b3 + hstep, voffB); PG8_STAGE(PG8_SA(1, 0), a3, voffA);
;             PG8_WAIT_V(8); PG8_WAIT_L(0); PG8_BAR; PG8_MMA(1, 0, At, B0); PG8_MMA(1, 1, At, B1); PG8_BAR; PG8_SCHED;
	s_add_i32 s54, s57, s25
	v_lshl_add_u64 v[198:199], v[198:199], 0, s[18:19]
	s_mov_b32 m0, s54
	ds_read_b128 v[182:185], v208 offset:49152
	ds_read_b128 v[186:189], v208 offset:50176
	ds_read_b128 v[190:193], v208 offset:51200
	ds_read_b128 v[194:197], v208 offset:52224
	ds_read_b128 v[210:213], v208 offset:53248
	ds_read_b128 v[214:217], v208 offset:54272
	ds_read_b128 v[218:221], v208 offset:55296
	ds_read_b128 v[222:225], v208 offset:56320
	global_load_lds_dwordx4 v[198:199], off
	s_add_i32 m0, s54, 0x2000
	s_add_u32 s38, s38, 0x40080
	v_lshl_add_u64 v[198:199], v[226:227], 0, s[18:19]
	s_addc_u32 s39, s39, 0
	s_add_i32 s54, s58, s25
	global_load_lds_dwordx4 v[198:199], off
	v_lshl_add_u64 v[198:199], s[38:39], 0, v[160:161]
	s_mov_b32 m0, s54
	s_nop 0
	global_load_lds_dwordx4 v[198:199], off
	v_lshl_add_u64 v[198:199], s[38:39], 0, v[164:165]
	s_add_i32 m0, s54, 0x2000
	s_nop 0
	global_load_lds_dwordx4 v[198:199], off
	v_lshl_add_u64 v[198:199], v[228:229], 0, s[18:19]
	s_mov_b32 m0, s41
	s_nop 0
	global_load_lds_dwordx4 v[198:199], off
	v_lshl_add_u64 v[198:199], v[230:231], 0, s[18:19]
	s_mov_b32 m0, s44
	s_nop 0
	global_load_lds_dwordx4 v[198:199], off
	s_waitcnt vmcnt(8)
	s_waitcnt lgkmcnt(0)
	s_barrier
	v_mfma_f32_16x16x32_bf16 v[62:65], v[130:133], v[182:185], v[62:65]
	v_mfma_f32_16x16x32_bf16 v[58:61], v[138:141], v[182:185], v[58:61]
	v_mfma_f32_16x16x32_bf16 v[54:57], v[130:133], v[190:193], v[54:57]
	v_mfma_f32_16x16x32_bf16 v[50:53], v[138:141], v[190:193], v[50:53]
	v_mfma_f32_16x16x32_bf16 v[46:49], v[130:133], v[210:213], v[46:49]
	v_mfma_f32_16x16x32_bf16 v[42:45], v[138:141], v[210:213], v[42:45]
	v_mfma_f32_16x16x32_bf16 v[38:41], v[130:133], v[218:221], v[38:41]
	v_mfma_f32_16x16x32_bf16 v[34:37], v[138:141], v[218:221], v[34:37]
	v_mfma_f32_16x16x32_bf16 v[62:65], v[134:137], v[186:189], v[62:65]
	v_mfma_f32_16x16x32_bf16 v[58:61], v[142:145], v[186:189], v[58:61]
	v_mfma_f32_16x16x32_bf16 v[54:57], v[134:137], v[194:197], v[54:57]
	v_mfma_f32_16x16x32_bf16 v[50:53], v[142:145], v[194:197], v[50:53]
	v_mfma_f32_16x16x32_bf16 v[46:49], v[134:137], v[214:217], v[46:49]
	v_mfma_f32_16x16x32_bf16 v[42:45], v[142:145], v[214:217], v[42:45]
	v_mfma_f32_16x16x32_bf16 v[38:41], v[134:137], v[222:225], v[38:41]
	v_mfma_f32_16x16x32_bf16 v[34:37], v[142:145], v[222:225], v[34:37]
	v_mfma_f32_16x16x32_bf16 v[30:33], v[146:149], v[182:185], v[30:33]
	v_mfma_f32_16x16x32_bf16 v[26:29], v[154:157], v[182:185], v[26:29]
	v_mfma_f32_16x16x32_bf16 v[22:25], v[146:149], v[190:193], v[22:25]
	v_mfma_f32_16x16x32_bf16 v[18:21], v[154:157], v[190:193], v[18:21]
	v_mfma_f32_16x16x32_bf16 v[14:17], v[146:149], v[210:213], v[14:17]
	v_mfma_f32_16x16x32_bf16 v[10:13], v[154:157], v[210:213], v[10:13]
	v_mfma_f32_16x16x32_bf16 v[6:9], v[146:149], v[218:221], v[6:9]
	v_mfma_f32_16x16x32_bf16 v[2:5], v[154:157], v[218:221], v[2:5]
	v_mfma_f32_16x16x32_bf16 v[30:33], v[150:153], v[186:189], v[30:33]
	v_mfma_f32_16x16x32_bf16 v[26:29], v[178:181], v[186:189], v[26:29]
	v_mfma_f32_16x16x32_bf16 v[22:25], v[150:153], v[194:197], v[22:25]
	v_mfma_f32_16x16x32_bf16 v[18:21], v[178:181], v[194:197], v[18:21]
	v_mfma_f32_16x16x32_bf16 v[14:17], v[150:153], v[214:217], v[14:17]
	v_mfma_f32_16x16x32_bf16 v[10:13], v[178:181], v[214:217], v[10:13]
	v_mfma_f32_16x16x32_bf16 v[6:9], v[150:153], v[222:225], v[6:9]
	v_mfma_f32_16x16x32_bf16 v[2:5], v[178:181], v[222:225], v[2:5]
	s_barrier
	s_add_i32 s56, s56, 2
	s_add_u32 s8, s8, 0x100
	s_addc_u32 s9, s9, 0
	s_add_u32 s51, s51, 0x100
	s_addc_u32 s53, s53, 0
	s_cmp_gt_u32 s56, 13
	s_cbranch_scc0 .LBB0_585
	s_and_b64 vcc, exec, s[20:21]
	s_cbranch_vccz .LBB0_588
	s_barrier

; #define PG8_STAGE(bufoff, gbase, voff) do { _Pragma("unroll") for (int _i = 0; _i < 2; ++_i) \
;         __builtin_amdgcn_global_load_lds((const unsigned*)((const char*)(gbase) + (voff)[_i]), (PG8_LAS unsigned*)(lds + (bufoff) + ldsw + _i * 8192), 16, 0, 0); } while (0)
; #define PG8_LDA(dst, b, h) do { _Pragma("unroll") for (int m = 0; m < 4; ++m) _Pragma("unroll") for (int k = 0; k < 2; ++k) dst[m][k] = *(const PG8_LAS bf16x8*)(lds + PG8_SA(b, h) + aoff + m * 2048 + k * 1024); } while (0)
; #define PG8_LDB(dst, b, h) do { _Pragma("unroll") for (int n = 0; n < 2; ++n) _Pragma("unroll") for (int k = 0; k < 2; ++k) dst[n][k] = *(const PG8_LAS bf16x8*)(lds + PG8_SB(b, h) + boff + n * 2048 + k * 1024); } while (0)
; #define PG8_MMA(ai, bj, At, Bt) do { __builtin_amdgcn_s_setprio(1); _Pragma("unroll") for (int m = 0; m < 4; ++m) _Pragma("unroll") for (int n = 0; n < 2; ++n) _Pragma("unroll") for (int k = 0; k < 2; ++k) \
;         acc[ai][bj][m][n] = __builtin_amdgcn_mfma_f32_16x16x32_bf16(Bt[n][k], At[m][k], acc[ai][bj][m][n], 0, 0, 0); __builtin_amdgcn_s_setprio(0); } while (0)
; #define PG8_WAIT_V(n) asm volatile("s_waitcnt vmcnt(" #n ")" ::: "memory")
; #define PG8_WAIT_L(n) asm volatile("s_waitcnt lgkmcnt(" #n ")" ::: "memory")
; template <class Epi, class Sched, bool ALIGN_EPI = false, bool SP2 = false, bool PAIR_ACC = false>
; __device__ __forceinline__ void gemm_phase(PG8_LAS unsigned char* lds, const Gemm g, const Sched& S, const Epi& E) {
;     ...
;             const bool last = (t == nt - 2);
;             const char* a1 = cA + (size_t)(t + 1) * kstep;
;             const char* a2 = last ? nA : cA + (size_t)(t + 2) * kstep; const char* b2 = last ? nB : cB + (size_t)(t + 2) * kstep;
;             const char* a3 = a2 + kstep; const char* b3 = b2 + kstep;
;             if (last && has_next) S.a_ready(nxt);
;             if constexpr (SP2) {
;             PG8_LDB(B0, 0, 0); PG8_LDB(B1, 0, 1); PG8_SCHED; PG8_LDA(At, 0, 0); PG8_STAGE(PG8_SA(1, 1), a1 + hstep, voffA);
;             PG8_WAIT_V(8); PG8_WAIT_L(0); PG8_BAR; PG8_MMA(0, 0, At, B0); PG8_MMA(0, 1, At, B1); PG8_BAR; PG8_SCHED;
;             PG8_LDA(At, 0, 1); PG8_STAGE(PG8_SB(0, 0), b2, voffB); PG8_STAGE(PG8_SB(0, 1), b2 + hstep, voffB); PG8_STAGE(PG8_SA(0, 0), a2, voffA);
;             PG8_WAIT_V(8); PG8_WAIT_L(0); PG8_BAR; PG8_MMA(1, 0, At, B0); PG8_MMA(1, 1, At, B1); PG8_BAR; PG8_SCHED;
.LBB0_727:
	v_add_u32_e32 v164, s57, v150
	ds_read_b128 v[152:155], v164
	ds_read_b128 v[156:159], v164 offset:1024
	ds_read_b128 v[160:163], v164 offset:2048
	ds_read_b128 v[174:177], v164 offset:3072
	v_add_u32_e32 v164, s58, v150
	s_add_u32 s38, s20, s52
	ds_read_b128 v[178:181], v164
	ds_read_b128 v[182:185], v164 offset:1024
	ds_read_b128 v[186:189], v164 offset:2048
	ds_read_b128 v[190:193], v164 offset:3072
	s_addc_u32 s39, s21, s53
	s_add_u32 s38, s38, 0x100
	s_addc_u32 s39, s39, 0
	s_add_u32 s65, s60, s52
	s_addc_u32 s66, s61, s53
	s_cmpk_eq_i32 s52, 0x700
	s_cselect_b32 s55, s43, s39
	s_cselect_b32 s54, s62, s38
	s_cselect_b32 s39, s31, s66
	s_cselect_b32 s38, s63, s65
	v_lshl_add_u64 v[164:165], v[146:147], 0, s[52:53]
	s_add_i32 m0, s40, 0xc000
	ds_read_b128 v[194:197], v151
	ds_read_b128 v[206:209], v151 offset:1024
	ds_read_b128 v[210:213], v151 offset:2048
	ds_read_b128 v[214:217], v151 offset:3072
	ds_read_b128 v[218:221], v151 offset:4096
	ds_read_b128 v[222:225], v151 offset:5120
	ds_read_b128 v[226:229], v151 offset:6144
	ds_read_b128 v[230:233], v151 offset:7168
	global_load_lds_dwordx4 v[164:165], off
	v_lshl_add_u64 v[164:165], v[148:149], 0, s[52:53]
	s_add_i32 m0, s40, 0xe000
	s_nop 0
	global_load_lds_dwordx4 v[164:165], off
	s_waitcnt vmcnt(8)
	s_waitcnt lgkmcnt(0)
	s_barrier
	v_mfma_f32_16x16x32_bf16 v[122:125], v[152:155], v[194:197], v[122:125]
	v_mfma_f32_16x16x32_bf16 v[126:129], v[160:163], v[194:197], v[126:129]
	v_mfma_f32_16x16x32_bf16 v[110:113], v[152:155], v[210:213], v[110:113]
	v_mfma_f32_16x16x32_bf16 v[106:109], v[160:163], v[210:213], v[106:109]
	v_mfma_f32_16x16x32_bf16 v[102:105], v[152:155], v[218:221], v[102:105]
	v_mfma_f32_16x16x32_bf16 v[98:101], v[160:163], v[218:221], v[98:101]
	v_mfma_f32_16x16x32_bf16 v[94:97], v[152:155], v[226:229], v[94:97]
	v_mfma_f32_16x16x32_bf16 v[90:93], v[160:163], v[226:229], v[90:93]
	v_mfma_f32_16x16x32_bf16 v[122:125], v[156:159], v[206:209], v[122:125]
	v_mfma_f32_16x16x32_bf16 v[126:129], v[174:177], v[206:209], v[126:129]
	v_mfma_f32_16x16x32_bf16 v[110:113], v[156:159], v[214:217], v[110:113]
	v_mfma_f32_16x16x32_bf16 v[106:109], v[174:177], v[214:217], v[106:109]
	v_mfma_f32_16x16x32_bf16 v[102:105], v[156:159], v[222:225], v[102:105]
	v_mfma_f32_16x16x32_bf16 v[98:101], v[174:177], v[222:225], v[98:101]
	v_mfma_f32_16x16x32_bf16 v[94:97], v[156:159], v[230:233], v[94:97]
	v_mfma_f32_16x16x32_bf16 v[90:93], v[174:177], v[230:233], v[90:93]
	v_mfma_f32_16x16x32_bf16 v[118:121], v[178:181], v[194:197], v[118:121]
	v_mfma_f32_16x16x32_bf16 v[114:117], v[186:189], v[194:197], v[114:117]
	v_mfma_f32_16x16x32_bf16 v[70:73], v[178:181], v[210:213], v[70:73]
	v_mfma_f32_16x16x32_bf16 v[66:69], v[186:189], v[210:213], v[66:69]
	v_mfma_f32_16x16x32_bf16 v[62:65], v[178:181], v[218:221], v[62:65]
	v_mfma_f32_16x16x32_bf16 v[58:61], v[186:189], v[218:221], v[58:61]
	v_mfma_f32_16x16x32_bf16 v[54:57], v[178:181], v[226:229], v[54:57]
	v_mfma_f32_16x16x32_bf16 v[50:53], v[186:189], v[226:229], v[50:53]
	v_mfma_f32_16x16x32_bf16 v[118:121], v[182:185], v[206:209], v[118:121]
	v_mfma_f32_16x16x32_bf16 v[114:117], v[190:193], v[206:209], v[114:117]
	v_mfma_f32_16x16x32_bf16 v[70:73], v[182:185], v[214:217], v[70:73]
	v_mfma_f32_16x16x32_bf16 v[66:69], v[190:193], v[214:217], v[66:69]
	v_mfma_f32_16x16x32_bf16 v[62:65], v[182:185], v[222:225], v[62:65]
	v_mfma_f32_16x16x32_bf16 v[58:61], v[190:193], v[222:225], v[58:61]
	v_mfma_f32_16x16x32_bf16 v[54:57], v[182:185], v[230:233], v[54:57]
	v_mfma_f32_16x16x32_bf16 v[50:53], v[190:193], v[230:233], v[50:53]
	s_barrier
	s_add_i32 s65, s57, s37
	v_lshl_add_u64 v[164:165], s[38:39], 0, v[132:133]
	s_mov_b32 m0, s65
	ds_read_b128 v[194:197], v151 offset:16384
	ds_read_b128 v[206:209], v151 offset:17408
	ds_read_b128 v[210:213], v151 offset:18432
	ds_read_b128 v[214:217], v151 offset:19456
	ds_read_b128 v[218:221], v151 offset:20480
	ds_read_b128 v[222:225], v151 offset:21504
	ds_read_b128 v[226:229], v151 offset:22528
	ds_read_b128 v[230:233], v151 offset:23552
	global_load_lds_dwordx4 v[164:165], off
	s_add_i32 m0, s65, 0x2000
	s_add_u32 s66, s38, 0x40000
	v_lshl_add_u64 v[168:169], s[38:39], 0, v[136:137]
	s_addc_u32 s67, s39, 0
	s_add_i32 s65, s58, s37
	global_load_lds_dwordx4 v[168:169], off
	v_lshl_add_u64 v[198:199], s[66:67], 0, v[132:133]
	s_mov_b32 m0, s65
	v_lshl_add_u64 v[234:235], s[54:55], 0, v[134:135]
	global_load_lds_dwordx4 v[198:199], off
	v_lshl_add_u64 v[198:199], s[66:67], 0, v[136:137]
	s_add_i32 m0, s65, 0x2000
	s_nop 0
	global_load_lds_dwordx4 v[198:199], off
	v_lshl_add_u64 v[198:199], s[54:55], 0, v[130:131]
	s_mov_b32 m0, s40
	s_nop 0
	global_load_lds_dwordx4 v[198:199], off
	s_mov_b32 m0, s41
	s_nop 0
	global_load_lds_dwordx4 v[234:235], off
	s_waitcnt vmcnt(8)
	s_waitcnt lgkmcnt(0)
	s_barrier
; #define PG8_STAGE(bufoff, gbase, voff) do { _Pragma("unroll") for (int _i = 0; _i < 2; ++_i) \
;         __builtin_amdgcn_global_load_lds((const unsigned*)((const char*)(gbase) + (voff)[_i]), (PG8_LAS unsigned*)(lds + (bufoff) + ldsw + _i * 8192), 16, 0, 0); } while (0)
; #define PG8_LDA(dst, b, h) do { _Pragma("unroll") for (int m = 0; m < 4; ++m) _Pragma("unroll") for (int k = 0; k < 2; ++k) dst[m][k] = *(const PG8_LAS bf16x8*)(lds + PG8_SA(b, h) + aoff + m * 2048 + k * 1024); } while (0)
; #define PG8_LDB(dst, b, h) do { _Pragma("unroll") for (int n = 0; n < 2; ++n) _Pragma("unroll") for (int k = 0; k < 2; ++k) dst[n][k] = *(const PG8_LAS bf16x8*)(lds + PG8_SB(b, h) + boff + n * 2048 + k * 1024); } while (0)
; #define PG8_MMA(ai, bj, At, Bt) do { __builtin_amdgcn_s_setprio(1); _Pragma("unroll") for (int m = 0; m < 4; ++m) _Pragma("unroll") for (int n = 0; n < 2; ++n) _Pragma("unroll") for (int k = 0; k < 2; ++k) \
;         acc[ai][bj][m][n] = __builtin_amdgcn_mfma_f32_16x16x32_bf16(Bt[n][k], At[m][k], acc[ai][bj][m][n], 0, 0, 0); __builtin_amdgcn_s_setprio(0); } while (0)
; #define PG8_WAIT_V(n) asm volatile("s_waitcnt vmcnt(" #n ")" ::: "memory")
; #define PG8_WAIT_L(n) asm volatile("s_waitcnt lgkmcnt(" #n ")" ::: "memory")
; #define PG8_BAR __builtin_amdgcn_s_barrier()
; #define PG8_SCHED __builtin_amdgcn_sched_barrier(0)
; template <class Epi, class Sched, bool ALIGN_EPI = false, bool SP2 = false, bool PAIR_ACC = false>
; __device__ __forceinline__ void gemm_phase(PG8_LAS unsigned char* lds, const Gemm g, const Sched& S, const Epi& E) {
;     ...
;             PG8_WAIT_V(8); PG8_WAIT_L(0); PG8_BAR; PG8_MMA(1, 0, At, B0); PG8_MMA(1, 1, At, B1); PG8_BAR; PG8_SCHED;
;             PG8_LDB(B0, 1, 0); PG8_LDB(B1, 1, 1); PG8_SCHED; PG8_LDA(At, 1, 0); PG8_STAGE(PG8_SA(0, 1), a2 + hstep, voffA);
;             PG8_WAIT_V(8); PG8_WAIT_L(0); PG8_BAR; PG8_MMA(0, 0, At, B0); PG8_MMA(0, 1, At, B1); PG8_BAR; PG8_SCHED;
	v_mfma_f32_16x16x32_bf16 v[86:89], v[152:155], v[194:197], v[86:89]
	v_mfma_f32_16x16x32_bf16 v[82:85], v[160:163], v[194:197], v[82:85]
	v_mfma_f32_16x16x32_bf16 v[78:81], v[152:155], v[210:213], v[78:81]
	v_mfma_f32_16x16x32_bf16 v[74:77], v[160:163], v[210:213], v[74:77]
	v_mfma_f32_16x16x32_bf16 v[30:33], v[152:155], v[218:221], v[30:33]
	v_mfma_f32_16x16x32_bf16 v[26:29], v[160:163], v[218:221], v[26:29]
	v_mfma_f32_16x16x32_bf16 v[14:17], v[152:155], v[226:229], v[14:17]
	v_mfma_f32_16x16x32_bf16 v[10:13], v[160:163], v[226:229], v[10:13]
	v_mfma_f32_16x16x32_bf16 v[86:89], v[156:159], v[206:209], v[86:89]
	v_mfma_f32_16x16x32_bf16 v[82:85], v[174:177], v[206:209], v[82:85]
	v_mfma_f32_16x16x32_bf16 v[78:81], v[156:159], v[214:217], v[78:81]
	v_mfma_f32_16x16x32_bf16 v[74:77], v[174:177], v[214:217], v[74:77]
	v_mfma_f32_16x16x32_bf16 v[30:33], v[156:159], v[222:225], v[30:33]
	v_mfma_f32_16x16x32_bf16 v[26:29], v[174:177], v[222:225], v[26:29]
	v_mfma_f32_16x16x32_bf16 v[14:17], v[156:159], v[230:233], v[14:17]
	v_mfma_f32_16x16x32_bf16 v[10:13], v[174:177], v[230:233], v[10:13]
	v_mfma_f32_16x16x32_bf16 v[46:49], v[178:181], v[194:197], v[46:49]
	v_mfma_f32_16x16x32_bf16 v[42:45], v[186:189], v[194:197], v[42:45]
	v_mfma_f32_16x16x32_bf16 v[38:41], v[178:181], v[210:213], v[38:41]
	v_mfma_f32_16x16x32_bf16 v[34:37], v[186:189], v[210:213], v[34:37]
	v_mfma_f32_16x16x32_bf16 v[22:25], v[178:181], v[218:221], v[22:25]
	v_mfma_f32_16x16x32_bf16 v[18:21], v[186:189], v[218:221], v[18:21]
	v_mfma_f32_16x16x32_bf16 v[6:9], v[178:181], v[226:229], v[6:9]
	v_mfma_f32_16x16x32_bf16 v[2:5], v[186:189], v[226:229], v[2:5]
	v_mfma_f32_16x16x32_bf16 v[46:49], v[182:185], v[206:209], v[46:49]
	v_mfma_f32_16x16x32_bf16 v[42:45], v[190:193], v[206:209], v[42:45]
	v_mfma_f32_16x16x32_bf16 v[38:41], v[182:185], v[214:217], v[38:41]
	v_mfma_f32_16x16x32_bf16 v[34:37], v[190:193], v[214:217], v[34:37]
	v_mfma_f32_16x16x32_bf16 v[22:25], v[182:185], v[222:225], v[22:25]
	v_mfma_f32_16x16x32_bf16 v[18:21], v[190:193], v[222:225], v[18:21]
	v_mfma_f32_16x16x32_bf16 v[6:9], v[182:185], v[230:233], v[6:9]
	v_mfma_f32_16x16x32_bf16 v[2:5], v[190:193], v[230:233], v[2:5]
	s_barrier
	s_add_i32 s65, 0, 0x18000
	v_add_u32_e32 v167, s65, v150
	s_add_i32 s66, 0, 0x1c000
	ds_read_b128 v[152:155], v167
	ds_read_b128 v[156:159], v167 offset:1024
	ds_read_b128 v[160:163], v167 offset:2048
	ds_read_b128 v[174:177], v167 offset:3072
	v_add_u32_e32 v167, s66, v150
	ds_read_b128 v[178:181], v167
	ds_read_b128 v[182:185], v167 offset:1024
	ds_read_b128 v[186:189], v167 offset:2048
	ds_read_b128 v[190:193], v167 offset:3072
	s_add_u32 s54, s54, 0x40000
	s_addc_u32 s55, s55, 0
	s_mov_b32 m0, s44
	v_lshl_add_u64 v[236:237], s[54:55], 0, v[130:131]
	ds_read_b128 v[194:197], v151 offset:32768
	ds_read_b128 v[206:209], v151 offset:33792
	ds_read_b128 v[210:213], v151 offset:34816
	ds_read_b128 v[214:217], v151 offset:35840
	ds_read_b128 v[218:221], v151 offset:36864
	ds_read_b128 v[222:225], v151 offset:37888
	ds_read_b128 v[226:229], v151 offset:38912
	ds_read_b128 v[230:233], v151 offset:39936
	global_load_lds_dwordx4 v[236:237], off
	v_lshl_add_u64 v[236:237], s[54:55], 0, v[134:135]
	s_mov_b32 m0, s45
	s_nop 0
	global_load_lds_dwordx4 v[236:237], off
	s_waitcnt vmcnt(8)
	s_waitcnt lgkmcnt(0)
	s_barrier
	v_mfma_f32_16x16x32_bf16 v[122:125], v[152:155], v[194:197], v[122:125]
	v_mfma_f32_16x16x32_bf16 v[126:129], v[160:163], v[194:197], v[126:129]
	v_mfma_f32_16x16x32_bf16 v[110:113], v[152:155], v[210:213], v[110:113]
	v_mfma_f32_16x16x32_bf16 v[106:109], v[160:163], v[210:213], v[106:109]
	v_mfma_f32_16x16x32_bf16 v[102:105], v[152:155], v[218:221], v[102:105]
	v_mfma_f32_16x16x32_bf16 v[98:101], v[160:163], v[218:221], v[98:101]
	v_mfma_f32_16x16x32_bf16 v[94:97], v[152:155], v[226:229], v[94:97]
	v_mfma_f32_16x16x32_bf16 v[90:93], v[160:163], v[226:229], v[90:93]
	v_mfma_f32_16x16x32_bf16 v[122:125], v[156:159], v[206:209], v[122:125]
	v_mfma_f32_16x16x32_bf16 v[126:129], v[174:177], v[206:209], v[126:129]
	v_mfma_f32_16x16x32_bf16 v[110:113], v[156:159], v[214:217], v[110:113]
	v_mfma_f32_16x16x32_bf16 v[106:109], v[174:177], v[214:217], v[106:109]
	v_mfma_f32_16x16x32_bf16 v[102:105], v[156:159], v[222:225], v[102:105]
	v_mfma_f32_16x16x32_bf16 v[98:101], v[174:177], v[222:225], v[98:101]
	v_mfma_f32_16x16x32_bf16 v[94:97], v[156:159], v[230:233], v[94:97]
	v_mfma_f32_16x16x32_bf16 v[90:93], v[174:177], v[230:233], v[90:93]
	v_mfma_f32_16x16x32_bf16 v[118:121], v[178:181], v[194:197], v[118:121]
	v_mfma_f32_16x16x32_bf16 v[114:117], v[186:189], v[194:197], v[114:117]
	v_mfma_f32_16x16x32_bf16 v[70:73], v[178:181], v[210:213], v[70:73]
	v_mfma_f32_16x16x32_bf16 v[66:69], v[186:189], v[210:213], v[66:69]
	v_mfma_f32_16x16x32_bf16 v[62:65], v[178:181], v[218:221], v[62:65]
	v_mfma_f32_16x16x32_bf16 v[58:61], v[186:189], v[218:221], v[58:61]
	v_mfma_f32_16x16x32_bf16 v[54:57], v[178:181], v[226:229], v[54:57]
	v_mfma_f32_16x16x32_bf16 v[50:53], v[186:189], v[226:229], v[50:53]
	v_mfma_f32_16x16x32_bf16 v[118:121], v[182:185], v[206:209], v[118:121]
	v_mfma_f32_16x16x32_bf16 v[114:117], v[190:193], v[206:209], v[114:117]
	v_mfma_f32_16x16x32_bf16 v[70:73], v[182:185], v[214:217], v[70:73]
	v_mfma_f32_16x16x32_bf16 v[66:69], v[190:193], v[214:217], v[66:69]
	v_mfma_f32_16x16x32_bf16 v[62:65], v[182:185], v[222:225], v[62:65]
	v_mfma_f32_16x16x32_bf16 v[58:61], v[190:193], v[222:225], v[58:61]
	v_mfma_f32_16x16x32_bf16 v[54:57], v[182:185], v[230:233], v[54:57]
	v_mfma_f32_16x16x32_bf16 v[50:53], v[190:193], v[230:233], v[50:53]
	s_barrier
; #define PG8_STAGE(bufoff, gbase, voff) do { _Pragma("unroll") for (int _i = 0; _i < 2; ++_i) \
;         __builtin_amdgcn_global_load_lds((const unsigned*)((const char*)(gbase) + (voff)[_i]), (PG8_LAS unsigned*)(lds + (bufoff) + ldsw + _i * 8192), 16, 0, 0); } while (0)
; #define PG8_LDA(dst, b, h) do { _Pragma("unroll") for (int m = 0; m < 4; ++m) _Pragma("unroll") for (int k = 0; k < 2; ++k) dst[m][k] = *(const PG8_LAS bf16x8*)(lds + PG8_SA(b, h) + aoff + m * 2048 + k * 1024); } while (0)
; #define PG8_MMA(ai, bj, At, Bt) do { __builtin_amdgcn_s_setprio(1); _Pragma("unroll") for (int m = 0; m < 4; ++m) _Pragma("unroll") for (int n = 0; n < 2; ++n) _Pragma("unroll") for (int k = 0; k < 2; ++k) \
;         acc[ai][bj][m][n] = __builtin_amdgcn_mfma_f32_16x16x32_bf16(Bt[n][k], At[m][k], acc[ai][bj][m][n], 0, 0, 0); __builtin_amdgcn_s_setprio(0); } while (0)
; #define PG8_WAIT_V(n) asm volatile("s_waitcnt vmcnt(" #n ")" ::: "memory")
; #define PG8_WAIT_L(n) asm volatile("s_waitcnt lgkmcnt(" #n ")" ::: "memory")
; #define PG8_BAR __builtin_amdgcn_s_barrier()
; #define PG8_SCHED __builtin_amdgcn_sched_barrier(0)
; template <class Epi, class Sched, bool ALIGN_EPI = false, bool SP2 = false, bool PAIR_ACC = false>
; __device__ __forceinline__ void gemm_phase(PG8_LAS unsigned char* lds, const Gemm g, const Sched& S, const Epi& E) {
;     ...
;             PG8_LDA(At, 1, 1); PG8_STAGE(PG8_SB(1, 0), b3, voffB); PG8_STAGE(PG8_SB(1, 1), b3 + hstep, voffB); PG8_STAGE(PG8_SA(1, 0), a3, voffA);
;             PG8_WAIT_V(8); PG8_WAIT_L(0); PG8_BAR; PG8_MMA(1, 0, At, B0); PG8_MMA(1, 1, At, B1); PG8_BAR; PG8_SCHED;
;     ...
;         if (!has_next) break;
;         if (!(PAIR_ACC && cur.pn < 4)) {
; #pragma unroll
;         for (int a = 0; a < 2; ++a)
; #pragma unroll
;             for (int b = 0; b < 2; ++b)
; #pragma unroll
;                 for (int m = 0; m < 4; ++m)
; #pragma unroll
;                     for (int n = 0; n < 2; ++n) acc[a][b][m][n] = (f32x4){0.f, 0.f, 0.f, 0.f};
;         }
	s_add_i32 s54, s65, s37
	v_lshl_add_u64 v[164:165], v[164:165], 0, s[28:29]
	s_mov_b32 m0, s54
	ds_read_b128 v[194:197], v151 offset:49152
	ds_read_b128 v[206:209], v151 offset:50176
	ds_read_b128 v[210:213], v151 offset:51200
	ds_read_b128 v[214:217], v151 offset:52224
	ds_read_b128 v[218:221], v151 offset:53248
	ds_read_b128 v[222:225], v151 offset:54272
	ds_read_b128 v[226:229], v151 offset:55296
	ds_read_b128 v[230:233], v151 offset:56320
	global_load_lds_dwordx4 v[164:165], off
	s_add_i32 m0, s54, 0x2000
	s_add_u32 s38, s38, 0x40080
	v_lshl_add_u64 v[164:165], v[168:169], 0, s[28:29]
	s_addc_u32 s39, s39, 0
	s_add_i32 s54, s66, s37
	global_load_lds_dwordx4 v[164:165], off
	v_lshl_add_u64 v[164:165], s[38:39], 0, v[132:133]
	s_mov_b32 m0, s54
	s_nop 0
	global_load_lds_dwordx4 v[164:165], off
	v_lshl_add_u64 v[164:165], s[38:39], 0, v[136:137]
	s_add_i32 m0, s54, 0x2000
	s_nop 0
	global_load_lds_dwordx4 v[164:165], off
	v_lshl_add_u64 v[164:165], v[198:199], 0, s[28:29]
	s_mov_b32 m0, s47
	s_nop 0
	global_load_lds_dwordx4 v[164:165], off
	v_lshl_add_u64 v[164:165], v[234:235], 0, s[28:29]
	s_mov_b32 m0, s56
	s_nop 0
	global_load_lds_dwordx4 v[164:165], off
	s_waitcnt vmcnt(8)
	s_waitcnt lgkmcnt(0)
	s_barrier
	v_mfma_f32_16x16x32_bf16 v[86:89], v[152:155], v[194:197], v[86:89]
	v_mfma_f32_16x16x32_bf16 v[82:85], v[160:163], v[194:197], v[82:85]
	v_mfma_f32_16x16x32_bf16 v[78:81], v[152:155], v[210:213], v[78:81]
	v_mfma_f32_16x16x32_bf16 v[74:77], v[160:163], v[210:213], v[74:77]
	v_mfma_f32_16x16x32_bf16 v[30:33], v[152:155], v[218:221], v[30:33]
	v_mfma_f32_16x16x32_bf16 v[26:29], v[160:163], v[218:221], v[26:29]
	v_mfma_f32_16x16x32_bf16 v[14:17], v[152:155], v[226:229], v[14:17]
	v_mfma_f32_16x16x32_bf16 v[10:13], v[160:163], v[226:229], v[10:13]
	v_mfma_f32_16x16x32_bf16 v[86:89], v[156:159], v[206:209], v[86:89]
	v_mfma_f32_16x16x32_bf16 v[82:85], v[174:177], v[206:209], v[82:85]
	v_mfma_f32_16x16x32_bf16 v[78:81], v[156:159], v[214:217], v[78:81]
	v_mfma_f32_16x16x32_bf16 v[74:77], v[174:177], v[214:217], v[74:77]
	v_mfma_f32_16x16x32_bf16 v[30:33], v[156:159], v[222:225], v[30:33]
	v_mfma_f32_16x16x32_bf16 v[26:29], v[174:177], v[222:225], v[26:29]
	v_mfma_f32_16x16x32_bf16 v[14:17], v[156:159], v[230:233], v[14:17]
	v_mfma_f32_16x16x32_bf16 v[10:13], v[174:177], v[230:233], v[10:13]
	v_mfma_f32_16x16x32_bf16 v[46:49], v[178:181], v[194:197], v[46:49]
	v_mfma_f32_16x16x32_bf16 v[42:45], v[186:189], v[194:197], v[42:45]
	v_mfma_f32_16x16x32_bf16 v[38:41], v[178:181], v[210:213], v[38:41]
	v_mfma_f32_16x16x32_bf16 v[34:37], v[186:189], v[210:213], v[34:37]
	v_mfma_f32_16x16x32_bf16 v[22:25], v[178:181], v[218:221], v[22:25]
	v_mfma_f32_16x16x32_bf16 v[18:21], v[186:189], v[218:221], v[18:21]
	v_mfma_f32_16x16x32_bf16 v[6:9], v[178:181], v[226:229], v[6:9]
	v_mfma_f32_16x16x32_bf16 v[2:5], v[186:189], v[226:229], v[2:5]
	v_mfma_f32_16x16x32_bf16 v[46:49], v[182:185], v[206:209], v[46:49]
	v_mfma_f32_16x16x32_bf16 v[42:45], v[190:193], v[206:209], v[42:45]
	v_mfma_f32_16x16x32_bf16 v[38:41], v[182:185], v[214:217], v[38:41]
	v_mfma_f32_16x16x32_bf16 v[34:37], v[190:193], v[214:217], v[34:37]
	v_mfma_f32_16x16x32_bf16 v[22:25], v[182:185], v[222:225], v[22:25]
	v_mfma_f32_16x16x32_bf16 v[18:21], v[190:193], v[222:225], v[18:21]
	v_mfma_f32_16x16x32_bf16 v[6:9], v[182:185], v[230:233], v[6:9]
	v_mfma_f32_16x16x32_bf16 v[2:5], v[190:193], v[230:233], v[2:5]
	s_barrier
	s_add_i32 s64, s64, 2
	s_add_u32 s52, s52, 0x100
	s_addc_u32 s53, s53, 0
	s_cmp_gt_u32 s64, 13
	s_cbranch_scc0 .LBB0_727
	s_add_u32 s38, s60, 0xffffff00
	s_addc_u32 s39, s61, -1
	s_andn2_b64 vcc, exec, s[8:9]
	s_cbranch_vccnz .LBB0_718
	v_mov_b32_e32 v2, 0
	s_mov_b32 s10, s30
	s_mov_b32 s16, s42
	s_mov_b64 s[20:21], s[50:51]
	s_mov_b32 s46, s59
	v_mov_b32_e32 v3, v2
	v_mov_b32_e32 v4, v2
	v_mov_b32_e32 v5, v2
	v_mov_b32_e32 v6, v2
	v_mov_b32_e32 v7, v2
	v_mov_b32_e32 v8, v2
	v_mov_b32_e32 v9, v2
	v_mov_b32_e32 v18, v2
	v_mov_b32_e32 v19, v2
	v_mov_b32_e32 v20, v2
	v_mov_b32_e32 v21, v2
	v_mov_b32_e32 v22, v2
	v_mov_b32_e32 v23, v2
	v_mov_b32_e32 v24, v2
	v_mov_b32_e32 v25, v2
	v_mov_b32_e32 v34, v2
	v_mov_b32_e32 v35, v2
	v_mov_b32_e32 v36, v2
	v_mov_b32_e32 v37, v2
	v_mov_b32_e32 v38, v2
	v_mov_b32_e32 v39, v2
	v_mov_b32_e32 v40, v2
	v_mov_b32_e32 v41, v2
	v_mov_b32_e32 v42, v2
	v_mov_b32_e32 v43, v2
	v_mov_b32_e32 v44, v2
	v_mov_b32_e32 v45, v2
	v_mov_b32_e32 v46, v2
	v_mov_b32_e32 v47, v2
	v_mov_b32_e32 v48, v2
	v_mov_b32_e32 v49, v2
	v_mov_b32_e32 v10, v2
	v_mov_b32_e32 v11, v2
	v_mov_b32_e32 v12, v2
	v_mov_b32_e32 v13, v2
	v_mov_b32_e32 v14, v2
	v_mov_b32_e32 v15, v2
	v_mov_b32_e32 v16, v2
	v_mov_b32_e32 v17, v2
	v_mov_b32_e32 v26, v2
	v_mov_b32_e32 v27, v2
	v_mov_b32_e32 v28, v2
	v_mov_b32_e32 v29, v2
	v_mov_b32_e32 v30, v2
	v_mov_b32_e32 v31, v2
	v_mov_b32_e32 v32, v2
	v_mov_b32_e32 v33, v2
	v_mov_b32_e32 v74, v2
	v_mov_b32_e32 v75, v2
	v_mov_b32_e32 v76, v2
	v_mov_b32_e32 v77, v2
	v_mov_b32_e32 v78, v2
	v_mov_b32_e32 v79, v2
	v_mov_b32_e32 v80, v2
	v_mov_b32_e32 v81, v2
	v_mov_b32_e32 v82, v2
	v_mov_b32_e32 v83, v2
	v_mov_b32_e32 v84, v2
	v_mov_b32_e32 v85, v2
	v_mov_b32_e32 v86, v2
	v_mov_b32_e32 v87, v2
	v_mov_b32_e32 v88, v2
	v_mov_b32_e32 v89, v2
	v_mov_b32_e32 v50, v2
	v_mov_b32_e32 v51, v2
	v_mov_b32_e32 v52, v2
	v_mov_b32_e32 v53, v2
	v_mov_b32_e32 v54, v2
	v_mov_b32_e32 v55, v2
	v_mov_b32_e32 v56, v2
	v_mov_b32_e32 v57, v2
	v_mov_b32_e32 v58, v2
	v_mov_b32_e32 v59, v2
	v_mov_b32_e32 v60, v2
	v_mov_b32_e32 v61, v2
	v_mov_b32_e32 v62, v2
	v_mov_b32_e32 v63, v2
	v_mov_b32_e32 v64, v2
	v_mov_b32_e32 v65, v2
	v_mov_b32_e32 v66, v2
	v_mov_b32_e32 v67, v2
	v_mov_b32_e32 v68, v2
	v_mov_b32_e32 v69, v2
	v_mov_b32_e32 v70, v2
	v_mov_b32_e32 v71, v2
	v_mov_b32_e32 v72, v2
	v_mov_b32_e32 v73, v2
	v_mov_b32_e32 v114, v2
	v_mov_b32_e32 v115, v2
	v_mov_b32_e32 v116, v2
	v_mov_b32_e32 v117, v2
	v_mov_b32_e32 v118, v2
	v_mov_b32_e32 v119, v2
	v_mov_b32_e32 v120, v2
	v_mov_b32_e32 v121, v2
	v_mov_b32_e32 v90, v2
	v_mov_b32_e32 v91, v2
	v_mov_b32_e32 v92, v2
	v_mov_b32_e32 v93, v2
	v_mov_b32_e32 v94, v2
	v_mov_b32_e32 v95, v2
	v_mov_b32_e32 v96, v2
	v_mov_b32_e32 v97, v2
	v_mov_b32_e32 v98, v2
	v_mov_b32_e32 v99, v2
	v_mov_b32_e32 v100, v2
	v_mov_b32_e32 v101, v2
	v_mov_b32_e32 v102, v2
	v_mov_b32_e32 v103, v2
	v_mov_b32_e32 v104, v2
	v_mov_b32_e32 v105, v2
	v_mov_b32_e32 v106, v2
	v_mov_b32_e32 v107, v2
	v_mov_b32_e32 v108, v2
	v_mov_b32_e32 v109, v2
	v_mov_b32_e32 v110, v2
	v_mov_b32_e32 v111, v2
	v_mov_b32_e32 v112, v2
	v_mov_b32_e32 v113, v2
	v_mov_b32_e32 v126, v2
	v_mov_b32_e32 v127, v2
	v_mov_b32_e32 v128, v2
	v_mov_b32_e32 v129, v2
	v_mov_b32_e32 v122, v2
	v_mov_b32_e32 v123, v2
	v_mov_b32_e32 v124, v2
	v_mov_b32_e32 v125, v2
	s_andn2_b64 vcc, exec, s[6:7]
	s_cbranch_vccnz .LBB0_719

; #define PG8_STAGE(bufoff, gbase, voff) do { _Pragma("unroll") for (int _i = 0; _i < 2; ++_i) \
;         __builtin_amdgcn_global_load_lds((const unsigned*)((const char*)(gbase) + (voff)[_i]), (PG8_LAS unsigned*)(lds + (bufoff) + ldsw + _i * 8192), 16, 0, 0); } while (0)
; #define PG8_LDA(dst, b, h) do { _Pragma("unroll") for (int m = 0; m < 4; ++m) _Pragma("unroll") for (int k = 0; k < 2; ++k) dst[m][k] = *(const PG8_LAS bf16x8*)(lds + PG8_SA(b, h) + aoff + m * 2048 + k * 1024); } while (0)
; #define PG8_LDB(dst, b, h) do { _Pragma("unroll") for (int n = 0; n < 2; ++n) _Pragma("unroll") for (int k = 0; k < 2; ++k) dst[n][k] = *(const PG8_LAS bf16x8*)(lds + PG8_SB(b, h) + boff + n * 2048 + k * 1024); } while (0)
; #define PG8_WAIT_V(n) asm volatile("s_waitcnt vmcnt(" #n ")" ::: "memory")
; #define PG8_WAIT_L(n) asm volatile("s_waitcnt lgkmcnt(" #n ")" ::: "memory")
; #define PG8_BAR __builtin_amdgcn_s_barrier()
; template <class Epi, class Sched, bool ALIGN_EPI = false, bool SP2 = false, bool PAIR_ACC = false>
; __device__ __forceinline__ void gemm_phase(PG8_LAS unsigned char* lds, const Gemm g, const Sched& S, const Epi& E) {
;     ...
;         const bool has_next = S.next(ui + 1, nxt);
;         const char* nA = has_next ? (const char*)g.A + (size_t)nxt.pm * tstep + (size_t)(nxt.pn / g.a_div) * g.a_sel : cA; const char* nB = has_next ? (const char*)g.Bt + (size_t)nxt.pn * tstep : cB;
;         for (int t = 0; t < nt; t += 2) {
;             const bool last = (t == nt - 2);
;             const char* a1 = cA + (size_t)(t + 1) * kstep;
;             const char* a2 = last ? nA : cA + (size_t)(t + 2) * kstep; const char* b2 = last ? nB : cB + (size_t)(t + 2) * kstep;
;             const char* a3 = a2 + kstep; const char* b3 = b2 + kstep;
;             if (last && has_next) S.a_ready(nxt);
;             if constexpr (SP2) {
;             PG8_LDB(B0, 0, 0); PG8_LDB(B1, 0, 1); PG8_SCHED; PG8_LDA(At, 0, 0); PG8_STAGE(PG8_SA(1, 1), a1 + hstep, voffA);
;             PG8_WAIT_V(8); PG8_WAIT_L(0); PG8_BAR; PG8_MMA(0, 0, At, B0); PG8_MMA(0, 1, At, B1); PG8_BAR; PG8_SCHED;
;             PG8_LDA(At, 0, 1); PG8_STAGE(PG8_SB(0, 0), b2, voffB); PG8_STAGE(PG8_SB(0, 1), b2 + hstep, voffB); PG8_STAGE(PG8_SA(0, 0), a2, voffA);
;             PG8_WAIT_V(8); PG8_WAIT_L(0); PG8_BAR; PG8_MMA(1, 0, At, B0); PG8_MMA(1, 1, At, B1); PG8_BAR; PG8_SCHED;
.LBB0_833:
	s_ashr_i32 s65, s64, 31
	s_lshl_b64 s[40:41], s[64:65], 19
	s_add_u32 s66, s4, s40
	s_addc_u32 s67, s5, s41
	s_and_b64 s[40:41], s[8:9], exec
	s_cselect_b32 s40, s67, s11
	s_cselect_b32 s41, s66, s10
	s_ashr_i32 s63, s62, 31
	s_lshl_b64 s[68:69], s[62:63], 19
	s_add_u32 s68, s23, s68
	s_addc_u32 s69, s24, s69
	s_and_b64 s[72:73], s[8:9], exec
	s_cselect_b32 s63, s69, s39
	s_cselect_b32 s65, s68, s38
	s_add_u32 s10, s10, 0x40080
	s_addc_u32 s11, s11, 0
	s_add_u32 s78, s38, 0x100
	s_addc_u32 s79, s39, 0
	s_mov_b32 s80, -2
	ds_read_b128 v[74:77], v197
	ds_read_b128 v[78:81], v197 offset:1024
	ds_read_b128 v[82:85], v197 offset:2048
	ds_read_b128 v[86:89], v197 offset:3072
	ds_read_b128 v[90:93], v198
	ds_read_b128 v[94:97], v198 offset:1024
	ds_read_b128 v[98:101], v198 offset:2048
	ds_read_b128 v[106:109], v198 offset:3072
	s_add_u32 s38, s10, 0xfffc0080
	s_addc_u32 s39, s11, -1
	s_cmp_eq_u32 s80, 12
	s_cselect_b32 s73, s40, s39
	s_cselect_b32 s72, s41, s38
	s_cselect_b32 s39, s63, s79
	s_cselect_b32 s38, s65, s78
	v_lshl_add_u64 v[170:171], s[10:11], 0, v[186:187]
	s_add_i32 m0, s36, 0xc000
	ds_read_b128 v[162:165], v199
	ds_read_b128 v[166:169], v199 offset:1024
	ds_read_b128 v[210:213], v199 offset:2048
	ds_read_b128 v[214:217], v199 offset:3072
	ds_read_b128 v[218:221], v199 offset:4096
	ds_read_b128 v[222:225], v199 offset:5120
	ds_read_b128 v[226:229], v199 offset:6144
	ds_read_b128 v[230:233], v199 offset:7168
	global_load_lds_dwordx4 v[170:171], off
	v_lshl_add_u64 v[170:171], s[10:11], 0, v[188:189]
	s_add_i32 m0, s36, 0xe000
	s_nop 0
	global_load_lds_dwordx4 v[170:171], off
	s_waitcnt vmcnt(8)
	s_waitcnt lgkmcnt(0)
	s_barrier
	v_mfma_f32_16x16x32_bf16 v[150:153], v[74:77], v[162:165], 0
	v_mfma_f32_16x16x32_bf16 v[146:149], v[82:85], v[162:165], 0
	v_mfma_f32_16x16x32_bf16 v[134:137], v[74:77], v[210:213], 0
	v_mfma_f32_16x16x32_bf16 v[130:133], v[82:85], v[210:213], 0
	v_mfma_f32_16x16x32_bf16 v[118:121], v[74:77], v[218:221], 0
	v_mfma_f32_16x16x32_bf16 v[110:113], v[82:85], v[218:221], 0
	v_mfma_f32_16x16x32_bf16 v[114:117], v[74:77], v[226:229], 0
	v_mfma_f32_16x16x32_bf16 v[102:105], v[82:85], v[226:229], 0
	v_mfma_f32_16x16x32_bf16 v[150:153], v[78:81], v[166:169], v[150:153]
	v_mfma_f32_16x16x32_bf16 v[146:149], v[86:89], v[166:169], v[146:149]
	v_mfma_f32_16x16x32_bf16 v[134:137], v[78:81], v[214:217], v[134:137]
	v_mfma_f32_16x16x32_bf16 v[130:133], v[86:89], v[214:217], v[130:133]
	v_mfma_f32_16x16x32_bf16 v[118:121], v[78:81], v[222:225], v[118:121]
	v_mfma_f32_16x16x32_bf16 v[110:113], v[86:89], v[222:225], v[110:113]
	v_mfma_f32_16x16x32_bf16 v[114:117], v[78:81], v[230:233], v[114:117]
	v_mfma_f32_16x16x32_bf16 v[102:105], v[86:89], v[230:233], v[102:105]
	v_mfma_f32_16x16x32_bf16 v[158:161], v[90:93], v[162:165], 0
	v_mfma_f32_16x16x32_bf16 v[154:157], v[98:101], v[162:165], 0
	v_mfma_f32_16x16x32_bf16 v[142:145], v[90:93], v[210:213], 0
	v_mfma_f32_16x16x32_bf16 v[138:141], v[98:101], v[210:213], 0
	v_mfma_f32_16x16x32_bf16 v[126:129], v[90:93], v[218:221], 0
	v_mfma_f32_16x16x32_bf16 v[122:125], v[98:101], v[218:221], 0
	v_mfma_f32_16x16x32_bf16 v[70:73], v[90:93], v[226:229], 0
	v_mfma_f32_16x16x32_bf16 v[66:69], v[98:101], v[226:229], 0
	v_mfma_f32_16x16x32_bf16 v[158:161], v[94:97], v[166:169], v[158:161]
	v_mfma_f32_16x16x32_bf16 v[154:157], v[106:109], v[166:169], v[154:157]
	v_mfma_f32_16x16x32_bf16 v[142:145], v[94:97], v[214:217], v[142:145]
	v_mfma_f32_16x16x32_bf16 v[138:141], v[106:109], v[214:217], v[138:141]
	v_mfma_f32_16x16x32_bf16 v[126:129], v[94:97], v[222:225], v[126:129]
	v_mfma_f32_16x16x32_bf16 v[122:125], v[106:109], v[222:225], v[122:125]
	v_mfma_f32_16x16x32_bf16 v[70:73], v[94:97], v[230:233], v[70:73]
	v_mfma_f32_16x16x32_bf16 v[66:69], v[106:109], v[230:233], v[66:69]
	s_barrier
	s_add_i32 s81, s61, s25
	v_lshl_add_u64 v[170:171], s[38:39], 0, v[178:179]
	s_mov_b32 m0, s81
	ds_read_b128 v[162:165], v199 offset:16384
	ds_read_b128 v[166:169], v199 offset:17408
	ds_read_b128 v[210:213], v199 offset:18432
	ds_read_b128 v[214:217], v199 offset:19456
	ds_read_b128 v[218:221], v199 offset:20480
	ds_read_b128 v[222:225], v199 offset:21504
	ds_read_b128 v[226:229], v199 offset:22528
	ds_read_b128 v[230:233], v199 offset:23552
	global_load_lds_dwordx4 v[170:171], off
	s_add_i32 m0, s81, 0x2000
	s_add_u32 s82, s38, 0x40000
	v_lshl_add_u64 v[194:195], s[38:39], 0, v[174:175]
	s_addc_u32 s83, s39, 0
	s_add_i32 s81, s74, s25
	global_load_lds_dwordx4 v[194:195], off
	v_lshl_add_u64 v[234:235], s[82:83], 0, v[178:179]
	s_mov_b32 m0, s81
	v_lshl_add_u64 v[236:237], s[72:73], 0, v[176:177]
	global_load_lds_dwordx4 v[234:235], off
	v_lshl_add_u64 v[234:235], s[82:83], 0, v[174:175]
	s_add_i32 m0, s81, 0x2000
	s_nop 0
	global_load_lds_dwordx4 v[234:235], off
	v_lshl_add_u64 v[234:235], s[72:73], 0, v[180:181]
	s_mov_b32 m0, s36
	s_nop 0
	global_load_lds_dwordx4 v[234:235], off
	s_mov_b32 m0, s37
	s_nop 0
	global_load_lds_dwordx4 v[236:237], off
	s_waitcnt vmcnt(8)
	s_waitcnt lgkmcnt(0)
	s_barrier
; #define PG8_STAGE(bufoff, gbase, voff) do { _Pragma("unroll") for (int _i = 0; _i < 2; ++_i) \
;         __builtin_amdgcn_global_load_lds((const unsigned*)((const char*)(gbase) + (voff)[_i]), (PG8_LAS unsigned*)(lds + (bufoff) + ldsw + _i * 8192), 16, 0, 0); } while (0)
; #define PG8_LDA(dst, b, h) do { _Pragma("unroll") for (int m = 0; m < 4; ++m) _Pragma("unroll") for (int k = 0; k < 2; ++k) dst[m][k] = *(const PG8_LAS bf16x8*)(lds + PG8_SA(b, h) + aoff + m * 2048 + k * 1024); } while (0)
; #define PG8_LDB(dst, b, h) do { _Pragma("unroll") for (int n = 0; n < 2; ++n) _Pragma("unroll") for (int k = 0; k < 2; ++k) dst[n][k] = *(const PG8_LAS bf16x8*)(lds + PG8_SB(b, h) + boff + n * 2048 + k * 1024); } while (0)
; #define PG8_MMA(ai, bj, At, Bt) do { __builtin_amdgcn_s_setprio(1); _Pragma("unroll") for (int m = 0; m < 4; ++m) _Pragma("unroll") for (int n = 0; n < 2; ++n) _Pragma("unroll") for (int k = 0; k < 2; ++k) \
;         acc[ai][bj][m][n] = __builtin_amdgcn_mfma_f32_16x16x32_bf16(Bt[n][k], At[m][k], acc[ai][bj][m][n], 0, 0, 0); __builtin_amdgcn_s_setprio(0); } while (0)
; #define PG8_WAIT_V(n) asm volatile("s_waitcnt vmcnt(" #n ")" ::: "memory")
; #define PG8_WAIT_L(n) asm volatile("s_waitcnt lgkmcnt(" #n ")" ::: "memory")
; #define PG8_BAR __builtin_amdgcn_s_barrier()
; #define PG8_SCHED __builtin_amdgcn_sched_barrier(0)
; template <class Epi, class Sched, bool ALIGN_EPI = false, bool SP2 = false, bool PAIR_ACC = false>
; __device__ __forceinline__ void gemm_phase(PG8_LAS unsigned char* lds, const Gemm g, const Sched& S, const Epi& E) {
;     ...
;             PG8_WAIT_V(8); PG8_WAIT_L(0); PG8_BAR; PG8_MMA(0, 0, At, B0); PG8_MMA(0, 1, At, B1); PG8_BAR; PG8_SCHED;
;             PG8_LDA(At, 0, 1); PG8_STAGE(PG8_SB(0, 0), b2, voffB); PG8_STAGE(PG8_SB(0, 1), b2 + hstep, voffB); PG8_STAGE(PG8_SA(0, 0), a2, voffA);
;             PG8_WAIT_V(8); PG8_WAIT_L(0); PG8_BAR; PG8_MMA(1, 0, At, B0); PG8_MMA(1, 1, At, B1); PG8_BAR; PG8_SCHED;
;             PG8_LDB(B0, 1, 0); PG8_LDB(B1, 1, 1); PG8_SCHED; PG8_LDA(At, 1, 0); PG8_STAGE(PG8_SA(0, 1), a2 + hstep, voffA);
;             PG8_WAIT_V(8); PG8_WAIT_L(0); PG8_BAR; PG8_MMA(0, 0, At, B0); PG8_MMA(0, 1, At, B1); PG8_BAR; PG8_SCHED;
	v_mfma_f32_16x16x32_bf16 v[54:57], v[74:77], v[162:165], 0
	v_mfma_f32_16x16x32_bf16 v[50:53], v[82:85], v[162:165], 0
	v_mfma_f32_16x16x32_bf16 v[38:41], v[74:77], v[210:213], 0
	v_mfma_f32_16x16x32_bf16 v[34:37], v[82:85], v[210:213], 0
	v_mfma_f32_16x16x32_bf16 v[22:25], v[74:77], v[218:221], 0
	v_mfma_f32_16x16x32_bf16 v[14:17], v[82:85], v[218:221], 0
	v_mfma_f32_16x16x32_bf16 v[18:21], v[74:77], v[226:229], 0
	v_mfma_f32_16x16x32_bf16 v[10:13], v[82:85], v[226:229], 0
	v_mfma_f32_16x16x32_bf16 v[54:57], v[78:81], v[166:169], v[54:57]
	v_mfma_f32_16x16x32_bf16 v[50:53], v[86:89], v[166:169], v[50:53]
	v_mfma_f32_16x16x32_bf16 v[38:41], v[78:81], v[214:217], v[38:41]
	v_mfma_f32_16x16x32_bf16 v[34:37], v[86:89], v[214:217], v[34:37]
	v_mfma_f32_16x16x32_bf16 v[22:25], v[78:81], v[222:225], v[22:25]
	v_mfma_f32_16x16x32_bf16 v[14:17], v[86:89], v[222:225], v[14:17]
	v_mfma_f32_16x16x32_bf16 v[18:21], v[78:81], v[230:233], v[18:21]
	v_mfma_f32_16x16x32_bf16 v[10:13], v[86:89], v[230:233], v[10:13]
	v_mfma_f32_16x16x32_bf16 v[62:65], v[90:93], v[162:165], 0
	v_mfma_f32_16x16x32_bf16 v[58:61], v[98:101], v[162:165], 0
	v_mfma_f32_16x16x32_bf16 v[46:49], v[90:93], v[210:213], 0
	v_mfma_f32_16x16x32_bf16 v[42:45], v[98:101], v[210:213], 0
	v_mfma_f32_16x16x32_bf16 v[30:33], v[90:93], v[218:221], 0
	v_mfma_f32_16x16x32_bf16 v[26:29], v[98:101], v[218:221], 0
	v_mfma_f32_16x16x32_bf16 v[6:9], v[90:93], v[226:229], 0
	v_mfma_f32_16x16x32_bf16 v[2:5], v[98:101], v[226:229], 0
	v_mfma_f32_16x16x32_bf16 v[62:65], v[94:97], v[166:169], v[62:65]
	v_mfma_f32_16x16x32_bf16 v[58:61], v[106:109], v[166:169], v[58:61]
	v_mfma_f32_16x16x32_bf16 v[46:49], v[94:97], v[214:217], v[46:49]
	v_mfma_f32_16x16x32_bf16 v[42:45], v[106:109], v[214:217], v[42:45]
	v_mfma_f32_16x16x32_bf16 v[30:33], v[94:97], v[222:225], v[30:33]
	v_mfma_f32_16x16x32_bf16 v[26:29], v[106:109], v[222:225], v[26:29]
	v_mfma_f32_16x16x32_bf16 v[6:9], v[94:97], v[230:233], v[6:9]
	v_mfma_f32_16x16x32_bf16 v[2:5], v[106:109], v[230:233], v[2:5]
	s_barrier
	s_branch .Lpeel_mid_834
.LBB0_834:
	ds_read_b128 v[74:77], v197
	ds_read_b128 v[78:81], v197 offset:1024
	ds_read_b128 v[82:85], v197 offset:2048
	ds_read_b128 v[86:89], v197 offset:3072
	ds_read_b128 v[90:93], v198
	ds_read_b128 v[94:97], v198 offset:1024
	ds_read_b128 v[98:101], v198 offset:2048
	ds_read_b128 v[106:109], v198 offset:3072
	s_add_u32 s38, s10, 0xfffc0080
	s_addc_u32 s39, s11, -1
	s_cmp_eq_u32 s80, 12
	s_cselect_b32 s73, s40, s39
	s_cselect_b32 s72, s41, s38
	s_cselect_b32 s39, s63, s79
	s_cselect_b32 s38, s65, s78
	v_lshl_add_u64 v[170:171], s[10:11], 0, v[186:187]
	s_add_i32 m0, s36, 0xc000
	ds_read_b128 v[162:165], v199
	ds_read_b128 v[166:169], v199 offset:1024
	ds_read_b128 v[210:213], v199 offset:2048
	ds_read_b128 v[214:217], v199 offset:3072
	ds_read_b128 v[218:221], v199 offset:4096
	ds_read_b128 v[222:225], v199 offset:5120
	ds_read_b128 v[226:229], v199 offset:6144
	ds_read_b128 v[230:233], v199 offset:7168
	global_load_lds_dwordx4 v[170:171], off
	v_lshl_add_u64 v[170:171], s[10:11], 0, v[188:189]
	s_add_i32 m0, s36, 0xe000
	s_nop 0
	global_load_lds_dwordx4 v[170:171], off
	s_waitcnt vmcnt(8)
	s_waitcnt lgkmcnt(0)
	s_barrier
	v_mfma_f32_16x16x32_bf16 v[150:153], v[74:77], v[162:165], v[150:153]
	v_mfma_f32_16x16x32_bf16 v[146:149], v[82:85], v[162:165], v[146:149]
	v_mfma_f32_16x16x32_bf16 v[134:137], v[74:77], v[210:213], v[134:137]
	v_mfma_f32_16x16x32_bf16 v[130:133], v[82:85], v[210:213], v[130:133]
	v_mfma_f32_16x16x32_bf16 v[118:121], v[74:77], v[218:221], v[118:121]
	v_mfma_f32_16x16x32_bf16 v[110:113], v[82:85], v[218:221], v[110:113]
	v_mfma_f32_16x16x32_bf16 v[114:117], v[74:77], v[226:229], v[114:117]
	v_mfma_f32_16x16x32_bf16 v[102:105], v[82:85], v[226:229], v[102:105]
	v_mfma_f32_16x16x32_bf16 v[150:153], v[78:81], v[166:169], v[150:153]
	v_mfma_f32_16x16x32_bf16 v[146:149], v[86:89], v[166:169], v[146:149]
	v_mfma_f32_16x16x32_bf16 v[134:137], v[78:81], v[214:217], v[134:137]
	v_mfma_f32_16x16x32_bf16 v[130:133], v[86:89], v[214:217], v[130:133]
	v_mfma_f32_16x16x32_bf16 v[118:121], v[78:81], v[222:225], v[118:121]
	v_mfma_f32_16x16x32_bf16 v[110:113], v[86:89], v[222:225], v[110:113]
	v_mfma_f32_16x16x32_bf16 v[114:117], v[78:81], v[230:233], v[114:117]
	v_mfma_f32_16x16x32_bf16 v[102:105], v[86:89], v[230:233], v[102:105]
	v_mfma_f32_16x16x32_bf16 v[158:161], v[90:93], v[162:165], v[158:161]
	v_mfma_f32_16x16x32_bf16 v[154:157], v[98:101], v[162:165], v[154:157]
	v_mfma_f32_16x16x32_bf16 v[142:145], v[90:93], v[210:213], v[142:145]
	v_mfma_f32_16x16x32_bf16 v[138:141], v[98:101], v[210:213], v[138:141]
	v_mfma_f32_16x16x32_bf16 v[126:129], v[90:93], v[218:221], v[126:129]
	v_mfma_f32_16x16x32_bf16 v[122:125], v[98:101], v[218:221], v[122:125]
	v_mfma_f32_16x16x32_bf16 v[70:73], v[90:93], v[226:229], v[70:73]
	v_mfma_f32_16x16x32_bf16 v[66:69], v[98:101], v[226:229], v[66:69]
	v_mfma_f32_16x16x32_bf16 v[158:161], v[94:97], v[166:169], v[158:161]
	v_mfma_f32_16x16x32_bf16 v[154:157], v[106:109], v[166:169], v[154:157]
	v_mfma_f32_16x16x32_bf16 v[142:145], v[94:97], v[214:217], v[142:145]
	v_mfma_f32_16x16x32_bf16 v[138:141], v[106:109], v[214:217], v[138:141]
	v_mfma_f32_16x16x32_bf16 v[126:129], v[94:97], v[222:225], v[126:129]
	v_mfma_f32_16x16x32_bf16 v[122:125], v[106:109], v[222:225], v[122:125]
	v_mfma_f32_16x16x32_bf16 v[70:73], v[94:97], v[230:233], v[70:73]
	v_mfma_f32_16x16x32_bf16 v[66:69], v[106:109], v[230:233], v[66:69]
	s_barrier
; #define PG8_STAGE(bufoff, gbase, voff) do { _Pragma("unroll") for (int _i = 0; _i < 2; ++_i) \
;         __builtin_amdgcn_global_load_lds((const unsigned*)((const char*)(gbase) + (voff)[_i]), (PG8_LAS unsigned*)(lds + (bufoff) + ldsw + _i * 8192), 16, 0, 0); } while (0)
; #define PG8_LDA(dst, b, h) do { _Pragma("unroll") for (int m = 0; m < 4; ++m) _Pragma("unroll") for (int k = 0; k < 2; ++k) dst[m][k] = *(const PG8_LAS bf16x8*)(lds + PG8_SA(b, h) + aoff + m * 2048 + k * 1024); } while (0)
; #define PG8_MMA(ai, bj, At, Bt) do { __builtin_amdgcn_s_setprio(1); _Pragma("unroll") for (int m = 0; m < 4; ++m) _Pragma("unroll") for (int n = 0; n < 2; ++n) _Pragma("unroll") for (int k = 0; k < 2; ++k) \
;         acc[ai][bj][m][n] = __builtin_amdgcn_mfma_f32_16x16x32_bf16(Bt[n][k], At[m][k], acc[ai][bj][m][n], 0, 0, 0); __builtin_amdgcn_s_setprio(0); } while (0)
; #define PG8_WAIT_V(n) asm volatile("s_waitcnt vmcnt(" #n ")" ::: "memory")
; #define PG8_WAIT_L(n) asm volatile("s_waitcnt lgkmcnt(" #n ")" ::: "memory")
; #define PG8_BAR __builtin_amdgcn_s_barrier()
; #define PG8_SCHED __builtin_amdgcn_sched_barrier(0)
; template <class Epi, class Sched, bool ALIGN_EPI = false, bool SP2 = false, bool PAIR_ACC = false>
; __device__ __forceinline__ void gemm_phase(PG8_LAS unsigned char* lds, const Gemm g, const Sched& S, const Epi& E) {
;     ...
;             PG8_LDA(At, 0, 1); PG8_STAGE(PG8_SB(0, 0), b2, voffB); PG8_STAGE(PG8_SB(0, 1), b2 + hstep, voffB); PG8_STAGE(PG8_SA(0, 0), a2, voffA);
;             PG8_WAIT_V(8); PG8_WAIT_L(0); PG8_BAR; PG8_MMA(1, 0, At, B0); PG8_MMA(1, 1, At, B1); PG8_BAR; PG8_SCHED;
	s_add_i32 s81, s61, s25
	v_lshl_add_u64 v[170:171], s[38:39], 0, v[178:179]
	s_mov_b32 m0, s81
	ds_read_b128 v[162:165], v199 offset:16384
	ds_read_b128 v[166:169], v199 offset:17408
	ds_read_b128 v[210:213], v199 offset:18432
	ds_read_b128 v[214:217], v199 offset:19456
	ds_read_b128 v[218:221], v199 offset:20480
	ds_read_b128 v[222:225], v199 offset:21504
	ds_read_b128 v[226:229], v199 offset:22528
	ds_read_b128 v[230:233], v199 offset:23552
	global_load_lds_dwordx4 v[170:171], off
	s_add_i32 m0, s81, 0x2000
	s_add_u32 s82, s38, 0x40000
	v_lshl_add_u64 v[194:195], s[38:39], 0, v[174:175]
	s_addc_u32 s83, s39, 0
	s_add_i32 s81, s74, s25
	global_load_lds_dwordx4 v[194:195], off
	v_lshl_add_u64 v[234:235], s[82:83], 0, v[178:179]
	s_mov_b32 m0, s81
	v_lshl_add_u64 v[236:237], s[72:73], 0, v[176:177]
	global_load_lds_dwordx4 v[234:235], off
	v_lshl_add_u64 v[234:235], s[82:83], 0, v[174:175]
	s_add_i32 m0, s81, 0x2000
	s_nop 0
	global_load_lds_dwordx4 v[234:235], off
	v_lshl_add_u64 v[234:235], s[72:73], 0, v[180:181]
	s_mov_b32 m0, s36
	s_nop 0
	global_load_lds_dwordx4 v[234:235], off
	s_mov_b32 m0, s37
	s_nop 0
	global_load_lds_dwordx4 v[236:237], off
	s_waitcnt vmcnt(8)
	s_waitcnt lgkmcnt(0)
	s_barrier
	v_mfma_f32_16x16x32_bf16 v[54:57], v[74:77], v[162:165], v[54:57]
	v_mfma_f32_16x16x32_bf16 v[50:53], v[82:85], v[162:165], v[50:53]
	v_mfma_f32_16x16x32_bf16 v[38:41], v[74:77], v[210:213], v[38:41]
	v_mfma_f32_16x16x32_bf16 v[34:37], v[82:85], v[210:213], v[34:37]
	v_mfma_f32_16x16x32_bf16 v[22:25], v[74:77], v[218:221], v[22:25]
	v_mfma_f32_16x16x32_bf16 v[14:17], v[82:85], v[218:221], v[14:17]
	v_mfma_f32_16x16x32_bf16 v[18:21], v[74:77], v[226:229], v[18:21]
	v_mfma_f32_16x16x32_bf16 v[10:13], v[82:85], v[226:229], v[10:13]
	v_mfma_f32_16x16x32_bf16 v[54:57], v[78:81], v[166:169], v[54:57]
	v_mfma_f32_16x16x32_bf16 v[50:53], v[86:89], v[166:169], v[50:53]
	v_mfma_f32_16x16x32_bf16 v[38:41], v[78:81], v[214:217], v[38:41]
	v_mfma_f32_16x16x32_bf16 v[34:37], v[86:89], v[214:217], v[34:37]
	v_mfma_f32_16x16x32_bf16 v[22:25], v[78:81], v[222:225], v[22:25]
	v_mfma_f32_16x16x32_bf16 v[14:17], v[86:89], v[222:225], v[14:17]
	v_mfma_f32_16x16x32_bf16 v[18:21], v[78:81], v[230:233], v[18:21]
	v_mfma_f32_16x16x32_bf16 v[10:13], v[86:89], v[230:233], v[10:13]
	v_mfma_f32_16x16x32_bf16 v[62:65], v[90:93], v[162:165], v[62:65]
	v_mfma_f32_16x16x32_bf16 v[58:61], v[98:101], v[162:165], v[58:61]
	v_mfma_f32_16x16x32_bf16 v[46:49], v[90:93], v[210:213], v[46:49]
	v_mfma_f32_16x16x32_bf16 v[42:45], v[98:101], v[210:213], v[42:45]
	v_mfma_f32_16x16x32_bf16 v[30:33], v[90:93], v[218:221], v[30:33]
	v_mfma_f32_16x16x32_bf16 v[26:29], v[98:101], v[218:221], v[26:29]
	v_mfma_f32_16x16x32_bf16 v[6:9], v[90:93], v[226:229], v[6:9]
	v_mfma_f32_16x16x32_bf16 v[2:5], v[98:101], v[226:229], v[2:5]
	v_mfma_f32_16x16x32_bf16 v[62:65], v[94:97], v[166:169], v[62:65]
	v_mfma_f32_16x16x32_bf16 v[58:61], v[106:109], v[166:169], v[58:61]
	v_mfma_f32_16x16x32_bf16 v[46:49], v[94:97], v[214:217], v[46:49]
	v_mfma_f32_16x16x32_bf16 v[42:45], v[106:109], v[214:217], v[42:45]
	v_mfma_f32_16x16x32_bf16 v[30:33], v[94:97], v[222:225], v[30:33]
	v_mfma_f32_16x16x32_bf16 v[26:29], v[106:109], v[222:225], v[26:29]
	v_mfma_f32_16x16x32_bf16 v[6:9], v[94:97], v[230:233], v[6:9]
	v_mfma_f32_16x16x32_bf16 v[2:5], v[106:109], v[230:233], v[2:5]
	s_barrier
; #define PG8_STAGE(bufoff, gbase, voff) do { _Pragma("unroll") for (int _i = 0; _i < 2; ++_i) \
;         __builtin_amdgcn_global_load_lds((const unsigned*)((const char*)(gbase) + (voff)[_i]), (PG8_LAS unsigned*)(lds + (bufoff) + ldsw + _i * 8192), 16, 0, 0); } while (0)
; #define PG8_LDA(dst, b, h) do { _Pragma("unroll") for (int m = 0; m < 4; ++m) _Pragma("unroll") for (int k = 0; k < 2; ++k) dst[m][k] = *(const PG8_LAS bf16x8*)(lds + PG8_SA(b, h) + aoff + m * 2048 + k * 1024); } while (0)
; #define PG8_LDB(dst, b, h) do { _Pragma("unroll") for (int n = 0; n < 2; ++n) _Pragma("unroll") for (int k = 0; k < 2; ++k) dst[n][k] = *(const PG8_LAS bf16x8*)(lds + PG8_SB(b, h) + boff + n * 2048 + k * 1024); } while (0)
; #define PG8_MMA(ai, bj, At, Bt) do { __builtin_amdgcn_s_setprio(1); _Pragma("unroll") for (int m = 0; m < 4; ++m) _Pragma("unroll") for (int n = 0; n < 2; ++n) _Pragma("unroll") for (int k = 0; k < 2; ++k) \
;         acc[ai][bj][m][n] = __builtin_amdgcn_mfma_f32_16x16x32_bf16(Bt[n][k], At[m][k], acc[ai][bj][m][n], 0, 0, 0); __builtin_amdgcn_s_setprio(0); } while (0)
; #define PG8_WAIT_V(n) asm volatile("s_waitcnt vmcnt(" #n ")" ::: "memory")
; #define PG8_WAIT_L(n) asm volatile("s_waitcnt lgkmcnt(" #n ")" ::: "memory")
; #define PG8_BAR __builtin_amdgcn_s_barrier()
; #define PG8_SCHED __builtin_amdgcn_sched_barrier(0)
; template <class Epi, class Sched, bool ALIGN_EPI = false, bool SP2 = false, bool PAIR_ACC = false>
; __device__ __forceinline__ void gemm_phase(PG8_LAS unsigned char* lds, const Gemm g, const Sched& S, const Epi& E) {
;     ...
;             PG8_LDB(B0, 1, 0); PG8_LDB(B1, 1, 1); PG8_SCHED; PG8_LDA(At, 1, 0); PG8_STAGE(PG8_SA(0, 1), a2 + hstep, voffA);
;             PG8_WAIT_V(8); PG8_WAIT_L(0); PG8_BAR; PG8_MMA(0, 0, At, B0); PG8_MMA(0, 1, At, B1); PG8_BAR; PG8_SCHED;
;             PG8_LDA(At, 1, 1); PG8_STAGE(PG8_SB(1, 0), b3, voffB); PG8_STAGE(PG8_SB(1, 1), b3 + hstep, voffB); PG8_STAGE(PG8_SA(1, 0), a3, voffA);
;             PG8_WAIT_V(8); PG8_WAIT_L(0); PG8_BAR; PG8_MMA(1, 0, At, B0); PG8_MMA(1, 1, At, B1); PG8_BAR; PG8_SCHED;
;     ...
;         if constexpr (ALIGN_EPI) { if (wr == 0) PG8_BAR; }
.Lpeel_mid_834:
	s_add_i32 s81, 0, 0x18000
	s_add_i32 s82, 0, 0x1c000
	v_add_u32_e32 v86, s81, v183
	v_add_u32_e32 v106, s82, v183
	ds_read_b128 v[74:77], v86
	ds_read_b128 v[78:81], v86 offset:1024
	ds_read_b128 v[82:85], v86 offset:2048
	ds_read_b128 v[86:89], v86 offset:3072
	ds_read_b128 v[90:93], v106
	ds_read_b128 v[94:97], v106 offset:1024
	ds_read_b128 v[98:101], v106 offset:2048
	ds_read_b128 v[106:109], v106 offset:3072
	s_add_u32 s72, s72, 0x40000
	s_addc_u32 s73, s73, 0
	s_mov_b32 m0, s42
	v_lshl_add_u64 v[238:239], s[72:73], 0, v[180:181]
	ds_read_b128 v[162:165], v199 offset:32768
	ds_read_b128 v[166:169], v199 offset:33792
	ds_read_b128 v[210:213], v199 offset:34816
	ds_read_b128 v[214:217], v199 offset:35840
	ds_read_b128 v[218:221], v199 offset:36864
	ds_read_b128 v[222:225], v199 offset:37888
	ds_read_b128 v[226:229], v199 offset:38912
	ds_read_b128 v[230:233], v199 offset:39936
	global_load_lds_dwordx4 v[238:239], off
	v_lshl_add_u64 v[238:239], s[72:73], 0, v[176:177]
	s_mov_b32 m0, s43
	s_nop 0
	global_load_lds_dwordx4 v[238:239], off
	s_waitcnt vmcnt(8)
	s_waitcnt lgkmcnt(0)
	s_barrier
	v_mfma_f32_16x16x32_bf16 v[150:153], v[74:77], v[162:165], v[150:153]
	v_mfma_f32_16x16x32_bf16 v[146:149], v[82:85], v[162:165], v[146:149]
	v_mfma_f32_16x16x32_bf16 v[134:137], v[74:77], v[210:213], v[134:137]
	v_mfma_f32_16x16x32_bf16 v[130:133], v[82:85], v[210:213], v[130:133]
	v_mfma_f32_16x16x32_bf16 v[118:121], v[74:77], v[218:221], v[118:121]
	v_mfma_f32_16x16x32_bf16 v[110:113], v[82:85], v[218:221], v[110:113]
	v_mfma_f32_16x16x32_bf16 v[114:117], v[74:77], v[226:229], v[114:117]
	v_mfma_f32_16x16x32_bf16 v[102:105], v[82:85], v[226:229], v[102:105]
	v_mfma_f32_16x16x32_bf16 v[150:153], v[78:81], v[166:169], v[150:153]
	v_mfma_f32_16x16x32_bf16 v[146:149], v[86:89], v[166:169], v[146:149]
	v_mfma_f32_16x16x32_bf16 v[134:137], v[78:81], v[214:217], v[134:137]
	v_mfma_f32_16x16x32_bf16 v[130:133], v[86:89], v[214:217], v[130:133]
	v_mfma_f32_16x16x32_bf16 v[118:121], v[78:81], v[222:225], v[118:121]
	v_mfma_f32_16x16x32_bf16 v[110:113], v[86:89], v[222:225], v[110:113]
	v_mfma_f32_16x16x32_bf16 v[114:117], v[78:81], v[230:233], v[114:117]
	v_mfma_f32_16x16x32_bf16 v[102:105], v[86:89], v[230:233], v[102:105]
	v_mfma_f32_16x16x32_bf16 v[158:161], v[90:93], v[162:165], v[158:161]
	v_mfma_f32_16x16x32_bf16 v[154:157], v[98:101], v[162:165], v[154:157]
	v_mfma_f32_16x16x32_bf16 v[142:145], v[90:93], v[210:213], v[142:145]
	v_mfma_f32_16x16x32_bf16 v[138:141], v[98:101], v[210:213], v[138:141]
	v_mfma_f32_16x16x32_bf16 v[126:129], v[90:93], v[218:221], v[126:129]
	v_mfma_f32_16x16x32_bf16 v[122:125], v[98:101], v[218:221], v[122:125]
	v_mfma_f32_16x16x32_bf16 v[70:73], v[90:93], v[226:229], v[70:73]
	v_mfma_f32_16x16x32_bf16 v[66:69], v[98:101], v[226:229], v[66:69]
	v_mfma_f32_16x16x32_bf16 v[158:161], v[94:97], v[166:169], v[158:161]
	v_mfma_f32_16x16x32_bf16 v[154:157], v[106:109], v[166:169], v[154:157]
	v_mfma_f32_16x16x32_bf16 v[142:145], v[94:97], v[214:217], v[142:145]
	v_mfma_f32_16x16x32_bf16 v[138:141], v[106:109], v[214:217], v[138:141]
	v_mfma_f32_16x16x32_bf16 v[126:129], v[94:97], v[222:225], v[126:129]
	v_mfma_f32_16x16x32_bf16 v[122:125], v[106:109], v[222:225], v[122:125]
	v_mfma_f32_16x16x32_bf16 v[70:73], v[94:97], v[230:233], v[70:73]
	v_mfma_f32_16x16x32_bf16 v[66:69], v[106:109], v[230:233], v[66:69]
	s_barrier
	s_add_i32 s72, s81, s25
	v_lshl_add_u64 v[170:171], v[170:171], 0, s[48:49]
	s_mov_b32 m0, s72
	ds_read_b128 v[162:165], v199 offset:49152
	ds_read_b128 v[166:169], v199 offset:50176
	ds_read_b128 v[210:213], v199 offset:51200
	ds_read_b128 v[214:217], v199 offset:52224
	ds_read_b128 v[218:221], v199 offset:53248
	ds_read_b128 v[222:225], v199 offset:54272
	ds_read_b128 v[226:229], v199 offset:55296
	ds_read_b128 v[230:233], v199 offset:56320
	global_load_lds_dwordx4 v[170:171], off
	s_add_i32 m0, s72, 0x2000
	s_add_u32 s38, s38, 0x40080
	v_lshl_add_u64 v[170:171], v[194:195], 0, s[48:49]
	s_addc_u32 s39, s39, 0
	s_add_i32 s72, s82, s25
	global_load_lds_dwordx4 v[170:171], off
	v_lshl_add_u64 v[170:171], s[38:39], 0, v[178:179]
	s_mov_b32 m0, s72
	s_nop 0
	global_load_lds_dwordx4 v[170:171], off
	v_lshl_add_u64 v[170:171], s[38:39], 0, v[174:175]
	s_add_i32 m0, s72, 0x2000
	s_nop 0
	global_load_lds_dwordx4 v[170:171], off
	v_lshl_add_u64 v[170:171], v[234:235], 0, s[48:49]
	s_mov_b32 m0, s45
	s_nop 0
	global_load_lds_dwordx4 v[170:171], off
	v_lshl_add_u64 v[170:171], v[236:237], 0, s[48:49]
	s_mov_b32 m0, s46
	s_nop 0
	global_load_lds_dwordx4 v[170:171], off
	s_waitcnt vmcnt(8)
	s_waitcnt lgkmcnt(0)
	s_barrier
	v_mfma_f32_16x16x32_bf16 v[54:57], v[74:77], v[162:165], v[54:57]
	v_mfma_f32_16x16x32_bf16 v[50:53], v[82:85], v[162:165], v[50:53]
	v_mfma_f32_16x16x32_bf16 v[38:41], v[74:77], v[210:213], v[38:41]
	v_mfma_f32_16x16x32_bf16 v[34:37], v[82:85], v[210:213], v[34:37]
	v_mfma_f32_16x16x32_bf16 v[22:25], v[74:77], v[218:221], v[22:25]
	v_mfma_f32_16x16x32_bf16 v[14:17], v[82:85], v[218:221], v[14:17]
	v_mfma_f32_16x16x32_bf16 v[18:21], v[74:77], v[226:229], v[18:21]
	v_mfma_f32_16x16x32_bf16 v[10:13], v[82:85], v[226:229], v[10:13]
	v_mfma_f32_16x16x32_bf16 v[54:57], v[78:81], v[166:169], v[54:57]
	v_mfma_f32_16x16x32_bf16 v[50:53], v[86:89], v[166:169], v[50:53]
	v_mfma_f32_16x16x32_bf16 v[38:41], v[78:81], v[214:217], v[38:41]
	v_mfma_f32_16x16x32_bf16 v[34:37], v[86:89], v[214:217], v[34:37]
	v_mfma_f32_16x16x32_bf16 v[22:25], v[78:81], v[222:225], v[22:25]
	v_mfma_f32_16x16x32_bf16 v[14:17], v[86:89], v[222:225], v[14:17]
	v_mfma_f32_16x16x32_bf16 v[18:21], v[78:81], v[230:233], v[18:21]
	v_mfma_f32_16x16x32_bf16 v[10:13], v[86:89], v[230:233], v[10:13]
	v_mfma_f32_16x16x32_bf16 v[62:65], v[90:93], v[162:165], v[62:65]
	v_mfma_f32_16x16x32_bf16 v[58:61], v[98:101], v[162:165], v[58:61]
	v_mfma_f32_16x16x32_bf16 v[46:49], v[90:93], v[210:213], v[46:49]
	v_mfma_f32_16x16x32_bf16 v[42:45], v[98:101], v[210:213], v[42:45]
	v_mfma_f32_16x16x32_bf16 v[30:33], v[90:93], v[218:221], v[30:33]
	v_mfma_f32_16x16x32_bf16 v[26:29], v[98:101], v[218:221], v[26:29]
	v_mfma_f32_16x16x32_bf16 v[6:9], v[90:93], v[226:229], v[6:9]
	v_mfma_f32_16x16x32_bf16 v[2:5], v[98:101], v[226:229], v[2:5]
	v_mfma_f32_16x16x32_bf16 v[62:65], v[94:97], v[166:169], v[62:65]
	v_mfma_f32_16x16x32_bf16 v[58:61], v[106:109], v[166:169], v[58:61]
	v_mfma_f32_16x16x32_bf16 v[46:49], v[94:97], v[214:217], v[46:49]
	v_mfma_f32_16x16x32_bf16 v[42:45], v[106:109], v[214:217], v[42:45]
	v_mfma_f32_16x16x32_bf16 v[30:33], v[94:97], v[222:225], v[30:33]
	v_mfma_f32_16x16x32_bf16 v[26:29], v[106:109], v[222:225], v[26:29]
	v_mfma_f32_16x16x32_bf16 v[6:9], v[94:97], v[230:233], v[6:9]
	v_mfma_f32_16x16x32_bf16 v[2:5], v[106:109], v[230:233], v[2:5]
	s_barrier
	s_add_i32 s80, s80, 2
	s_add_u32 s10, s10, 0x100
	s_addc_u32 s11, s11, 0
	s_add_u32 s78, s78, 0x100
	s_addc_u32 s79, s79, 0
	s_cmp_gt_u32 s80, 13
	s_cbranch_scc0 .LBB0_834
	s_and_b64 vcc, exec, s[50:51]
	s_cbranch_vccz .LBB0_837
	s_barrier

; #define PG8_STAGE(bufoff, gbase, voff) do { _Pragma("unroll") for (int _i = 0; _i < 2; ++_i) \
;         __builtin_amdgcn_global_load_lds((const unsigned*)((const char*)(gbase) + (voff)[_i]), (PG8_LAS unsigned*)(lds + (bufoff) + ldsw + _i * 8192), 16, 0, 0); } while (0)
; #define PG8_LDA(dst, b, h) do { _Pragma("unroll") for (int m = 0; m < 4; ++m) _Pragma("unroll") for (int k = 0; k < 2; ++k) dst[m][k] = *(const PG8_LAS bf16x8*)(lds + PG8_SA(b, h) + aoff + m * 2048 + k * 1024); } while (0)
; #define PG8_LDB(dst, b, h) do { _Pragma("unroll") for (int n = 0; n < 2; ++n) _Pragma("unroll") for (int k = 0; k < 2; ++k) dst[n][k] = *(const PG8_LAS bf16x8*)(lds + PG8_SB(b, h) + boff + n * 2048 + k * 1024); } while (0)
; #define PG8_MMA(ai, bj, At, Bt) do { __builtin_amdgcn_s_setprio(1); _Pragma("unroll") for (int m = 0; m < 4; ++m) _Pragma("unroll") for (int n = 0; n < 2; ++n) _Pragma("unroll") for (int k = 0; k < 2; ++k) \
;         acc[ai][bj][m][n] = __builtin_amdgcn_mfma_f32_16x16x32_bf16(Bt[n][k], At[m][k], acc[ai][bj][m][n], 0, 0, 0); __builtin_amdgcn_s_setprio(0); } while (0)
; #define PG8_WAIT_V(n) asm volatile("s_waitcnt vmcnt(" #n ")" ::: "memory")
; #define PG8_WAIT_L(n) asm volatile("s_waitcnt lgkmcnt(" #n ")" ::: "memory")
; template <class Epi, class Sched, bool ALIGN_EPI = false, bool SP2 = false, bool PAIR_ACC = false>
; __device__ __forceinline__ void gemm_phase(PG8_LAS unsigned char* lds, const Gemm g, const Sched& S, const Epi& E) {
;     ...
;             const bool last = (t == nt - 2);
;             const char* a1 = cA + (size_t)(t + 1) * kstep;
;             const char* a2 = last ? nA : cA + (size_t)(t + 2) * kstep; const char* b2 = last ? nB : cB + (size_t)(t + 2) * kstep;
;             const char* a3 = a2 + kstep; const char* b3 = b2 + kstep;
;             if (last && has_next) S.a_ready(nxt);
;             if constexpr (SP2) {
;             PG8_LDB(B0, 0, 0); PG8_LDB(B1, 0, 1); PG8_SCHED; PG8_LDA(At, 0, 0); PG8_STAGE(PG8_SA(1, 1), a1 + hstep, voffA);
;             PG8_WAIT_V(8); PG8_WAIT_L(0); PG8_BAR; PG8_MMA(0, 0, At, B0); PG8_MMA(0, 1, At, B1); PG8_BAR; PG8_SCHED;
;             PG8_LDA(At, 0, 1); PG8_STAGE(PG8_SB(0, 0), b2, voffB); PG8_STAGE(PG8_SB(0, 1), b2 + hstep, voffB); PG8_STAGE(PG8_SA(0, 0), a2, voffA);
;             PG8_WAIT_V(8); PG8_WAIT_L(0); PG8_BAR; PG8_MMA(1, 0, At, B0); PG8_MMA(1, 1, At, B1); PG8_BAR; PG8_SCHED;
.LBB0_937:
	v_add_u32_e32 v164, s46, v150
	ds_read_b128 v[152:155], v164
	ds_read_b128 v[156:159], v164 offset:1024
	ds_read_b128 v[160:163], v164 offset:2048
	ds_read_b128 v[174:177], v164 offset:3072
	v_add_u32_e32 v164, s47, v150
	s_add_u32 s38, s28, s50
	ds_read_b128 v[178:181], v164
	ds_read_b128 v[182:185], v164 offset:1024
	ds_read_b128 v[186:189], v164 offset:2048
	ds_read_b128 v[190:193], v164 offset:3072
	s_addc_u32 s39, s29, s51
	s_add_u32 s38, s38, 0x100
	s_addc_u32 s39, s39, 0
	s_add_u32 s60, s57, s50
	s_addc_u32 s61, s58, s51
	s_cmpk_eq_i32 s50, 0x1500
	s_cselect_b32 s53, s49, s39
	s_cselect_b32 s52, s48, s38
	s_cselect_b32 s39, s11, s61
	s_cselect_b32 s38, s10, s60
	v_lshl_add_u64 v[164:165], v[146:147], 0, s[50:51]
	s_add_i32 m0, s37, 0xc000
	ds_read_b128 v[194:197], v151
	ds_read_b128 v[206:209], v151 offset:1024
	ds_read_b128 v[210:213], v151 offset:2048
	ds_read_b128 v[214:217], v151 offset:3072
	ds_read_b128 v[218:221], v151 offset:4096
	ds_read_b128 v[222:225], v151 offset:5120
	ds_read_b128 v[226:229], v151 offset:6144
	ds_read_b128 v[230:233], v151 offset:7168
	global_load_lds_dwordx4 v[164:165], off
	v_lshl_add_u64 v[164:165], v[148:149], 0, s[50:51]
	s_add_i32 m0, s37, 0xe000
	s_nop 0
	global_load_lds_dwordx4 v[164:165], off
	s_waitcnt vmcnt(8)
	s_waitcnt lgkmcnt(0)
	s_barrier
	v_mfma_f32_16x16x32_bf16 v[58:61], v[152:155], v[194:197], v[58:61]
	v_mfma_f32_16x16x32_bf16 v[62:65], v[160:163], v[194:197], v[62:65]
	v_mfma_f32_16x16x32_bf16 v[82:85], v[152:155], v[210:213], v[82:85]
	v_mfma_f32_16x16x32_bf16 v[74:77], v[160:163], v[210:213], v[74:77]
	v_mfma_f32_16x16x32_bf16 v[98:101], v[152:155], v[218:221], v[98:101]
	v_mfma_f32_16x16x32_bf16 v[90:93], v[160:163], v[218:221], v[90:93]
	v_mfma_f32_16x16x32_bf16 v[114:117], v[152:155], v[226:229], v[114:117]
	v_mfma_f32_16x16x32_bf16 v[110:113], v[160:163], v[226:229], v[110:113]
	v_mfma_f32_16x16x32_bf16 v[58:61], v[156:159], v[206:209], v[58:61]
	v_mfma_f32_16x16x32_bf16 v[62:65], v[174:177], v[206:209], v[62:65]
	v_mfma_f32_16x16x32_bf16 v[82:85], v[156:159], v[214:217], v[82:85]
	v_mfma_f32_16x16x32_bf16 v[74:77], v[174:177], v[214:217], v[74:77]
	v_mfma_f32_16x16x32_bf16 v[98:101], v[156:159], v[222:225], v[98:101]
	v_mfma_f32_16x16x32_bf16 v[90:93], v[174:177], v[222:225], v[90:93]
	v_mfma_f32_16x16x32_bf16 v[114:117], v[156:159], v[230:233], v[114:117]
	v_mfma_f32_16x16x32_bf16 v[110:113], v[174:177], v[230:233], v[110:113]
	v_mfma_f32_16x16x32_bf16 v[54:57], v[178:181], v[194:197], v[54:57]
	v_mfma_f32_16x16x32_bf16 v[46:49], v[186:189], v[194:197], v[46:49]
	v_mfma_f32_16x16x32_bf16 v[50:53], v[178:181], v[210:213], v[50:53]
	v_mfma_f32_16x16x32_bf16 v[42:45], v[186:189], v[210:213], v[42:45]
	v_mfma_f32_16x16x32_bf16 v[78:81], v[178:181], v[218:221], v[78:81]
	v_mfma_f32_16x16x32_bf16 v[70:73], v[186:189], v[218:221], v[70:73]
	v_mfma_f32_16x16x32_bf16 v[102:105], v[178:181], v[226:229], v[102:105]
	v_mfma_f32_16x16x32_bf16 v[94:97], v[186:189], v[226:229], v[94:97]
	v_mfma_f32_16x16x32_bf16 v[54:57], v[182:185], v[206:209], v[54:57]
	v_mfma_f32_16x16x32_bf16 v[46:49], v[190:193], v[206:209], v[46:49]
	v_mfma_f32_16x16x32_bf16 v[50:53], v[182:185], v[214:217], v[50:53]
	v_mfma_f32_16x16x32_bf16 v[42:45], v[190:193], v[214:217], v[42:45]
	v_mfma_f32_16x16x32_bf16 v[78:81], v[182:185], v[222:225], v[78:81]
	v_mfma_f32_16x16x32_bf16 v[70:73], v[190:193], v[222:225], v[70:73]
	v_mfma_f32_16x16x32_bf16 v[102:105], v[182:185], v[230:233], v[102:105]
	v_mfma_f32_16x16x32_bf16 v[94:97], v[190:193], v[230:233], v[94:97]
	s_barrier
	s_add_i32 s60, s46, s36
	v_lshl_add_u64 v[164:165], s[38:39], 0, v[132:133]
	s_mov_b32 m0, s60
	ds_read_b128 v[194:197], v151 offset:16384
	ds_read_b128 v[206:209], v151 offset:17408
	ds_read_b128 v[210:213], v151 offset:18432
	ds_read_b128 v[214:217], v151 offset:19456
	ds_read_b128 v[218:221], v151 offset:20480
	ds_read_b128 v[222:225], v151 offset:21504
	ds_read_b128 v[226:229], v151 offset:22528
	ds_read_b128 v[230:233], v151 offset:23552
	global_load_lds_dwordx4 v[164:165], off
	s_add_i32 m0, s60, 0x2000
	s_add_u32 s60, s38, 0xb0000
	v_lshl_add_u64 v[170:171], s[38:39], 0, v[136:137]
	s_addc_u32 s61, s39, 0
	s_add_i32 s62, s47, s36
	global_load_lds_dwordx4 v[170:171], off
	v_lshl_add_u64 v[198:199], s[60:61], 0, v[132:133]
	s_mov_b32 m0, s62
	v_lshl_add_u64 v[234:235], s[52:53], 0, v[134:135]
	global_load_lds_dwordx4 v[198:199], off
	v_lshl_add_u64 v[198:199], s[60:61], 0, v[136:137]
	s_add_i32 m0, s62, 0x2000
	s_nop 0
	global_load_lds_dwordx4 v[198:199], off
	v_lshl_add_u64 v[198:199], s[52:53], 0, v[130:131]
	s_mov_b32 m0, s37
	s_nop 0
	global_load_lds_dwordx4 v[198:199], off
	s_mov_b32 m0, s40
	s_nop 0
	global_load_lds_dwordx4 v[234:235], off
	s_waitcnt vmcnt(8)
	s_waitcnt lgkmcnt(0)
	s_barrier
; #define PG8_STAGE(bufoff, gbase, voff) do { _Pragma("unroll") for (int _i = 0; _i < 2; ++_i) \
;         __builtin_amdgcn_global_load_lds((const unsigned*)((const char*)(gbase) + (voff)[_i]), (PG8_LAS unsigned*)(lds + (bufoff) + ldsw + _i * 8192), 16, 0, 0); } while (0)
; #define PG8_LDA(dst, b, h) do { _Pragma("unroll") for (int m = 0; m < 4; ++m) _Pragma("unroll") for (int k = 0; k < 2; ++k) dst[m][k] = *(const PG8_LAS bf16x8*)(lds + PG8_SA(b, h) + aoff + m * 2048 + k * 1024); } while (0)
; #define PG8_LDB(dst, b, h) do { _Pragma("unroll") for (int n = 0; n < 2; ++n) _Pragma("unroll") for (int k = 0; k < 2; ++k) dst[n][k] = *(const PG8_LAS bf16x8*)(lds + PG8_SB(b, h) + boff + n * 2048 + k * 1024); } while (0)
; #define PG8_MMA(ai, bj, At, Bt) do { __builtin_amdgcn_s_setprio(1); _Pragma("unroll") for (int m = 0; m < 4; ++m) _Pragma("unroll") for (int n = 0; n < 2; ++n) _Pragma("unroll") for (int k = 0; k < 2; ++k) \
;         acc[ai][bj][m][n] = __builtin_amdgcn_mfma_f32_16x16x32_bf16(Bt[n][k], At[m][k], acc[ai][bj][m][n], 0, 0, 0); __builtin_amdgcn_s_setprio(0); } while (0)
; #define PG8_WAIT_V(n) asm volatile("s_waitcnt vmcnt(" #n ")" ::: "memory")
; #define PG8_WAIT_L(n) asm volatile("s_waitcnt lgkmcnt(" #n ")" ::: "memory")
; #define PG8_BAR __builtin_amdgcn_s_barrier()
; #define PG8_SCHED __builtin_amdgcn_sched_barrier(0)
; template <class Epi, class Sched, bool ALIGN_EPI = false, bool SP2 = false, bool PAIR_ACC = false>
; __device__ __forceinline__ void gemm_phase(PG8_LAS unsigned char* lds, const Gemm g, const Sched& S, const Epi& E) {
;     ...
;             PG8_WAIT_V(8); PG8_WAIT_L(0); PG8_BAR; PG8_MMA(1, 0, At, B0); PG8_MMA(1, 1, At, B1); PG8_BAR; PG8_SCHED;
;             PG8_LDB(B0, 1, 0); PG8_LDB(B1, 1, 1); PG8_SCHED; PG8_LDA(At, 1, 0); PG8_STAGE(PG8_SA(0, 1), a2 + hstep, voffA);
;             PG8_WAIT_V(8); PG8_WAIT_L(0); PG8_BAR; PG8_MMA(0, 0, At, B0); PG8_MMA(0, 1, At, B1); PG8_BAR; PG8_SCHED;
	v_mfma_f32_16x16x32_bf16 v[126:129], v[152:155], v[194:197], v[126:129]
	v_mfma_f32_16x16x32_bf16 v[122:125], v[160:163], v[194:197], v[122:125]
	v_mfma_f32_16x16x32_bf16 v[86:89], v[152:155], v[210:213], v[86:89]
	v_mfma_f32_16x16x32_bf16 v[66:69], v[160:163], v[210:213], v[66:69]
	v_mfma_f32_16x16x32_bf16 v[30:33], v[152:155], v[218:221], v[30:33]
	v_mfma_f32_16x16x32_bf16 v[26:29], v[160:163], v[218:221], v[26:29]
	v_mfma_f32_16x16x32_bf16 v[14:17], v[152:155], v[226:229], v[14:17]
	v_mfma_f32_16x16x32_bf16 v[10:13], v[160:163], v[226:229], v[10:13]
	v_mfma_f32_16x16x32_bf16 v[126:129], v[156:159], v[206:209], v[126:129]
	v_mfma_f32_16x16x32_bf16 v[122:125], v[174:177], v[206:209], v[122:125]
	v_mfma_f32_16x16x32_bf16 v[86:89], v[156:159], v[214:217], v[86:89]
	v_mfma_f32_16x16x32_bf16 v[66:69], v[174:177], v[214:217], v[66:69]
	v_mfma_f32_16x16x32_bf16 v[30:33], v[156:159], v[222:225], v[30:33]
	v_mfma_f32_16x16x32_bf16 v[26:29], v[174:177], v[222:225], v[26:29]
	v_mfma_f32_16x16x32_bf16 v[14:17], v[156:159], v[230:233], v[14:17]
	v_mfma_f32_16x16x32_bf16 v[10:13], v[174:177], v[230:233], v[10:13]
	v_mfma_f32_16x16x32_bf16 v[118:121], v[178:181], v[194:197], v[118:121]
	v_mfma_f32_16x16x32_bf16 v[106:109], v[186:189], v[194:197], v[106:109]
	v_mfma_f32_16x16x32_bf16 v[38:41], v[178:181], v[210:213], v[38:41]
	v_mfma_f32_16x16x32_bf16 v[34:37], v[186:189], v[210:213], v[34:37]
	v_mfma_f32_16x16x32_bf16 v[22:25], v[178:181], v[218:221], v[22:25]
	v_mfma_f32_16x16x32_bf16 v[18:21], v[186:189], v[218:221], v[18:21]
	v_mfma_f32_16x16x32_bf16 v[6:9], v[178:181], v[226:229], v[6:9]
	v_mfma_f32_16x16x32_bf16 v[2:5], v[186:189], v[226:229], v[2:5]
	v_mfma_f32_16x16x32_bf16 v[118:121], v[182:185], v[206:209], v[118:121]
	v_mfma_f32_16x16x32_bf16 v[106:109], v[190:193], v[206:209], v[106:109]
	v_mfma_f32_16x16x32_bf16 v[38:41], v[182:185], v[214:217], v[38:41]
	v_mfma_f32_16x16x32_bf16 v[34:37], v[190:193], v[214:217], v[34:37]
	v_mfma_f32_16x16x32_bf16 v[22:25], v[182:185], v[222:225], v[22:25]
	v_mfma_f32_16x16x32_bf16 v[18:21], v[190:193], v[222:225], v[18:21]
	v_mfma_f32_16x16x32_bf16 v[6:9], v[182:185], v[230:233], v[6:9]
	v_mfma_f32_16x16x32_bf16 v[2:5], v[190:193], v[230:233], v[2:5]
	s_barrier
	s_add_i32 s60, 0, 0x18000
	v_add_u32_e32 v169, s60, v150
	s_add_i32 s61, 0, 0x1c000
	ds_read_b128 v[152:155], v169
	ds_read_b128 v[156:159], v169 offset:1024
	ds_read_b128 v[160:163], v169 offset:2048
	ds_read_b128 v[174:177], v169 offset:3072
	v_add_u32_e32 v169, s61, v150
	ds_read_b128 v[178:181], v169
	ds_read_b128 v[182:185], v169 offset:1024
	ds_read_b128 v[186:189], v169 offset:2048
	ds_read_b128 v[190:193], v169 offset:3072
	s_add_u32 s52, s52, 0xb0000
	s_addc_u32 s53, s53, 0
	s_mov_b32 m0, s41
	v_lshl_add_u64 v[236:237], s[52:53], 0, v[130:131]
	ds_read_b128 v[194:197], v151 offset:32768
	ds_read_b128 v[206:209], v151 offset:33792
	ds_read_b128 v[210:213], v151 offset:34816
	ds_read_b128 v[214:217], v151 offset:35840
	ds_read_b128 v[218:221], v151 offset:36864
	ds_read_b128 v[222:225], v151 offset:37888
	ds_read_b128 v[226:229], v151 offset:38912
	ds_read_b128 v[230:233], v151 offset:39936
	global_load_lds_dwordx4 v[236:237], off
	v_lshl_add_u64 v[236:237], s[52:53], 0, v[134:135]
	s_mov_b32 m0, s42
	s_nop 0
	global_load_lds_dwordx4 v[236:237], off
	s_waitcnt vmcnt(8)
	s_waitcnt lgkmcnt(0)
	s_barrier
	v_mfma_f32_16x16x32_bf16 v[58:61], v[152:155], v[194:197], v[58:61]
	v_mfma_f32_16x16x32_bf16 v[62:65], v[160:163], v[194:197], v[62:65]
	v_mfma_f32_16x16x32_bf16 v[82:85], v[152:155], v[210:213], v[82:85]
	v_mfma_f32_16x16x32_bf16 v[74:77], v[160:163], v[210:213], v[74:77]
	v_mfma_f32_16x16x32_bf16 v[98:101], v[152:155], v[218:221], v[98:101]
	v_mfma_f32_16x16x32_bf16 v[90:93], v[160:163], v[218:221], v[90:93]
	v_mfma_f32_16x16x32_bf16 v[114:117], v[152:155], v[226:229], v[114:117]
	v_mfma_f32_16x16x32_bf16 v[110:113], v[160:163], v[226:229], v[110:113]
	v_mfma_f32_16x16x32_bf16 v[58:61], v[156:159], v[206:209], v[58:61]
	v_mfma_f32_16x16x32_bf16 v[62:65], v[174:177], v[206:209], v[62:65]
	v_mfma_f32_16x16x32_bf16 v[82:85], v[156:159], v[214:217], v[82:85]
	v_mfma_f32_16x16x32_bf16 v[74:77], v[174:177], v[214:217], v[74:77]
	v_mfma_f32_16x16x32_bf16 v[98:101], v[156:159], v[222:225], v[98:101]
	v_mfma_f32_16x16x32_bf16 v[90:93], v[174:177], v[222:225], v[90:93]
	v_mfma_f32_16x16x32_bf16 v[114:117], v[156:159], v[230:233], v[114:117]
	v_mfma_f32_16x16x32_bf16 v[110:113], v[174:177], v[230:233], v[110:113]
	v_mfma_f32_16x16x32_bf16 v[54:57], v[178:181], v[194:197], v[54:57]
	v_mfma_f32_16x16x32_bf16 v[46:49], v[186:189], v[194:197], v[46:49]
	v_mfma_f32_16x16x32_bf16 v[50:53], v[178:181], v[210:213], v[50:53]
	v_mfma_f32_16x16x32_bf16 v[42:45], v[186:189], v[210:213], v[42:45]
	v_mfma_f32_16x16x32_bf16 v[78:81], v[178:181], v[218:221], v[78:81]
	v_mfma_f32_16x16x32_bf16 v[70:73], v[186:189], v[218:221], v[70:73]
	v_mfma_f32_16x16x32_bf16 v[102:105], v[178:181], v[226:229], v[102:105]
	v_mfma_f32_16x16x32_bf16 v[94:97], v[186:189], v[226:229], v[94:97]
	v_mfma_f32_16x16x32_bf16 v[54:57], v[182:185], v[206:209], v[54:57]
	v_mfma_f32_16x16x32_bf16 v[46:49], v[190:193], v[206:209], v[46:49]
	v_mfma_f32_16x16x32_bf16 v[50:53], v[182:185], v[214:217], v[50:53]
	v_mfma_f32_16x16x32_bf16 v[42:45], v[190:193], v[214:217], v[42:45]
	v_mfma_f32_16x16x32_bf16 v[78:81], v[182:185], v[222:225], v[78:81]
	v_mfma_f32_16x16x32_bf16 v[70:73], v[190:193], v[222:225], v[70:73]
	v_mfma_f32_16x16x32_bf16 v[102:105], v[182:185], v[230:233], v[102:105]
	v_mfma_f32_16x16x32_bf16 v[94:97], v[190:193], v[230:233], v[94:97]
	s_barrier
; #define PG8_STAGE(bufoff, gbase, voff) do { _Pragma("unroll") for (int _i = 0; _i < 2; ++_i) \
;         __builtin_amdgcn_global_load_lds((const unsigned*)((const char*)(gbase) + (voff)[_i]), (PG8_LAS unsigned*)(lds + (bufoff) + ldsw + _i * 8192), 16, 0, 0); } while (0)
; #define PG8_LDA(dst, b, h) do { _Pragma("unroll") for (int m = 0; m < 4; ++m) _Pragma("unroll") for (int k = 0; k < 2; ++k) dst[m][k] = *(const PG8_LAS bf16x8*)(lds + PG8_SA(b, h) + aoff + m * 2048 + k * 1024); } while (0)
; #define PG8_MMA(ai, bj, At, Bt) do { __builtin_amdgcn_s_setprio(1); _Pragma("unroll") for (int m = 0; m < 4; ++m) _Pragma("unroll") for (int n = 0; n < 2; ++n) _Pragma("unroll") for (int k = 0; k < 2; ++k) \
;         acc[ai][bj][m][n] = __builtin_amdgcn_mfma_f32_16x16x32_bf16(Bt[n][k], At[m][k], acc[ai][bj][m][n], 0, 0, 0); __builtin_amdgcn_s_setprio(0); } while (0)
; #define PG8_WAIT_V(n) asm volatile("s_waitcnt vmcnt(" #n ")" ::: "memory")
; #define PG8_WAIT_L(n) asm volatile("s_waitcnt lgkmcnt(" #n ")" ::: "memory")
; #define PG8_BAR __builtin_amdgcn_s_barrier()
; #define PG8_SCHED __builtin_amdgcn_sched_barrier(0)
; template <class Epi, class Sched, bool ALIGN_EPI = false, bool SP2 = false, bool PAIR_ACC = false>
; __device__ __forceinline__ void gemm_phase(PG8_LAS unsigned char* lds, const Gemm g, const Sched& S, const Epi& E) {
;     ...
;             PG8_LDA(At, 1, 1); PG8_STAGE(PG8_SB(1, 0), b3, voffB); PG8_STAGE(PG8_SB(1, 1), b3 + hstep, voffB); PG8_STAGE(PG8_SA(1, 0), a3, voffA);
;             PG8_WAIT_V(8); PG8_WAIT_L(0); PG8_BAR; PG8_MMA(1, 0, At, B0); PG8_MMA(1, 1, At, B1); PG8_BAR; PG8_SCHED;
;     ...
;         if (!has_next) break;
;         if (!(PAIR_ACC && cur.pn < 4)) {
; #pragma unroll
;         for (int a = 0; a < 2; ++a)
; #pragma unroll
;             for (int b = 0; b < 2; ++b)
; #pragma unroll
;                 for (int m = 0; m < 4; ++m)
; #pragma unroll
;                     for (int n = 0; n < 2; ++n) acc[a][b][m][n] = (f32x4){0.f, 0.f, 0.f, 0.f};
;         }
	s_add_i32 s52, s60, s36
	v_lshl_add_u64 v[164:165], v[164:165], 0, s[30:31]
	s_mov_b32 m0, s52
	ds_read_b128 v[194:197], v151 offset:49152
	ds_read_b128 v[206:209], v151 offset:50176
	ds_read_b128 v[210:213], v151 offset:51200
	ds_read_b128 v[214:217], v151 offset:52224
	ds_read_b128 v[218:221], v151 offset:53248
	ds_read_b128 v[222:225], v151 offset:54272
	ds_read_b128 v[226:229], v151 offset:55296
	ds_read_b128 v[230:233], v151 offset:56320
	global_load_lds_dwordx4 v[164:165], off
	s_add_i32 m0, s52, 0x2000
	s_add_u32 s38, s38, 0xb0080
	v_lshl_add_u64 v[164:165], v[170:171], 0, s[30:31]
	s_addc_u32 s39, s39, 0
	s_add_i32 s52, s61, s36
	global_load_lds_dwordx4 v[164:165], off
	v_lshl_add_u64 v[164:165], s[38:39], 0, v[132:133]
	s_mov_b32 m0, s52
	s_nop 0
	global_load_lds_dwordx4 v[164:165], off
	v_lshl_add_u64 v[164:165], s[38:39], 0, v[136:137]
	s_add_i32 m0, s52, 0x2000
	s_nop 0
	global_load_lds_dwordx4 v[164:165], off
	v_lshl_add_u64 v[164:165], v[198:199], 0, s[30:31]
	s_mov_b32 m0, s44
	s_nop 0
	global_load_lds_dwordx4 v[164:165], off
	v_lshl_add_u64 v[164:165], v[234:235], 0, s[30:31]
	s_mov_b32 m0, s45
	s_nop 0
	global_load_lds_dwordx4 v[164:165], off
	s_waitcnt vmcnt(8)
	s_waitcnt lgkmcnt(0)
	s_barrier
	v_mfma_f32_16x16x32_bf16 v[126:129], v[152:155], v[194:197], v[126:129]
	v_mfma_f32_16x16x32_bf16 v[122:125], v[160:163], v[194:197], v[122:125]
	v_mfma_f32_16x16x32_bf16 v[86:89], v[152:155], v[210:213], v[86:89]
	v_mfma_f32_16x16x32_bf16 v[66:69], v[160:163], v[210:213], v[66:69]
	v_mfma_f32_16x16x32_bf16 v[30:33], v[152:155], v[218:221], v[30:33]
	v_mfma_f32_16x16x32_bf16 v[26:29], v[160:163], v[218:221], v[26:29]
	v_mfma_f32_16x16x32_bf16 v[14:17], v[152:155], v[226:229], v[14:17]
	v_mfma_f32_16x16x32_bf16 v[10:13], v[160:163], v[226:229], v[10:13]
	v_mfma_f32_16x16x32_bf16 v[126:129], v[156:159], v[206:209], v[126:129]
	v_mfma_f32_16x16x32_bf16 v[122:125], v[174:177], v[206:209], v[122:125]
	v_mfma_f32_16x16x32_bf16 v[86:89], v[156:159], v[214:217], v[86:89]
	v_mfma_f32_16x16x32_bf16 v[66:69], v[174:177], v[214:217], v[66:69]
	v_mfma_f32_16x16x32_bf16 v[30:33], v[156:159], v[222:225], v[30:33]
	v_mfma_f32_16x16x32_bf16 v[26:29], v[174:177], v[222:225], v[26:29]
	v_mfma_f32_16x16x32_bf16 v[14:17], v[156:159], v[230:233], v[14:17]
	v_mfma_f32_16x16x32_bf16 v[10:13], v[174:177], v[230:233], v[10:13]
	v_mfma_f32_16x16x32_bf16 v[118:121], v[178:181], v[194:197], v[118:121]
	v_mfma_f32_16x16x32_bf16 v[106:109], v[186:189], v[194:197], v[106:109]
	v_mfma_f32_16x16x32_bf16 v[38:41], v[178:181], v[210:213], v[38:41]
	v_mfma_f32_16x16x32_bf16 v[34:37], v[186:189], v[210:213], v[34:37]
	v_mfma_f32_16x16x32_bf16 v[22:25], v[178:181], v[218:221], v[22:25]
	v_mfma_f32_16x16x32_bf16 v[18:21], v[186:189], v[218:221], v[18:21]
	v_mfma_f32_16x16x32_bf16 v[6:9], v[178:181], v[226:229], v[6:9]
	v_mfma_f32_16x16x32_bf16 v[2:5], v[186:189], v[226:229], v[2:5]
	v_mfma_f32_16x16x32_bf16 v[118:121], v[182:185], v[206:209], v[118:121]
	v_mfma_f32_16x16x32_bf16 v[106:109], v[190:193], v[206:209], v[106:109]
	v_mfma_f32_16x16x32_bf16 v[38:41], v[182:185], v[214:217], v[38:41]
	v_mfma_f32_16x16x32_bf16 v[34:37], v[190:193], v[214:217], v[34:37]
	v_mfma_f32_16x16x32_bf16 v[22:25], v[182:185], v[222:225], v[22:25]
	v_mfma_f32_16x16x32_bf16 v[18:21], v[190:193], v[222:225], v[18:21]
	v_mfma_f32_16x16x32_bf16 v[6:9], v[182:185], v[230:233], v[6:9]
	v_mfma_f32_16x16x32_bf16 v[2:5], v[190:193], v[230:233], v[2:5]
	s_barrier
	s_add_i32 s59, s59, 2
	s_add_u32 s50, s50, 0x100
	s_addc_u32 s51, s51, 0
	s_cmp_gt_u32 s59, 41
	s_cbranch_scc0 .LBB0_937
	s_add_u32 s38, s57, 0xffffff00
	s_addc_u32 s39, s58, -1
	s_and_b64 vcc, exec, s[8:9]
	s_cbranch_vccnz .LBB0_924
	v_mov_b32_e32 v2, 0
	s_mov_b32 s18, s54
	s_mov_b32 s5, s55
	s_mov_b64 s[28:29], s[48:49]
	s_mov_b32 s43, s56
	v_mov_b32_e32 v3, v2
	v_mov_b32_e32 v4, v2
	v_mov_b32_e32 v5, v2
	v_mov_b32_e32 v6, v2
	v_mov_b32_e32 v7, v2
	v_mov_b32_e32 v8, v2
	v_mov_b32_e32 v9, v2
	v_mov_b32_e32 v18, v2
	v_mov_b32_e32 v19, v2
	v_mov_b32_e32 v20, v2
	v_mov_b32_e32 v21, v2
	v_mov_b32_e32 v22, v2
	v_mov_b32_e32 v23, v2
	v_mov_b32_e32 v24, v2
	v_mov_b32_e32 v25, v2
	v_mov_b32_e32 v34, v2
	v_mov_b32_e32 v35, v2
	v_mov_b32_e32 v36, v2
	v_mov_b32_e32 v37, v2
	v_mov_b32_e32 v38, v2
	v_mov_b32_e32 v39, v2
	v_mov_b32_e32 v40, v2
	v_mov_b32_e32 v41, v2
	v_mov_b32_e32 v106, v2
	v_mov_b32_e32 v107, v2
	v_mov_b32_e32 v108, v2
	v_mov_b32_e32 v109, v2
	v_mov_b32_e32 v118, v2
	v_mov_b32_e32 v119, v2
	v_mov_b32_e32 v120, v2
	v_mov_b32_e32 v121, v2
	v_mov_b32_e32 v10, v2
	v_mov_b32_e32 v11, v2
	v_mov_b32_e32 v12, v2
	v_mov_b32_e32 v13, v2
	v_mov_b32_e32 v14, v2
	v_mov_b32_e32 v15, v2
	v_mov_b32_e32 v16, v2
	v_mov_b32_e32 v17, v2
	v_mov_b32_e32 v26, v2
	v_mov_b32_e32 v27, v2
	v_mov_b32_e32 v28, v2
	v_mov_b32_e32 v29, v2
	v_mov_b32_e32 v30, v2
	v_mov_b32_e32 v31, v2
	v_mov_b32_e32 v32, v2
	v_mov_b32_e32 v33, v2
	v_mov_b32_e32 v66, v2
	v_mov_b32_e32 v67, v2
	v_mov_b32_e32 v68, v2
	v_mov_b32_e32 v69, v2
	v_mov_b32_e32 v86, v2
	v_mov_b32_e32 v87, v2
	v_mov_b32_e32 v88, v2
	v_mov_b32_e32 v89, v2
	v_mov_b32_e32 v122, v2
	v_mov_b32_e32 v123, v2
	v_mov_b32_e32 v124, v2
	v_mov_b32_e32 v125, v2
	v_mov_b32_e32 v126, v2
	v_mov_b32_e32 v127, v2
	v_mov_b32_e32 v128, v2
	v_mov_b32_e32 v129, v2
	v_mov_b32_e32 v94, v2
	v_mov_b32_e32 v95, v2
	v_mov_b32_e32 v96, v2
	v_mov_b32_e32 v97, v2
	v_mov_b32_e32 v102, v2
	v_mov_b32_e32 v103, v2
	v_mov_b32_e32 v104, v2
	v_mov_b32_e32 v105, v2
	v_mov_b32_e32 v70, v2
	v_mov_b32_e32 v71, v2
	v_mov_b32_e32 v72, v2
	v_mov_b32_e32 v73, v2
	v_mov_b32_e32 v78, v2
	v_mov_b32_e32 v79, v2
	v_mov_b32_e32 v80, v2
	v_mov_b32_e32 v81, v2
	v_mov_b32_e32 v42, v2
	v_mov_b32_e32 v43, v2
	v_mov_b32_e32 v44, v2
	v_mov_b32_e32 v45, v2
	v_mov_b32_e32 v50, v2
	v_mov_b32_e32 v51, v2
	v_mov_b32_e32 v52, v2
	v_mov_b32_e32 v53, v2
	v_mov_b32_e32 v46, v2
	v_mov_b32_e32 v47, v2
	v_mov_b32_e32 v48, v2
	v_mov_b32_e32 v49, v2
	v_mov_b32_e32 v54, v2
	v_mov_b32_e32 v55, v2
	v_mov_b32_e32 v56, v2
	v_mov_b32_e32 v57, v2
	v_mov_b32_e32 v110, v2
	v_mov_b32_e32 v111, v2
	v_mov_b32_e32 v112, v2
	v_mov_b32_e32 v113, v2
	v_mov_b32_e32 v114, v2
	v_mov_b32_e32 v115, v2
	v_mov_b32_e32 v116, v2
	v_mov_b32_e32 v117, v2
	v_mov_b32_e32 v90, v2
	v_mov_b32_e32 v91, v2
	v_mov_b32_e32 v92, v2
	v_mov_b32_e32 v93, v2
	v_mov_b32_e32 v98, v2
	v_mov_b32_e32 v99, v2
	v_mov_b32_e32 v100, v2
	v_mov_b32_e32 v101, v2
	v_mov_b32_e32 v74, v2
	v_mov_b32_e32 v75, v2
	v_mov_b32_e32 v76, v2
	v_mov_b32_e32 v77, v2
	v_mov_b32_e32 v82, v2
	v_mov_b32_e32 v83, v2
	v_mov_b32_e32 v84, v2
	v_mov_b32_e32 v85, v2
	v_mov_b32_e32 v62, v2
	v_mov_b32_e32 v63, v2
	v_mov_b32_e32 v64, v2
	v_mov_b32_e32 v65, v2
	v_mov_b32_e32 v58, v2
	v_mov_b32_e32 v59, v2
	v_mov_b32_e32 v60, v2
	v_mov_b32_e32 v61, v2
	s_andn2_b64 vcc, exec, s[6:7]
	s_cbranch_vccnz .LBB0_925

; #define PG8_STAGE(bufoff, gbase, voff) do { _Pragma("unroll") for (int _i = 0; _i < 2; ++_i) \
;         __builtin_amdgcn_global_load_lds((const unsigned*)((const char*)(gbase) + (voff)[_i]), (PG8_LAS unsigned*)(lds + (bufoff) + ldsw + _i * 8192), 16, 0, 0); } while (0)
; #define PG8_LDA(dst, b, h) do { _Pragma("unroll") for (int m = 0; m < 4; ++m) _Pragma("unroll") for (int k = 0; k < 2; ++k) dst[m][k] = *(const PG8_LAS bf16x8*)(lds + PG8_SA(b, h) + aoff + m * 2048 + k * 1024); } while (0)
; #define PG8_LDB(dst, b, h) do { _Pragma("unroll") for (int n = 0; n < 2; ++n) _Pragma("unroll") for (int k = 0; k < 2; ++k) dst[n][k] = *(const PG8_LAS bf16x8*)(lds + PG8_SB(b, h) + boff + n * 2048 + k * 1024); } while (0)
; #define PG8_WAIT_V(n) asm volatile("s_waitcnt vmcnt(" #n ")" ::: "memory")
; #define PG8_WAIT_L(n) asm volatile("s_waitcnt lgkmcnt(" #n ")" ::: "memory")
; #define PG8_BAR __builtin_amdgcn_s_barrier()
; template <class Epi, class Sched, bool ALIGN_EPI = false, bool SP2 = false, bool PAIR_ACC = false>
; __device__ __forceinline__ void gemm_phase(PG8_LAS unsigned char* lds, const Gemm g, const Sched& S, const Epi& E) {
;     ...
;         const bool has_next = S.next(ui + 1, nxt);
;         const char* nA = has_next ? (const char*)g.A + (size_t)nxt.pm * tstep + (size_t)(nxt.pn / g.a_div) * g.a_sel : cA; const char* nB = has_next ? (const char*)g.Bt + (size_t)nxt.pn * tstep : cB;
;         for (int t = 0; t < nt; t += 2) {
;             const bool last = (t == nt - 2);
;             const char* a1 = cA + (size_t)(t + 1) * kstep;
;             const char* a2 = last ? nA : cA + (size_t)(t + 2) * kstep; const char* b2 = last ? nB : cB + (size_t)(t + 2) * kstep;
;             const char* a3 = a2 + kstep; const char* b3 = b2 + kstep;
;             if (last && has_next) S.a_ready(nxt);
;             if constexpr (SP2) {
;             PG8_LDB(B0, 0, 0); PG8_LDB(B1, 0, 1); PG8_SCHED; PG8_LDA(At, 0, 0); PG8_STAGE(PG8_SA(1, 1), a1 + hstep, voffA);
;             PG8_WAIT_V(8); PG8_WAIT_L(0); PG8_BAR; PG8_MMA(0, 0, At, B0); PG8_MMA(0, 1, At, B1); PG8_BAR; PG8_SCHED;
;             PG8_LDA(At, 0, 1); PG8_STAGE(PG8_SB(0, 0), b2, voffB); PG8_STAGE(PG8_SB(0, 1), b2 + hstep, voffB); PG8_STAGE(PG8_SA(0, 0), a2, voffA);
;             PG8_WAIT_V(8); PG8_WAIT_L(0); PG8_BAR; PG8_MMA(1, 0, At, B0); PG8_MMA(1, 1, At, B1); PG8_BAR; PG8_SCHED;
.LBB0_1092:
	s_mov_b32 s78, s23
	s_ashr_i32 s79, s23, 31
	s_lshl_b64 s[20:21], s[78:79], 19
	s_add_u32 s82, s59, s20
	s_addc_u32 s83, s61, s21
	s_mov_b32 s76, s19
	s_and_b64 s[20:21], s[80:81], exec
	s_cselect_b32 s15, s83, s13
	s_cselect_b32 s19, s82, s12
	s_ashr_i32 s77, s76, 31
	s_lshl_b64 s[20:21], s[76:77], 19
	s_add_u32 s84, s63, s20
	s_addc_u32 s85, s69, s21
	s_and_b64 s[20:21], s[80:81], exec
	s_cselect_b32 s22, s85, s17
	s_cselect_b32 s23, s84, s16
	s_add_u32 s12, s12, 0x40080
	s_addc_u32 s13, s13, 0
	s_add_u32 s30, s16, 0x100
	s_addc_u32 s42, s17, 0
	s_mov_b32 s43, -2
	s_waitcnt lgkmcnt(0)
	ds_read_b128 v[130:133], v195
	ds_read_b128 v[134:137], v195 offset:1024
	ds_read_b128 v[138:141], v195 offset:2048
	ds_read_b128 v[142:145], v195 offset:3072
	ds_read_b128 v[176:179], v196
	ds_read_b128 v[180:183], v196 offset:1024
	ds_read_b128 v[184:187], v196 offset:2048
	ds_read_b128 v[188:191], v196 offset:3072
	s_add_u32 s16, s12, 0xfffc0080
	s_addc_u32 s17, s13, -1
	s_cmp_eq_u32 s43, 12
	s_cselect_b32 s21, s15, s17
	s_cselect_b32 s20, s19, s16
	s_cselect_b32 s17, s22, s42
	s_cselect_b32 s16, s23, s30
	v_lshl_add_u64 v[192:193], s[12:13], 0, v[170:171]
	s_add_i32 m0, s73, 0xc000
	ds_read_b128 v[200:203], v197
	ds_read_b128 v[204:207], v197 offset:1024
	ds_read_b128 v[208:211], v197 offset:2048
	ds_read_b128 v[212:215], v197 offset:3072
	ds_read_b128 v[216:219], v197 offset:4096
	ds_read_b128 v[220:223], v197 offset:5120
	ds_read_b128 v[224:227], v197 offset:6144
	ds_read_b128 v[228:231], v197 offset:7168
	global_load_lds_dwordx4 v[192:193], off
	v_lshl_add_u64 v[192:193], s[12:13], 0, v[172:173]
	s_add_i32 m0, s73, 0xe000
	s_nop 0
	global_load_lds_dwordx4 v[192:193], off
	s_waitcnt vmcnt(8)
	s_waitcnt lgkmcnt(0)
	s_barrier
	v_mfma_f32_16x16x32_bf16 v[126:129], v[130:133], v[200:203], 0
	v_mfma_f32_16x16x32_bf16 v[122:125], v[138:141], v[200:203], 0
	v_mfma_f32_16x16x32_bf16 v[110:113], v[130:133], v[208:211], 0
	v_mfma_f32_16x16x32_bf16 v[106:109], v[138:141], v[208:211], 0
	v_mfma_f32_16x16x32_bf16 v[94:97], v[130:133], v[216:219], 0
	v_mfma_f32_16x16x32_bf16 v[90:93], v[138:141], v[216:219], 0
	v_mfma_f32_16x16x32_bf16 v[78:81], v[130:133], v[224:227], 0
	v_mfma_f32_16x16x32_bf16 v[74:77], v[138:141], v[224:227], 0
	v_mfma_f32_16x16x32_bf16 v[126:129], v[134:137], v[204:207], v[126:129]
	v_mfma_f32_16x16x32_bf16 v[122:125], v[142:145], v[204:207], v[122:125]
	v_mfma_f32_16x16x32_bf16 v[110:113], v[134:137], v[212:215], v[110:113]
	v_mfma_f32_16x16x32_bf16 v[106:109], v[142:145], v[212:215], v[106:109]
	v_mfma_f32_16x16x32_bf16 v[94:97], v[134:137], v[220:223], v[94:97]
	v_mfma_f32_16x16x32_bf16 v[90:93], v[142:145], v[220:223], v[90:93]
	v_mfma_f32_16x16x32_bf16 v[78:81], v[134:137], v[228:231], v[78:81]
	v_mfma_f32_16x16x32_bf16 v[74:77], v[142:145], v[228:231], v[74:77]
	v_mfma_f32_16x16x32_bf16 v[118:121], v[176:179], v[200:203], 0
	v_mfma_f32_16x16x32_bf16 v[114:117], v[184:187], v[200:203], 0
	v_mfma_f32_16x16x32_bf16 v[102:105], v[176:179], v[208:211], 0
	v_mfma_f32_16x16x32_bf16 v[98:101], v[184:187], v[208:211], 0
	v_mfma_f32_16x16x32_bf16 v[86:89], v[176:179], v[216:219], 0
	v_mfma_f32_16x16x32_bf16 v[82:85], v[184:187], v[216:219], 0
	v_mfma_f32_16x16x32_bf16 v[70:73], v[176:179], v[224:227], 0
	v_mfma_f32_16x16x32_bf16 v[66:69], v[184:187], v[224:227], 0
	v_mfma_f32_16x16x32_bf16 v[118:121], v[180:183], v[204:207], v[118:121]
	v_mfma_f32_16x16x32_bf16 v[114:117], v[188:191], v[204:207], v[114:117]
	v_mfma_f32_16x16x32_bf16 v[102:105], v[180:183], v[212:215], v[102:105]
	v_mfma_f32_16x16x32_bf16 v[98:101], v[188:191], v[212:215], v[98:101]
	v_mfma_f32_16x16x32_bf16 v[86:89], v[180:183], v[220:223], v[86:89]
	v_mfma_f32_16x16x32_bf16 v[82:85], v[188:191], v[220:223], v[82:85]
	v_mfma_f32_16x16x32_bf16 v[70:73], v[180:183], v[228:231], v[70:73]
	v_mfma_f32_16x16x32_bf16 v[66:69], v[188:191], v[228:231], v[66:69]
	s_barrier
	s_add_i32 s77, s34, s71
	v_lshl_add_u64 v[192:193], s[16:17], 0, v[148:149]
	s_mov_b32 m0, s77
	ds_read_b128 v[200:203], v197 offset:16384
	ds_read_b128 v[204:207], v197 offset:17408
	ds_read_b128 v[208:211], v197 offset:18432
	ds_read_b128 v[212:215], v197 offset:19456
	ds_read_b128 v[216:219], v197 offset:20480
	ds_read_b128 v[220:223], v197 offset:21504
	ds_read_b128 v[224:227], v197 offset:22528
	ds_read_b128 v[228:231], v197 offset:23552
	global_load_lds_dwordx4 v[192:193], off
	s_add_i32 m0, s77, 0x2000
	s_add_u32 s86, s16, 0x40000
	v_lshl_add_u64 v[232:233], s[16:17], 0, v[152:153]
	s_addc_u32 s87, s17, 0
	s_add_i32 s77, s35, s71
	global_load_lds_dwordx4 v[232:233], off
	v_lshl_add_u64 v[234:235], s[86:87], 0, v[148:149]
	s_mov_b32 m0, s77
	v_lshl_add_u64 v[236:237], s[20:21], 0, v[150:151]
	global_load_lds_dwordx4 v[234:235], off
	v_lshl_add_u64 v[234:235], s[86:87], 0, v[152:153]
	s_add_i32 m0, s77, 0x2000
	s_nop 0
	global_load_lds_dwordx4 v[234:235], off
	v_lshl_add_u64 v[234:235], s[20:21], 0, v[146:147]
	s_mov_b32 m0, s73
	s_nop 0
	global_load_lds_dwordx4 v[234:235], off
	s_mov_b32 m0, s75
	s_nop 0
	global_load_lds_dwordx4 v[236:237], off
	s_waitcnt vmcnt(8)
	s_waitcnt lgkmcnt(0)
	s_barrier
; #define PG8_STAGE(bufoff, gbase, voff) do { _Pragma("unroll") for (int _i = 0; _i < 2; ++_i) \
;         __builtin_amdgcn_global_load_lds((const unsigned*)((const char*)(gbase) + (voff)[_i]), (PG8_LAS unsigned*)(lds + (bufoff) + ldsw + _i * 8192), 16, 0, 0); } while (0)
; #define PG8_LDA(dst, b, h) do { _Pragma("unroll") for (int m = 0; m < 4; ++m) _Pragma("unroll") for (int k = 0; k < 2; ++k) dst[m][k] = *(const PG8_LAS bf16x8*)(lds + PG8_SA(b, h) + aoff + m * 2048 + k * 1024); } while (0)
; #define PG8_LDB(dst, b, h) do { _Pragma("unroll") for (int n = 0; n < 2; ++n) _Pragma("unroll") for (int k = 0; k < 2; ++k) dst[n][k] = *(const PG8_LAS bf16x8*)(lds + PG8_SB(b, h) + boff + n * 2048 + k * 1024); } while (0)
; #define PG8_MMA(ai, bj, At, Bt) do { __builtin_amdgcn_s_setprio(1); _Pragma("unroll") for (int m = 0; m < 4; ++m) _Pragma("unroll") for (int n = 0; n < 2; ++n) _Pragma("unroll") for (int k = 0; k < 2; ++k) \
;         acc[ai][bj][m][n] = __builtin_amdgcn_mfma_f32_16x16x32_bf16(Bt[n][k], At[m][k], acc[ai][bj][m][n], 0, 0, 0); __builtin_amdgcn_s_setprio(0); } while (0)
; #define PG8_WAIT_V(n) asm volatile("s_waitcnt vmcnt(" #n ")" ::: "memory")
; #define PG8_WAIT_L(n) asm volatile("s_waitcnt lgkmcnt(" #n ")" ::: "memory")
; #define PG8_BAR __builtin_amdgcn_s_barrier()
; #define PG8_SCHED __builtin_amdgcn_sched_barrier(0)
; template <class Epi, class Sched, bool ALIGN_EPI = false, bool SP2 = false, bool PAIR_ACC = false>
; __device__ __forceinline__ void gemm_phase(PG8_LAS unsigned char* lds, const Gemm g, const Sched& S, const Epi& E) {
;     ...
;             PG8_WAIT_V(8); PG8_WAIT_L(0); PG8_BAR; PG8_MMA(0, 0, At, B0); PG8_MMA(0, 1, At, B1); PG8_BAR; PG8_SCHED;
;             PG8_LDA(At, 0, 1); PG8_STAGE(PG8_SB(0, 0), b2, voffB); PG8_STAGE(PG8_SB(0, 1), b2 + hstep, voffB); PG8_STAGE(PG8_SA(0, 0), a2, voffA);
;             PG8_WAIT_V(8); PG8_WAIT_L(0); PG8_BAR; PG8_MMA(1, 0, At, B0); PG8_MMA(1, 1, At, B1); PG8_BAR; PG8_SCHED;
;             PG8_LDB(B0, 1, 0); PG8_LDB(B1, 1, 1); PG8_SCHED; PG8_LDA(At, 1, 0); PG8_STAGE(PG8_SA(0, 1), a2 + hstep, voffA);
;             PG8_WAIT_V(8); PG8_WAIT_L(0); PG8_BAR; PG8_MMA(0, 0, At, B0); PG8_MMA(0, 1, At, B1); PG8_BAR; PG8_SCHED;
	v_mfma_f32_16x16x32_bf16 v[62:65], v[130:133], v[200:203], 0
	v_mfma_f32_16x16x32_bf16 v[58:61], v[138:141], v[200:203], 0
	v_mfma_f32_16x16x32_bf16 v[46:49], v[130:133], v[208:211], 0
	v_mfma_f32_16x16x32_bf16 v[42:45], v[138:141], v[208:211], 0
	v_mfma_f32_16x16x32_bf16 v[30:33], v[130:133], v[216:219], 0
	v_mfma_f32_16x16x32_bf16 v[26:29], v[138:141], v[216:219], 0
	v_mfma_f32_16x16x32_bf16 v[14:17], v[130:133], v[224:227], 0
	v_mfma_f32_16x16x32_bf16 v[10:13], v[138:141], v[224:227], 0
	v_mfma_f32_16x16x32_bf16 v[62:65], v[134:137], v[204:207], v[62:65]
	v_mfma_f32_16x16x32_bf16 v[58:61], v[142:145], v[204:207], v[58:61]
	v_mfma_f32_16x16x32_bf16 v[46:49], v[134:137], v[212:215], v[46:49]
	v_mfma_f32_16x16x32_bf16 v[42:45], v[142:145], v[212:215], v[42:45]
	v_mfma_f32_16x16x32_bf16 v[30:33], v[134:137], v[220:223], v[30:33]
	v_mfma_f32_16x16x32_bf16 v[26:29], v[142:145], v[220:223], v[26:29]
	v_mfma_f32_16x16x32_bf16 v[14:17], v[134:137], v[228:231], v[14:17]
	v_mfma_f32_16x16x32_bf16 v[10:13], v[142:145], v[228:231], v[10:13]
	v_mfma_f32_16x16x32_bf16 v[54:57], v[176:179], v[200:203], 0
	v_mfma_f32_16x16x32_bf16 v[50:53], v[184:187], v[200:203], 0
	v_mfma_f32_16x16x32_bf16 v[38:41], v[176:179], v[208:211], 0
	v_mfma_f32_16x16x32_bf16 v[34:37], v[184:187], v[208:211], 0
	v_mfma_f32_16x16x32_bf16 v[22:25], v[176:179], v[216:219], 0
	v_mfma_f32_16x16x32_bf16 v[18:21], v[184:187], v[216:219], 0
	v_mfma_f32_16x16x32_bf16 v[6:9], v[176:179], v[224:227], 0
	v_mfma_f32_16x16x32_bf16 v[2:5], v[184:187], v[224:227], 0
	v_mfma_f32_16x16x32_bf16 v[54:57], v[180:183], v[204:207], v[54:57]
	v_mfma_f32_16x16x32_bf16 v[50:53], v[188:191], v[204:207], v[50:53]
	v_mfma_f32_16x16x32_bf16 v[38:41], v[180:183], v[212:215], v[38:41]
	v_mfma_f32_16x16x32_bf16 v[34:37], v[188:191], v[212:215], v[34:37]
	v_mfma_f32_16x16x32_bf16 v[22:25], v[180:183], v[220:223], v[22:25]
	v_mfma_f32_16x16x32_bf16 v[18:21], v[188:191], v[220:223], v[18:21]
	v_mfma_f32_16x16x32_bf16 v[6:9], v[180:183], v[228:231], v[6:9]
	v_mfma_f32_16x16x32_bf16 v[2:5], v[188:191], v[228:231], v[2:5]
	s_barrier
	s_branch .Lpeel_mid_1093
.LBB0_1093:
	ds_read_b128 v[130:133], v195
	ds_read_b128 v[134:137], v195 offset:1024
	ds_read_b128 v[138:141], v195 offset:2048
	ds_read_b128 v[142:145], v195 offset:3072
	ds_read_b128 v[176:179], v196
	ds_read_b128 v[180:183], v196 offset:1024
	ds_read_b128 v[184:187], v196 offset:2048
	ds_read_b128 v[188:191], v196 offset:3072
	s_add_u32 s16, s12, 0xfffc0080
	s_addc_u32 s17, s13, -1
	s_cmp_eq_u32 s43, 12
	s_cselect_b32 s21, s15, s17
	s_cselect_b32 s20, s19, s16
	s_cselect_b32 s17, s22, s42
	s_cselect_b32 s16, s23, s30
	v_lshl_add_u64 v[192:193], s[12:13], 0, v[170:171]
	s_add_i32 m0, s73, 0xc000
	ds_read_b128 v[200:203], v197
	ds_read_b128 v[204:207], v197 offset:1024
	ds_read_b128 v[208:211], v197 offset:2048
	ds_read_b128 v[212:215], v197 offset:3072
	ds_read_b128 v[216:219], v197 offset:4096
	ds_read_b128 v[220:223], v197 offset:5120
	ds_read_b128 v[224:227], v197 offset:6144
	ds_read_b128 v[228:231], v197 offset:7168
	global_load_lds_dwordx4 v[192:193], off
	v_lshl_add_u64 v[192:193], s[12:13], 0, v[172:173]
	s_add_i32 m0, s73, 0xe000
	s_nop 0
	global_load_lds_dwordx4 v[192:193], off
	s_waitcnt vmcnt(8)
	s_waitcnt lgkmcnt(0)
	s_barrier
	v_mfma_f32_16x16x32_bf16 v[126:129], v[130:133], v[200:203], v[126:129]
	v_mfma_f32_16x16x32_bf16 v[122:125], v[138:141], v[200:203], v[122:125]
	v_mfma_f32_16x16x32_bf16 v[110:113], v[130:133], v[208:211], v[110:113]
	v_mfma_f32_16x16x32_bf16 v[106:109], v[138:141], v[208:211], v[106:109]
	v_mfma_f32_16x16x32_bf16 v[94:97], v[130:133], v[216:219], v[94:97]
	v_mfma_f32_16x16x32_bf16 v[90:93], v[138:141], v[216:219], v[90:93]
	v_mfma_f32_16x16x32_bf16 v[78:81], v[130:133], v[224:227], v[78:81]
	v_mfma_f32_16x16x32_bf16 v[74:77], v[138:141], v[224:227], v[74:77]
	v_mfma_f32_16x16x32_bf16 v[126:129], v[134:137], v[204:207], v[126:129]
	v_mfma_f32_16x16x32_bf16 v[122:125], v[142:145], v[204:207], v[122:125]
	v_mfma_f32_16x16x32_bf16 v[110:113], v[134:137], v[212:215], v[110:113]
	v_mfma_f32_16x16x32_bf16 v[106:109], v[142:145], v[212:215], v[106:109]
	v_mfma_f32_16x16x32_bf16 v[94:97], v[134:137], v[220:223], v[94:97]
	v_mfma_f32_16x16x32_bf16 v[90:93], v[142:145], v[220:223], v[90:93]
	v_mfma_f32_16x16x32_bf16 v[78:81], v[134:137], v[228:231], v[78:81]
	v_mfma_f32_16x16x32_bf16 v[74:77], v[142:145], v[228:231], v[74:77]
	v_mfma_f32_16x16x32_bf16 v[118:121], v[176:179], v[200:203], v[118:121]
	v_mfma_f32_16x16x32_bf16 v[114:117], v[184:187], v[200:203], v[114:117]
	v_mfma_f32_16x16x32_bf16 v[102:105], v[176:179], v[208:211], v[102:105]
	v_mfma_f32_16x16x32_bf16 v[98:101], v[184:187], v[208:211], v[98:101]
	v_mfma_f32_16x16x32_bf16 v[86:89], v[176:179], v[216:219], v[86:89]
	v_mfma_f32_16x16x32_bf16 v[82:85], v[184:187], v[216:219], v[82:85]
	v_mfma_f32_16x16x32_bf16 v[70:73], v[176:179], v[224:227], v[70:73]
	v_mfma_f32_16x16x32_bf16 v[66:69], v[184:187], v[224:227], v[66:69]
	v_mfma_f32_16x16x32_bf16 v[118:121], v[180:183], v[204:207], v[118:121]
	v_mfma_f32_16x16x32_bf16 v[114:117], v[188:191], v[204:207], v[114:117]
	v_mfma_f32_16x16x32_bf16 v[102:105], v[180:183], v[212:215], v[102:105]
	v_mfma_f32_16x16x32_bf16 v[98:101], v[188:191], v[212:215], v[98:101]
	v_mfma_f32_16x16x32_bf16 v[86:89], v[180:183], v[220:223], v[86:89]
	v_mfma_f32_16x16x32_bf16 v[82:85], v[188:191], v[220:223], v[82:85]
	v_mfma_f32_16x16x32_bf16 v[70:73], v[180:183], v[228:231], v[70:73]
	v_mfma_f32_16x16x32_bf16 v[66:69], v[188:191], v[228:231], v[66:69]
	s_barrier
; #define PG8_STAGE(bufoff, gbase, voff) do { _Pragma("unroll") for (int _i = 0; _i < 2; ++_i) \
;         __builtin_amdgcn_global_load_lds((const unsigned*)((const char*)(gbase) + (voff)[_i]), (PG8_LAS unsigned*)(lds + (bufoff) + ldsw + _i * 8192), 16, 0, 0); } while (0)
; #define PG8_LDA(dst, b, h) do { _Pragma("unroll") for (int m = 0; m < 4; ++m) _Pragma("unroll") for (int k = 0; k < 2; ++k) dst[m][k] = *(const PG8_LAS bf16x8*)(lds + PG8_SA(b, h) + aoff + m * 2048 + k * 1024); } while (0)
; #define PG8_LDB(dst, b, h) do { _Pragma("unroll") for (int n = 0; n < 2; ++n) _Pragma("unroll") for (int k = 0; k < 2; ++k) dst[n][k] = *(const PG8_LAS bf16x8*)(lds + PG8_SB(b, h) + boff + n * 2048 + k * 1024); } while (0)
; #define PG8_MMA(ai, bj, At, Bt) do { __builtin_amdgcn_s_setprio(1); _Pragma("unroll") for (int m = 0; m < 4; ++m) _Pragma("unroll") for (int n = 0; n < 2; ++n) _Pragma("unroll") for (int k = 0; k < 2; ++k) \
;         acc[ai][bj][m][n] = __builtin_amdgcn_mfma_f32_16x16x32_bf16(Bt[n][k], At[m][k], acc[ai][bj][m][n], 0, 0, 0); __builtin_amdgcn_s_setprio(0); } while (0)
; #define PG8_WAIT_V(n) asm volatile("s_waitcnt vmcnt(" #n ")" ::: "memory")
; #define PG8_WAIT_L(n) asm volatile("s_waitcnt lgkmcnt(" #n ")" ::: "memory")
; #define PG8_BAR __builtin_amdgcn_s_barrier()
; #define PG8_SCHED __builtin_amdgcn_sched_barrier(0)
; template <class Epi, class Sched, bool ALIGN_EPI = false, bool SP2 = false, bool PAIR_ACC = false>
; __device__ __forceinline__ void gemm_phase(PG8_LAS unsigned char* lds, const Gemm g, const Sched& S, const Epi& E) {
;     ...
;             PG8_LDA(At, 0, 1); PG8_STAGE(PG8_SB(0, 0), b2, voffB); PG8_STAGE(PG8_SB(0, 1), b2 + hstep, voffB); PG8_STAGE(PG8_SA(0, 0), a2, voffA);
;             PG8_WAIT_V(8); PG8_WAIT_L(0); PG8_BAR; PG8_MMA(1, 0, At, B0); PG8_MMA(1, 1, At, B1); PG8_BAR; PG8_SCHED;
;             PG8_LDB(B0, 1, 0); PG8_LDB(B1, 1, 1); PG8_SCHED; PG8_LDA(At, 1, 0); PG8_STAGE(PG8_SA(0, 1), a2 + hstep, voffA);
	s_add_i32 s77, s34, s71
	v_lshl_add_u64 v[192:193], s[16:17], 0, v[148:149]
	s_mov_b32 m0, s77
	ds_read_b128 v[200:203], v197 offset:16384
	ds_read_b128 v[204:207], v197 offset:17408
	ds_read_b128 v[208:211], v197 offset:18432
	ds_read_b128 v[212:215], v197 offset:19456
	ds_read_b128 v[216:219], v197 offset:20480
	ds_read_b128 v[220:223], v197 offset:21504
	ds_read_b128 v[224:227], v197 offset:22528
	ds_read_b128 v[228:231], v197 offset:23552
	global_load_lds_dwordx4 v[192:193], off
	s_add_i32 m0, s77, 0x2000
	s_add_u32 s86, s16, 0x40000
	v_lshl_add_u64 v[232:233], s[16:17], 0, v[152:153]
	s_addc_u32 s87, s17, 0
	s_add_i32 s77, s35, s71
	global_load_lds_dwordx4 v[232:233], off
	v_lshl_add_u64 v[234:235], s[86:87], 0, v[148:149]
	s_mov_b32 m0, s77
	v_lshl_add_u64 v[236:237], s[20:21], 0, v[150:151]
	global_load_lds_dwordx4 v[234:235], off
	v_lshl_add_u64 v[234:235], s[86:87], 0, v[152:153]
	s_add_i32 m0, s77, 0x2000
	s_nop 0
	global_load_lds_dwordx4 v[234:235], off
	v_lshl_add_u64 v[234:235], s[20:21], 0, v[146:147]
	s_mov_b32 m0, s73
	s_nop 0
	global_load_lds_dwordx4 v[234:235], off
	s_mov_b32 m0, s75
	s_nop 0
	global_load_lds_dwordx4 v[236:237], off
	s_waitcnt vmcnt(8)
	s_waitcnt lgkmcnt(0)
	s_barrier
	v_mfma_f32_16x16x32_bf16 v[62:65], v[130:133], v[200:203], v[62:65]
	v_mfma_f32_16x16x32_bf16 v[58:61], v[138:141], v[200:203], v[58:61]
	v_mfma_f32_16x16x32_bf16 v[46:49], v[130:133], v[208:211], v[46:49]
	v_mfma_f32_16x16x32_bf16 v[42:45], v[138:141], v[208:211], v[42:45]
	v_mfma_f32_16x16x32_bf16 v[30:33], v[130:133], v[216:219], v[30:33]
	v_mfma_f32_16x16x32_bf16 v[26:29], v[138:141], v[216:219], v[26:29]
	v_mfma_f32_16x16x32_bf16 v[14:17], v[130:133], v[224:227], v[14:17]
	v_mfma_f32_16x16x32_bf16 v[10:13], v[138:141], v[224:227], v[10:13]
	v_mfma_f32_16x16x32_bf16 v[62:65], v[134:137], v[204:207], v[62:65]
	v_mfma_f32_16x16x32_bf16 v[58:61], v[142:145], v[204:207], v[58:61]
	v_mfma_f32_16x16x32_bf16 v[46:49], v[134:137], v[212:215], v[46:49]
	v_mfma_f32_16x16x32_bf16 v[42:45], v[142:145], v[212:215], v[42:45]
	v_mfma_f32_16x16x32_bf16 v[30:33], v[134:137], v[220:223], v[30:33]
	v_mfma_f32_16x16x32_bf16 v[26:29], v[142:145], v[220:223], v[26:29]
	v_mfma_f32_16x16x32_bf16 v[14:17], v[134:137], v[228:231], v[14:17]
	v_mfma_f32_16x16x32_bf16 v[10:13], v[142:145], v[228:231], v[10:13]
	v_mfma_f32_16x16x32_bf16 v[54:57], v[176:179], v[200:203], v[54:57]
	v_mfma_f32_16x16x32_bf16 v[50:53], v[184:187], v[200:203], v[50:53]
	v_mfma_f32_16x16x32_bf16 v[38:41], v[176:179], v[208:211], v[38:41]
	v_mfma_f32_16x16x32_bf16 v[34:37], v[184:187], v[208:211], v[34:37]
	v_mfma_f32_16x16x32_bf16 v[22:25], v[176:179], v[216:219], v[22:25]
	v_mfma_f32_16x16x32_bf16 v[18:21], v[184:187], v[216:219], v[18:21]
	v_mfma_f32_16x16x32_bf16 v[6:9], v[176:179], v[224:227], v[6:9]
	v_mfma_f32_16x16x32_bf16 v[2:5], v[184:187], v[224:227], v[2:5]
	v_mfma_f32_16x16x32_bf16 v[54:57], v[180:183], v[204:207], v[54:57]
	v_mfma_f32_16x16x32_bf16 v[50:53], v[188:191], v[204:207], v[50:53]
	v_mfma_f32_16x16x32_bf16 v[38:41], v[180:183], v[212:215], v[38:41]
	v_mfma_f32_16x16x32_bf16 v[34:37], v[188:191], v[212:215], v[34:37]
	v_mfma_f32_16x16x32_bf16 v[22:25], v[180:183], v[220:223], v[22:25]
	v_mfma_f32_16x16x32_bf16 v[18:21], v[188:191], v[220:223], v[18:21]
	v_mfma_f32_16x16x32_bf16 v[6:9], v[180:183], v[228:231], v[6:9]
	v_mfma_f32_16x16x32_bf16 v[2:5], v[188:191], v[228:231], v[2:5]
	s_barrier
.Lpeel_mid_1093:
	s_add_i32 s77, 0, 0x18000
	s_add_i32 s79, 0, 0x1c000
	v_add_u32_e32 v142, s77, v194
	v_add_u32_e32 v154, s79, v194
	ds_read_b128 v[130:133], v142
	ds_read_b128 v[134:137], v142 offset:1024
	ds_read_b128 v[138:141], v142 offset:2048
	ds_read_b128 v[142:145], v142 offset:3072
	ds_read_b128 v[176:179], v154
	ds_read_b128 v[180:183], v154 offset:1024
	ds_read_b128 v[184:187], v154 offset:2048
	ds_read_b128 v[188:191], v154 offset:3072
	s_add_u32 s20, s20, 0x40000
	s_addc_u32 s21, s21, 0
	s_mov_b32 m0, s44
	v_lshl_add_u64 v[238:239], s[20:21], 0, v[146:147]
	ds_read_b128 v[200:203], v197 offset:32768
	ds_read_b128 v[204:207], v197 offset:33792
	ds_read_b128 v[208:211], v197 offset:34816
	ds_read_b128 v[212:215], v197 offset:35840
	ds_read_b128 v[216:219], v197 offset:36864
	ds_read_b128 v[220:223], v197 offset:37888
	ds_read_b128 v[224:227], v197 offset:38912
	ds_read_b128 v[228:231], v197 offset:39936
	global_load_lds_dwordx4 v[238:239], off
	v_lshl_add_u64 v[238:239], s[20:21], 0, v[150:151]
	s_mov_b32 m0, s45
	s_nop 0
	global_load_lds_dwordx4 v[238:239], off
	s_waitcnt vmcnt(8)
	s_waitcnt lgkmcnt(0)
	s_barrier
; #define PG8_STAGE(bufoff, gbase, voff) do { _Pragma("unroll") for (int _i = 0; _i < 2; ++_i) \
;         __builtin_amdgcn_global_load_lds((const unsigned*)((const char*)(gbase) + (voff)[_i]), (PG8_LAS unsigned*)(lds + (bufoff) + ldsw + _i * 8192), 16, 0, 0); } while (0)
; #define PG8_LDA(dst, b, h) do { _Pragma("unroll") for (int m = 0; m < 4; ++m) _Pragma("unroll") for (int k = 0; k < 2; ++k) dst[m][k] = *(const PG8_LAS bf16x8*)(lds + PG8_SA(b, h) + aoff + m * 2048 + k * 1024); } while (0)
; #define PG8_MMA(ai, bj, At, Bt) do { __builtin_amdgcn_s_setprio(1); _Pragma("unroll") for (int m = 0; m < 4; ++m) _Pragma("unroll") for (int n = 0; n < 2; ++n) _Pragma("unroll") for (int k = 0; k < 2; ++k) \
;         acc[ai][bj][m][n] = __builtin_amdgcn_mfma_f32_16x16x32_bf16(Bt[n][k], At[m][k], acc[ai][bj][m][n], 0, 0, 0); __builtin_amdgcn_s_setprio(0); } while (0)
; #define PG8_WAIT_V(n) asm volatile("s_waitcnt vmcnt(" #n ")" ::: "memory")
; #define PG8_WAIT_L(n) asm volatile("s_waitcnt lgkmcnt(" #n ")" ::: "memory")
; #define PG8_BAR __builtin_amdgcn_s_barrier()
; #define PG8_SCHED __builtin_amdgcn_sched_barrier(0)
; template <class Epi, class Sched, bool ALIGN_EPI = false, bool SP2 = false, bool PAIR_ACC = false>
; __device__ __forceinline__ void gemm_phase(PG8_LAS unsigned char* lds, const Gemm g, const Sched& S, const Epi& E) {
;     ...
;             PG8_WAIT_V(8); PG8_WAIT_L(0); PG8_BAR; PG8_MMA(0, 0, At, B0); PG8_MMA(0, 1, At, B1); PG8_BAR; PG8_SCHED;
;             PG8_LDA(At, 1, 1); PG8_STAGE(PG8_SB(1, 0), b3, voffB); PG8_STAGE(PG8_SB(1, 1), b3 + hstep, voffB); PG8_STAGE(PG8_SA(1, 0), a3, voffA);
;             PG8_WAIT_V(8); PG8_WAIT_L(0); PG8_BAR; PG8_MMA(1, 0, At, B0); PG8_MMA(1, 1, At, B1); PG8_BAR; PG8_SCHED;
;     ...
;         if constexpr (ALIGN_EPI) { if (wr == 0) PG8_BAR; }
	v_mfma_f32_16x16x32_bf16 v[126:129], v[130:133], v[200:203], v[126:129]
	v_mfma_f32_16x16x32_bf16 v[122:125], v[138:141], v[200:203], v[122:125]
	v_mfma_f32_16x16x32_bf16 v[110:113], v[130:133], v[208:211], v[110:113]
	v_mfma_f32_16x16x32_bf16 v[106:109], v[138:141], v[208:211], v[106:109]
	v_mfma_f32_16x16x32_bf16 v[94:97], v[130:133], v[216:219], v[94:97]
	v_mfma_f32_16x16x32_bf16 v[90:93], v[138:141], v[216:219], v[90:93]
	v_mfma_f32_16x16x32_bf16 v[78:81], v[130:133], v[224:227], v[78:81]
	v_mfma_f32_16x16x32_bf16 v[74:77], v[138:141], v[224:227], v[74:77]
	v_mfma_f32_16x16x32_bf16 v[126:129], v[134:137], v[204:207], v[126:129]
	v_mfma_f32_16x16x32_bf16 v[122:125], v[142:145], v[204:207], v[122:125]
	v_mfma_f32_16x16x32_bf16 v[110:113], v[134:137], v[212:215], v[110:113]
	v_mfma_f32_16x16x32_bf16 v[106:109], v[142:145], v[212:215], v[106:109]
	v_mfma_f32_16x16x32_bf16 v[94:97], v[134:137], v[220:223], v[94:97]
	v_mfma_f32_16x16x32_bf16 v[90:93], v[142:145], v[220:223], v[90:93]
	v_mfma_f32_16x16x32_bf16 v[78:81], v[134:137], v[228:231], v[78:81]
	v_mfma_f32_16x16x32_bf16 v[74:77], v[142:145], v[228:231], v[74:77]
	v_mfma_f32_16x16x32_bf16 v[118:121], v[176:179], v[200:203], v[118:121]
	v_mfma_f32_16x16x32_bf16 v[114:117], v[184:187], v[200:203], v[114:117]
	v_mfma_f32_16x16x32_bf16 v[102:105], v[176:179], v[208:211], v[102:105]
	v_mfma_f32_16x16x32_bf16 v[98:101], v[184:187], v[208:211], v[98:101]
	v_mfma_f32_16x16x32_bf16 v[86:89], v[176:179], v[216:219], v[86:89]
	v_mfma_f32_16x16x32_bf16 v[82:85], v[184:187], v[216:219], v[82:85]
	v_mfma_f32_16x16x32_bf16 v[70:73], v[176:179], v[224:227], v[70:73]
	v_mfma_f32_16x16x32_bf16 v[66:69], v[184:187], v[224:227], v[66:69]
	v_mfma_f32_16x16x32_bf16 v[118:121], v[180:183], v[204:207], v[118:121]
	v_mfma_f32_16x16x32_bf16 v[114:117], v[188:191], v[204:207], v[114:117]
	v_mfma_f32_16x16x32_bf16 v[102:105], v[180:183], v[212:215], v[102:105]
	v_mfma_f32_16x16x32_bf16 v[98:101], v[188:191], v[212:215], v[98:101]
	v_mfma_f32_16x16x32_bf16 v[86:89], v[180:183], v[220:223], v[86:89]
	v_mfma_f32_16x16x32_bf16 v[82:85], v[188:191], v[220:223], v[82:85]
	v_mfma_f32_16x16x32_bf16 v[70:73], v[180:183], v[228:231], v[70:73]
	v_mfma_f32_16x16x32_bf16 v[66:69], v[188:191], v[228:231], v[66:69]
	s_barrier
	s_add_i32 s20, s77, s71
	v_lshl_add_u64 v[192:193], v[192:193], 0, s[48:49]
	s_mov_b32 m0, s20
	ds_read_b128 v[200:203], v197 offset:49152
	ds_read_b128 v[204:207], v197 offset:50176
	ds_read_b128 v[208:211], v197 offset:51200
	ds_read_b128 v[212:215], v197 offset:52224
	ds_read_b128 v[216:219], v197 offset:53248
	ds_read_b128 v[220:223], v197 offset:54272
	ds_read_b128 v[224:227], v197 offset:55296
	ds_read_b128 v[228:231], v197 offset:56320
	global_load_lds_dwordx4 v[192:193], off
	s_add_i32 m0, s20, 0x2000
	s_add_u32 s16, s16, 0x40080
	v_lshl_add_u64 v[192:193], v[232:233], 0, s[48:49]
	s_addc_u32 s17, s17, 0
	s_add_i32 s20, s79, s71
	global_load_lds_dwordx4 v[192:193], off
	v_lshl_add_u64 v[192:193], s[16:17], 0, v[148:149]
	s_mov_b32 m0, s20
	s_nop 0
	global_load_lds_dwordx4 v[192:193], off
	v_lshl_add_u64 v[192:193], s[16:17], 0, v[152:153]
	s_add_i32 m0, s20, 0x2000
	s_nop 0
	global_load_lds_dwordx4 v[192:193], off
	v_lshl_add_u64 v[192:193], v[234:235], 0, s[48:49]
	s_mov_b32 m0, s36
	s_nop 0
	global_load_lds_dwordx4 v[192:193], off
	v_lshl_add_u64 v[192:193], v[236:237], 0, s[48:49]
	s_mov_b32 m0, s37
	s_nop 0
	global_load_lds_dwordx4 v[192:193], off
	s_waitcnt vmcnt(8)
	s_waitcnt lgkmcnt(0)
	s_barrier
	v_mfma_f32_16x16x32_bf16 v[62:65], v[130:133], v[200:203], v[62:65]
	v_mfma_f32_16x16x32_bf16 v[58:61], v[138:141], v[200:203], v[58:61]
	v_mfma_f32_16x16x32_bf16 v[46:49], v[130:133], v[208:211], v[46:49]
	v_mfma_f32_16x16x32_bf16 v[42:45], v[138:141], v[208:211], v[42:45]
	v_mfma_f32_16x16x32_bf16 v[30:33], v[130:133], v[216:219], v[30:33]
	v_mfma_f32_16x16x32_bf16 v[26:29], v[138:141], v[216:219], v[26:29]
	v_mfma_f32_16x16x32_bf16 v[14:17], v[130:133], v[224:227], v[14:17]
	v_mfma_f32_16x16x32_bf16 v[10:13], v[138:141], v[224:227], v[10:13]
	v_mfma_f32_16x16x32_bf16 v[62:65], v[134:137], v[204:207], v[62:65]
	v_mfma_f32_16x16x32_bf16 v[58:61], v[142:145], v[204:207], v[58:61]
	v_mfma_f32_16x16x32_bf16 v[46:49], v[134:137], v[212:215], v[46:49]
	v_mfma_f32_16x16x32_bf16 v[42:45], v[142:145], v[212:215], v[42:45]
	v_mfma_f32_16x16x32_bf16 v[30:33], v[134:137], v[220:223], v[30:33]
	v_mfma_f32_16x16x32_bf16 v[26:29], v[142:145], v[220:223], v[26:29]
	v_mfma_f32_16x16x32_bf16 v[14:17], v[134:137], v[228:231], v[14:17]
	v_mfma_f32_16x16x32_bf16 v[10:13], v[142:145], v[228:231], v[10:13]
	v_mfma_f32_16x16x32_bf16 v[54:57], v[176:179], v[200:203], v[54:57]
	v_mfma_f32_16x16x32_bf16 v[50:53], v[184:187], v[200:203], v[50:53]
	v_mfma_f32_16x16x32_bf16 v[38:41], v[176:179], v[208:211], v[38:41]
	v_mfma_f32_16x16x32_bf16 v[34:37], v[184:187], v[208:211], v[34:37]
	v_mfma_f32_16x16x32_bf16 v[22:25], v[176:179], v[216:219], v[22:25]
	v_mfma_f32_16x16x32_bf16 v[18:21], v[184:187], v[216:219], v[18:21]
	v_mfma_f32_16x16x32_bf16 v[6:9], v[176:179], v[224:227], v[6:9]
	v_mfma_f32_16x16x32_bf16 v[2:5], v[184:187], v[224:227], v[2:5]
	v_mfma_f32_16x16x32_bf16 v[54:57], v[180:183], v[204:207], v[54:57]
	v_mfma_f32_16x16x32_bf16 v[50:53], v[188:191], v[204:207], v[50:53]
	v_mfma_f32_16x16x32_bf16 v[38:41], v[180:183], v[212:215], v[38:41]
	v_mfma_f32_16x16x32_bf16 v[34:37], v[188:191], v[212:215], v[34:37]
	v_mfma_f32_16x16x32_bf16 v[22:25], v[180:183], v[220:223], v[22:25]
	v_mfma_f32_16x16x32_bf16 v[18:21], v[188:191], v[220:223], v[18:21]
	v_mfma_f32_16x16x32_bf16 v[6:9], v[180:183], v[228:231], v[6:9]
	v_mfma_f32_16x16x32_bf16 v[2:5], v[188:191], v[228:231], v[2:5]
	s_barrier
	s_add_i32 s43, s43, 2
	s_add_u32 s12, s12, 0x100
	s_addc_u32 s13, s13, 0
	s_add_u32 s30, s30, 0x100
	s_addc_u32 s42, s42, 0
	s_cmp_gt_u32 s43, 13
	s_cbranch_scc0 .LBB0_1093
	s_and_b64 vcc, exec, s[50:51]
	s_cbranch_vccz .LBB0_1096
	s_barrier

; #define PG8_STAGE(bufoff, gbase, voff) do { _Pragma("unroll") for (int _i = 0; _i < 2; ++_i) \
;         __builtin_amdgcn_global_load_lds((const unsigned*)((const char*)(gbase) + (voff)[_i]), (PG8_LAS unsigned*)(lds + (bufoff) + ldsw + _i * 8192), 16, 0, 0); } while (0)
; #define PG8_LDA(dst, b, h) do { _Pragma("unroll") for (int m = 0; m < 4; ++m) _Pragma("unroll") for (int k = 0; k < 2; ++k) dst[m][k] = *(const PG8_LAS bf16x8*)(lds + PG8_SA(b, h) + aoff + m * 2048 + k * 1024); } while (0)
; #define PG8_LDB(dst, b, h) do { _Pragma("unroll") for (int n = 0; n < 2; ++n) _Pragma("unroll") for (int k = 0; k < 2; ++k) dst[n][k] = *(const PG8_LAS bf16x8*)(lds + PG8_SB(b, h) + boff + n * 2048 + k * 1024); } while (0)
; #define PG8_MMA(ai, bj, At, Bt) do { __builtin_amdgcn_s_setprio(1); _Pragma("unroll") for (int m = 0; m < 4; ++m) _Pragma("unroll") for (int n = 0; n < 2; ++n) _Pragma("unroll") for (int k = 0; k < 2; ++k) \
;         acc[ai][bj][m][n] = __builtin_amdgcn_mfma_f32_16x16x32_bf16(Bt[n][k], At[m][k], acc[ai][bj][m][n], 0, 0, 0); __builtin_amdgcn_s_setprio(0); } while (0)
; #define PG8_WAIT_V(n) asm volatile("s_waitcnt vmcnt(" #n ")" ::: "memory")
; #define PG8_WAIT_L(n) asm volatile("s_waitcnt lgkmcnt(" #n ")" ::: "memory")
; #define PG8_BAR __builtin_amdgcn_s_barrier()
; #define PG8_SCHED __builtin_amdgcn_sched_barrier(0)
; template <class Epi, class Sched, bool ALIGN_EPI = false, bool SP2 = false, bool PAIR_ACC = false>
; __device__ __forceinline__ void gemm_phase(PG8_LAS unsigned char* lds, const Gemm g, const Sched& S, const Epi& E) {
;     ...
;             const bool last = (t == nt - 2);
;             const char* a1 = cA + (size_t)(t + 1) * kstep;
;             const char* a2 = last ? nA : cA + (size_t)(t + 2) * kstep; const char* b2 = last ? nB : cB + (size_t)(t + 2) * kstep;
;             const char* a3 = a2 + kstep; const char* b3 = b2 + kstep;
;             if (last && has_next) S.a_ready(nxt);
;             if constexpr (SP2) {
;             PG8_LDB(B0, 0, 0); PG8_LDB(B1, 0, 1); PG8_SCHED; PG8_LDA(At, 0, 0); PG8_STAGE(PG8_SA(1, 1), a1 + hstep, voffA);
;             PG8_WAIT_V(8); PG8_WAIT_L(0); PG8_BAR; PG8_MMA(0, 0, At, B0); PG8_MMA(0, 1, At, B1); PG8_BAR; PG8_SCHED;
.LBB0_1488:
	v_add_u32_e32 v142, s51, v199
	v_add_u32_e32 v166, s52, v199
	ds_read_b128 v[130:133], v142
	ds_read_b128 v[134:137], v142 offset:1024
	ds_read_b128 v[138:141], v142 offset:2048
	ds_read_b128 v[142:145], v142 offset:3072
	ds_read_b128 v[146:149], v166
	ds_read_b128 v[150:153], v166 offset:1024
	ds_read_b128 v[154:157], v166 offset:2048
	ds_read_b128 v[176:179], v166 offset:3072
	s_add_u32 s46, s8, 0xfffc0080
	s_addc_u32 s47, s9, -1
	s_cmp_eq_u32 s54, 12
	s_cselect_b32 s49, s31, s47
	s_cselect_b32 s48, s30, s46
	s_cselect_b32 s47, s23, s53
	s_cselect_b32 s46, s29, s41
	v_lshl_add_u64 v[196:197], s[8:9], 0, v[168:169]
	s_add_i32 m0, s35, 0xc000
	ds_read_b128 v[180:183], v201
	ds_read_b128 v[184:187], v201 offset:1024
	ds_read_b128 v[188:191], v201 offset:2048
	ds_read_b128 v[192:195], v201 offset:3072
	ds_read_b128 v[202:205], v201 offset:4096
	ds_read_b128 v[206:209], v201 offset:5120
	ds_read_b128 v[210:213], v201 offset:6144
	ds_read_b128 v[214:217], v201 offset:7168
	global_load_lds_dwordx4 v[196:197], off
	v_lshl_add_u64 v[196:197], s[8:9], 0, v[170:171]
	s_add_i32 m0, s35, 0xe000
	s_nop 0
	global_load_lds_dwordx4 v[196:197], off
	s_waitcnt vmcnt(8)
	s_waitcnt lgkmcnt(0)
	s_barrier
	v_mfma_f32_16x16x32_bf16 v[126:129], v[130:133], v[180:183], v[126:129]
	v_mfma_f32_16x16x32_bf16 v[122:125], v[138:141], v[180:183], v[122:125]
	v_mfma_f32_16x16x32_bf16 v[118:121], v[130:133], v[188:191], v[118:121]
	v_mfma_f32_16x16x32_bf16 v[114:117], v[138:141], v[188:191], v[114:117]
	v_mfma_f32_16x16x32_bf16 v[110:113], v[130:133], v[202:205], v[110:113]
	v_mfma_f32_16x16x32_bf16 v[106:109], v[138:141], v[202:205], v[106:109]
	v_mfma_f32_16x16x32_bf16 v[102:105], v[130:133], v[210:213], v[102:105]
	v_mfma_f32_16x16x32_bf16 v[98:101], v[138:141], v[210:213], v[98:101]
	v_mfma_f32_16x16x32_bf16 v[126:129], v[134:137], v[184:187], v[126:129]
	v_mfma_f32_16x16x32_bf16 v[122:125], v[142:145], v[184:187], v[122:125]
	v_mfma_f32_16x16x32_bf16 v[118:121], v[134:137], v[192:195], v[118:121]
	v_mfma_f32_16x16x32_bf16 v[114:117], v[142:145], v[192:195], v[114:117]
	v_mfma_f32_16x16x32_bf16 v[110:113], v[134:137], v[206:209], v[110:113]
	v_mfma_f32_16x16x32_bf16 v[106:109], v[142:145], v[206:209], v[106:109]
	v_mfma_f32_16x16x32_bf16 v[102:105], v[134:137], v[214:217], v[102:105]
	v_mfma_f32_16x16x32_bf16 v[98:101], v[142:145], v[214:217], v[98:101]
	v_mfma_f32_16x16x32_bf16 v[94:97], v[146:149], v[180:183], v[94:97]
	v_mfma_f32_16x16x32_bf16 v[90:93], v[154:157], v[180:183], v[90:93]
	v_mfma_f32_16x16x32_bf16 v[86:89], v[146:149], v[188:191], v[86:89]
	v_mfma_f32_16x16x32_bf16 v[82:85], v[154:157], v[188:191], v[82:85]
	v_mfma_f32_16x16x32_bf16 v[78:81], v[146:149], v[202:205], v[78:81]
	v_mfma_f32_16x16x32_bf16 v[74:77], v[154:157], v[202:205], v[74:77]
	v_mfma_f32_16x16x32_bf16 v[70:73], v[146:149], v[210:213], v[70:73]
	v_mfma_f32_16x16x32_bf16 v[66:69], v[154:157], v[210:213], v[66:69]
	v_mfma_f32_16x16x32_bf16 v[94:97], v[150:153], v[184:187], v[94:97]
	v_mfma_f32_16x16x32_bf16 v[90:93], v[176:179], v[184:187], v[90:93]
	v_mfma_f32_16x16x32_bf16 v[86:89], v[150:153], v[192:195], v[86:89]
	v_mfma_f32_16x16x32_bf16 v[82:85], v[176:179], v[192:195], v[82:85]
	v_mfma_f32_16x16x32_bf16 v[78:81], v[150:153], v[206:209], v[78:81]
	v_mfma_f32_16x16x32_bf16 v[74:77], v[176:179], v[206:209], v[74:77]
	v_mfma_f32_16x16x32_bf16 v[70:73], v[150:153], v[214:217], v[70:73]
	v_mfma_f32_16x16x32_bf16 v[66:69], v[176:179], v[214:217], v[66:69]
	s_barrier
	s_add_i32 s55, s51, s34
	v_lshl_add_u64 v[196:197], s[46:47], 0, v[160:161]
	s_mov_b32 m0, s55
	ds_read_b128 v[180:183], v201 offset:16384
	ds_read_b128 v[184:187], v201 offset:17408
	ds_read_b128 v[188:191], v201 offset:18432
	ds_read_b128 v[192:195], v201 offset:19456
	ds_read_b128 v[202:205], v201 offset:20480
	ds_read_b128 v[206:209], v201 offset:21504
	ds_read_b128 v[210:213], v201 offset:22528
	ds_read_b128 v[214:217], v201 offset:23552
	global_load_lds_dwordx4 v[196:197], off
	s_add_i32 m0, s55, 0x2000
	s_add_u32 s56, s46, 0x40000
	v_lshl_add_u64 v[218:219], s[46:47], 0, v[164:165]
	s_addc_u32 s57, s47, 0
	s_add_i32 s55, s52, s34
	global_load_lds_dwordx4 v[218:219], off
	v_lshl_add_u64 v[220:221], s[56:57], 0, v[160:161]
	s_mov_b32 m0, s55
	v_lshl_add_u64 v[222:223], s[48:49], 0, v[162:163]
	global_load_lds_dwordx4 v[220:221], off
	v_lshl_add_u64 v[220:221], s[56:57], 0, v[164:165]
	s_add_i32 m0, s55, 0x2000
	s_nop 0
	global_load_lds_dwordx4 v[220:221], off
	v_lshl_add_u64 v[220:221], s[48:49], 0, v[158:159]
	s_mov_b32 m0, s35
	s_nop 0
	global_load_lds_dwordx4 v[220:221], off
	s_mov_b32 m0, s36
	s_nop 0
	global_load_lds_dwordx4 v[222:223], off
	s_waitcnt vmcnt(8)
	s_waitcnt lgkmcnt(0)
	s_barrier
; #define PG8_STAGE(bufoff, gbase, voff) do { _Pragma("unroll") for (int _i = 0; _i < 2; ++_i) \
;         __builtin_amdgcn_global_load_lds((const unsigned*)((const char*)(gbase) + (voff)[_i]), (PG8_LAS unsigned*)(lds + (bufoff) + ldsw + _i * 8192), 16, 0, 0); } while (0)
; #define PG8_LDA(dst, b, h) do { _Pragma("unroll") for (int m = 0; m < 4; ++m) _Pragma("unroll") for (int k = 0; k < 2; ++k) dst[m][k] = *(const PG8_LAS bf16x8*)(lds + PG8_SA(b, h) + aoff + m * 2048 + k * 1024); } while (0)
; #define PG8_LDB(dst, b, h) do { _Pragma("unroll") for (int n = 0; n < 2; ++n) _Pragma("unroll") for (int k = 0; k < 2; ++k) dst[n][k] = *(const PG8_LAS bf16x8*)(lds + PG8_SB(b, h) + boff + n * 2048 + k * 1024); } while (0)
; #define PG8_MMA(ai, bj, At, Bt) do { __builtin_amdgcn_s_setprio(1); _Pragma("unroll") for (int m = 0; m < 4; ++m) _Pragma("unroll") for (int n = 0; n < 2; ++n) _Pragma("unroll") for (int k = 0; k < 2; ++k) \
;         acc[ai][bj][m][n] = __builtin_amdgcn_mfma_f32_16x16x32_bf16(Bt[n][k], At[m][k], acc[ai][bj][m][n], 0, 0, 0); __builtin_amdgcn_s_setprio(0); } while (0)
; #define PG8_WAIT_V(n) asm volatile("s_waitcnt vmcnt(" #n ")" ::: "memory")
; #define PG8_WAIT_L(n) asm volatile("s_waitcnt lgkmcnt(" #n ")" ::: "memory")
; #define PG8_BAR __builtin_amdgcn_s_barrier()
; #define PG8_SCHED __builtin_amdgcn_sched_barrier(0)
; template <class Epi, class Sched, bool ALIGN_EPI = false, bool SP2 = false, bool PAIR_ACC = false>
; __device__ __forceinline__ void gemm_phase(PG8_LAS unsigned char* lds, const Gemm g, const Sched& S, const Epi& E) {
;     ...
;             PG8_WAIT_V(8); PG8_WAIT_L(0); PG8_BAR; PG8_MMA(1, 0, At, B0); PG8_MMA(1, 1, At, B1); PG8_BAR; PG8_SCHED;
;             PG8_LDB(B0, 1, 0); PG8_LDB(B1, 1, 1); PG8_SCHED; PG8_LDA(At, 1, 0); PG8_STAGE(PG8_SA(0, 1), a2 + hstep, voffA);
;             PG8_WAIT_V(8); PG8_WAIT_L(0); PG8_BAR; PG8_MMA(0, 0, At, B0); PG8_MMA(0, 1, At, B1); PG8_BAR; PG8_SCHED;
	v_mfma_f32_16x16x32_bf16 v[62:65], v[130:133], v[180:183], v[62:65]
	v_mfma_f32_16x16x32_bf16 v[58:61], v[138:141], v[180:183], v[58:61]
	v_mfma_f32_16x16x32_bf16 v[54:57], v[130:133], v[188:191], v[54:57]
	v_mfma_f32_16x16x32_bf16 v[50:53], v[138:141], v[188:191], v[50:53]
	v_mfma_f32_16x16x32_bf16 v[46:49], v[130:133], v[202:205], v[46:49]
	v_mfma_f32_16x16x32_bf16 v[42:45], v[138:141], v[202:205], v[42:45]
	v_mfma_f32_16x16x32_bf16 v[38:41], v[130:133], v[210:213], v[38:41]
	v_mfma_f32_16x16x32_bf16 v[34:37], v[138:141], v[210:213], v[34:37]
	v_mfma_f32_16x16x32_bf16 v[62:65], v[134:137], v[184:187], v[62:65]
	v_mfma_f32_16x16x32_bf16 v[58:61], v[142:145], v[184:187], v[58:61]
	v_mfma_f32_16x16x32_bf16 v[54:57], v[134:137], v[192:195], v[54:57]
	v_mfma_f32_16x16x32_bf16 v[50:53], v[142:145], v[192:195], v[50:53]
	v_mfma_f32_16x16x32_bf16 v[46:49], v[134:137], v[206:209], v[46:49]
	v_mfma_f32_16x16x32_bf16 v[42:45], v[142:145], v[206:209], v[42:45]
	v_mfma_f32_16x16x32_bf16 v[38:41], v[134:137], v[214:217], v[38:41]
	v_mfma_f32_16x16x32_bf16 v[34:37], v[142:145], v[214:217], v[34:37]
	v_mfma_f32_16x16x32_bf16 v[30:33], v[146:149], v[180:183], v[30:33]
	v_mfma_f32_16x16x32_bf16 v[26:29], v[154:157], v[180:183], v[26:29]
	v_mfma_f32_16x16x32_bf16 v[22:25], v[146:149], v[188:191], v[22:25]
	v_mfma_f32_16x16x32_bf16 v[18:21], v[154:157], v[188:191], v[18:21]
	v_mfma_f32_16x16x32_bf16 v[14:17], v[146:149], v[202:205], v[14:17]
	v_mfma_f32_16x16x32_bf16 v[10:13], v[154:157], v[202:205], v[10:13]
	v_mfma_f32_16x16x32_bf16 v[6:9], v[146:149], v[210:213], v[6:9]
	v_mfma_f32_16x16x32_bf16 v[2:5], v[154:157], v[210:213], v[2:5]
	v_mfma_f32_16x16x32_bf16 v[30:33], v[150:153], v[184:187], v[30:33]
	v_mfma_f32_16x16x32_bf16 v[26:29], v[176:179], v[184:187], v[26:29]
	v_mfma_f32_16x16x32_bf16 v[22:25], v[150:153], v[192:195], v[22:25]
	v_mfma_f32_16x16x32_bf16 v[18:21], v[176:179], v[192:195], v[18:21]
	v_mfma_f32_16x16x32_bf16 v[14:17], v[150:153], v[206:209], v[14:17]
	v_mfma_f32_16x16x32_bf16 v[10:13], v[176:179], v[206:209], v[10:13]
	v_mfma_f32_16x16x32_bf16 v[6:9], v[150:153], v[214:217], v[6:9]
	v_mfma_f32_16x16x32_bf16 v[2:5], v[176:179], v[214:217], v[2:5]
	s_barrier
	s_add_i32 s55, 0, 0x18000
	s_add_i32 s56, 0, 0x1c000
	v_add_u32_e32 v142, s55, v199
	v_add_u32_e32 v166, s56, v199
	ds_read_b128 v[130:133], v142
	ds_read_b128 v[134:137], v142 offset:1024
	ds_read_b128 v[138:141], v142 offset:2048
	ds_read_b128 v[142:145], v142 offset:3072
	ds_read_b128 v[146:149], v166
	ds_read_b128 v[150:153], v166 offset:1024
	ds_read_b128 v[154:157], v166 offset:2048
	ds_read_b128 v[176:179], v166 offset:3072
	s_add_u32 s48, s48, 0x40000
	s_addc_u32 s49, s49, 0
	s_mov_b32 m0, s37
	v_lshl_add_u64 v[224:225], s[48:49], 0, v[158:159]
	ds_read_b128 v[180:183], v201 offset:32768
	ds_read_b128 v[184:187], v201 offset:33792
	ds_read_b128 v[188:191], v201 offset:34816
	ds_read_b128 v[192:195], v201 offset:35840
	ds_read_b128 v[202:205], v201 offset:36864
	ds_read_b128 v[206:209], v201 offset:37888
	ds_read_b128 v[210:213], v201 offset:38912
	ds_read_b128 v[214:217], v201 offset:39936
	global_load_lds_dwordx4 v[224:225], off
	v_lshl_add_u64 v[224:225], s[48:49], 0, v[162:163]
	s_mov_b32 m0, s42
	s_nop 0
	global_load_lds_dwordx4 v[224:225], off
	s_waitcnt vmcnt(8)
	s_waitcnt lgkmcnt(0)
	s_barrier
	v_mfma_f32_16x16x32_bf16 v[126:129], v[130:133], v[180:183], v[126:129]
	v_mfma_f32_16x16x32_bf16 v[122:125], v[138:141], v[180:183], v[122:125]
	v_mfma_f32_16x16x32_bf16 v[118:121], v[130:133], v[188:191], v[118:121]
	v_mfma_f32_16x16x32_bf16 v[114:117], v[138:141], v[188:191], v[114:117]
	v_mfma_f32_16x16x32_bf16 v[110:113], v[130:133], v[202:205], v[110:113]
	v_mfma_f32_16x16x32_bf16 v[106:109], v[138:141], v[202:205], v[106:109]
	v_mfma_f32_16x16x32_bf16 v[102:105], v[130:133], v[210:213], v[102:105]
	v_mfma_f32_16x16x32_bf16 v[98:101], v[138:141], v[210:213], v[98:101]
	v_mfma_f32_16x16x32_bf16 v[126:129], v[134:137], v[184:187], v[126:129]
	v_mfma_f32_16x16x32_bf16 v[122:125], v[142:145], v[184:187], v[122:125]
	v_mfma_f32_16x16x32_bf16 v[118:121], v[134:137], v[192:195], v[118:121]
	v_mfma_f32_16x16x32_bf16 v[114:117], v[142:145], v[192:195], v[114:117]
	v_mfma_f32_16x16x32_bf16 v[110:113], v[134:137], v[206:209], v[110:113]
	v_mfma_f32_16x16x32_bf16 v[106:109], v[142:145], v[206:209], v[106:109]
	v_mfma_f32_16x16x32_bf16 v[102:105], v[134:137], v[214:217], v[102:105]
	v_mfma_f32_16x16x32_bf16 v[98:101], v[142:145], v[214:217], v[98:101]
	v_mfma_f32_16x16x32_bf16 v[94:97], v[146:149], v[180:183], v[94:97]
	v_mfma_f32_16x16x32_bf16 v[90:93], v[154:157], v[180:183], v[90:93]
	v_mfma_f32_16x16x32_bf16 v[86:89], v[146:149], v[188:191], v[86:89]
	v_mfma_f32_16x16x32_bf16 v[82:85], v[154:157], v[188:191], v[82:85]
	v_mfma_f32_16x16x32_bf16 v[78:81], v[146:149], v[202:205], v[78:81]
	v_mfma_f32_16x16x32_bf16 v[74:77], v[154:157], v[202:205], v[74:77]
	v_mfma_f32_16x16x32_bf16 v[70:73], v[146:149], v[210:213], v[70:73]
	v_mfma_f32_16x16x32_bf16 v[66:69], v[154:157], v[210:213], v[66:69]
	v_mfma_f32_16x16x32_bf16 v[94:97], v[150:153], v[184:187], v[94:97]
	v_mfma_f32_16x16x32_bf16 v[90:93], v[176:179], v[184:187], v[90:93]
	v_mfma_f32_16x16x32_bf16 v[86:89], v[150:153], v[192:195], v[86:89]
	v_mfma_f32_16x16x32_bf16 v[82:85], v[176:179], v[192:195], v[82:85]
	v_mfma_f32_16x16x32_bf16 v[78:81], v[150:153], v[206:209], v[78:81]
	v_mfma_f32_16x16x32_bf16 v[74:77], v[176:179], v[206:209], v[74:77]
	v_mfma_f32_16x16x32_bf16 v[70:73], v[150:153], v[214:217], v[70:73]
	v_mfma_f32_16x16x32_bf16 v[66:69], v[176:179], v[214:217], v[66:69]
	s_barrier
; #define PG8_STAGE(bufoff, gbase, voff) do { _Pragma("unroll") for (int _i = 0; _i < 2; ++_i) \
;         __builtin_amdgcn_global_load_lds((const unsigned*)((const char*)(gbase) + (voff)[_i]), (PG8_LAS unsigned*)(lds + (bufoff) + ldsw + _i * 8192), 16, 0, 0); } while (0)
; #define PG8_LDA(dst, b, h) do { _Pragma("unroll") for (int m = 0; m < 4; ++m) _Pragma("unroll") for (int k = 0; k < 2; ++k) dst[m][k] = *(const PG8_LAS bf16x8*)(lds + PG8_SA(b, h) + aoff + m * 2048 + k * 1024); } while (0)
; #define PG8_MMA(ai, bj, At, Bt) do { __builtin_amdgcn_s_setprio(1); _Pragma("unroll") for (int m = 0; m < 4; ++m) _Pragma("unroll") for (int n = 0; n < 2; ++n) _Pragma("unroll") for (int k = 0; k < 2; ++k) \
;         acc[ai][bj][m][n] = __builtin_amdgcn_mfma_f32_16x16x32_bf16(Bt[n][k], At[m][k], acc[ai][bj][m][n], 0, 0, 0); __builtin_amdgcn_s_setprio(0); } while (0)
; #define PG8_WAIT_V(n) asm volatile("s_waitcnt vmcnt(" #n ")" ::: "memory")
; #define PG8_WAIT_L(n) asm volatile("s_waitcnt lgkmcnt(" #n ")" ::: "memory")
; #define PG8_BAR __builtin_amdgcn_s_barrier()
; #define PG8_SCHED __builtin_amdgcn_sched_barrier(0)
; template <class Epi, class Sched, bool ALIGN_EPI = false, bool SP2 = false, bool PAIR_ACC = false>
; __device__ __forceinline__ void gemm_phase(PG8_LAS unsigned char* lds, const Gemm g, const Sched& S, const Epi& E) {
;     ...
;             PG8_LDA(At, 1, 1); PG8_STAGE(PG8_SB(1, 0), b3, voffB); PG8_STAGE(PG8_SB(1, 1), b3 + hstep, voffB); PG8_STAGE(PG8_SA(1, 0), a3, voffA);
;             PG8_WAIT_V(8); PG8_WAIT_L(0); PG8_BAR; PG8_MMA(1, 0, At, B0); PG8_MMA(1, 1, At, B1); PG8_BAR; PG8_SCHED;
;     ...
;         if constexpr (ALIGN_EPI) { if (wr == 0) PG8_BAR; }
	s_add_i32 s48, s55, s34
	v_lshl_add_u64 v[196:197], v[196:197], 0, s[18:19]
	s_mov_b32 m0, s48
	ds_read_b128 v[180:183], v201 offset:49152
	ds_read_b128 v[184:187], v201 offset:50176
	ds_read_b128 v[188:191], v201 offset:51200
	ds_read_b128 v[192:195], v201 offset:52224
	ds_read_b128 v[202:205], v201 offset:53248
	ds_read_b128 v[206:209], v201 offset:54272
	ds_read_b128 v[210:213], v201 offset:55296
	ds_read_b128 v[214:217], v201 offset:56320
	global_load_lds_dwordx4 v[196:197], off
	s_add_i32 m0, s48, 0x2000
	s_add_u32 s46, s46, 0x40080
	v_lshl_add_u64 v[196:197], v[218:219], 0, s[18:19]
	s_addc_u32 s47, s47, 0
	s_add_i32 s48, s56, s34
	global_load_lds_dwordx4 v[196:197], off
	v_lshl_add_u64 v[196:197], s[46:47], 0, v[160:161]
	s_mov_b32 m0, s48
	s_nop 0
	global_load_lds_dwordx4 v[196:197], off
	v_lshl_add_u64 v[196:197], s[46:47], 0, v[164:165]
	s_add_i32 m0, s48, 0x2000
	s_nop 0
	global_load_lds_dwordx4 v[196:197], off
	v_lshl_add_u64 v[196:197], v[220:221], 0, s[18:19]
	s_mov_b32 m0, s45
	s_nop 0
	global_load_lds_dwordx4 v[196:197], off
	v_lshl_add_u64 v[196:197], v[222:223], 0, s[18:19]
	s_mov_b32 m0, s50
	s_nop 0
	global_load_lds_dwordx4 v[196:197], off
	s_waitcnt vmcnt(8)
	s_waitcnt lgkmcnt(0)
	s_barrier
	v_mfma_f32_16x16x32_bf16 v[62:65], v[130:133], v[180:183], v[62:65]
	v_mfma_f32_16x16x32_bf16 v[58:61], v[138:141], v[180:183], v[58:61]
	v_mfma_f32_16x16x32_bf16 v[54:57], v[130:133], v[188:191], v[54:57]
	v_mfma_f32_16x16x32_bf16 v[50:53], v[138:141], v[188:191], v[50:53]
	v_mfma_f32_16x16x32_bf16 v[46:49], v[130:133], v[202:205], v[46:49]
	v_mfma_f32_16x16x32_bf16 v[42:45], v[138:141], v[202:205], v[42:45]
	v_mfma_f32_16x16x32_bf16 v[38:41], v[130:133], v[210:213], v[38:41]
	v_mfma_f32_16x16x32_bf16 v[34:37], v[138:141], v[210:213], v[34:37]
	v_mfma_f32_16x16x32_bf16 v[62:65], v[134:137], v[184:187], v[62:65]
	v_mfma_f32_16x16x32_bf16 v[58:61], v[142:145], v[184:187], v[58:61]
	v_mfma_f32_16x16x32_bf16 v[54:57], v[134:137], v[192:195], v[54:57]
	v_mfma_f32_16x16x32_bf16 v[50:53], v[142:145], v[192:195], v[50:53]
	v_mfma_f32_16x16x32_bf16 v[46:49], v[134:137], v[206:209], v[46:49]
	v_mfma_f32_16x16x32_bf16 v[42:45], v[142:145], v[206:209], v[42:45]
	v_mfma_f32_16x16x32_bf16 v[38:41], v[134:137], v[214:217], v[38:41]
	v_mfma_f32_16x16x32_bf16 v[34:37], v[142:145], v[214:217], v[34:37]
	v_mfma_f32_16x16x32_bf16 v[30:33], v[146:149], v[180:183], v[30:33]
	v_mfma_f32_16x16x32_bf16 v[26:29], v[154:157], v[180:183], v[26:29]
	v_mfma_f32_16x16x32_bf16 v[22:25], v[146:149], v[188:191], v[22:25]
	v_mfma_f32_16x16x32_bf16 v[18:21], v[154:157], v[188:191], v[18:21]
	v_mfma_f32_16x16x32_bf16 v[14:17], v[146:149], v[202:205], v[14:17]
	v_mfma_f32_16x16x32_bf16 v[10:13], v[154:157], v[202:205], v[10:13]
	v_mfma_f32_16x16x32_bf16 v[6:9], v[146:149], v[210:213], v[6:9]
	v_mfma_f32_16x16x32_bf16 v[2:5], v[154:157], v[210:213], v[2:5]
	v_mfma_f32_16x16x32_bf16 v[30:33], v[150:153], v[184:187], v[30:33]
	v_mfma_f32_16x16x32_bf16 v[26:29], v[176:179], v[184:187], v[26:29]
	v_mfma_f32_16x16x32_bf16 v[22:25], v[150:153], v[192:195], v[22:25]
	v_mfma_f32_16x16x32_bf16 v[18:21], v[176:179], v[192:195], v[18:21]
	v_mfma_f32_16x16x32_bf16 v[14:17], v[150:153], v[206:209], v[14:17]
	v_mfma_f32_16x16x32_bf16 v[10:13], v[176:179], v[206:209], v[10:13]
	v_mfma_f32_16x16x32_bf16 v[6:9], v[150:153], v[214:217], v[6:9]
	v_mfma_f32_16x16x32_bf16 v[2:5], v[176:179], v[214:217], v[2:5]
	s_barrier
	s_add_i32 s54, s54, 2
	s_add_u32 s8, s8, 0x100
	s_addc_u32 s9, s9, 0
	s_add_u32 s41, s41, 0x100
	s_addc_u32 s53, s53, 0
	s_cmp_gt_u32 s54, 13
	s_cbranch_scc0 .LBB0_1488
	s_and_b64 vcc, exec, s[20:21]
	s_cbranch_vccz .LBB0_1491
	s_barrier

; #define PG8_STAGE(bufoff, gbase, voff) do { _Pragma("unroll") for (int _i = 0; _i < 2; ++_i) \
;         __builtin_amdgcn_global_load_lds((const unsigned*)((const char*)(gbase) + (voff)[_i]), (PG8_LAS unsigned*)(lds + (bufoff) + ldsw + _i * 8192), 16, 0, 0); } while (0)
; #define PG8_LDA(dst, b, h) do { _Pragma("unroll") for (int m = 0; m < 4; ++m) _Pragma("unroll") for (int k = 0; k < 2; ++k) dst[m][k] = *(const PG8_LAS bf16x8*)(lds + PG8_SA(b, h) + aoff + m * 2048 + k * 1024); } while (0)
; #define PG8_LDB(dst, b, h) do { _Pragma("unroll") for (int n = 0; n < 2; ++n) _Pragma("unroll") for (int k = 0; k < 2; ++k) dst[n][k] = *(const PG8_LAS bf16x8*)(lds + PG8_SB(b, h) + boff + n * 2048 + k * 1024); } while (0)
; #define PG8_MMA(ai, bj, At, Bt) do { __builtin_amdgcn_s_setprio(1); _Pragma("unroll") for (int m = 0; m < 4; ++m) _Pragma("unroll") for (int n = 0; n < 2; ++n) _Pragma("unroll") for (int k = 0; k < 2; ++k) \
;         acc[ai][bj][m][n] = __builtin_amdgcn_mfma_f32_16x16x32_bf16(Bt[n][k], At[m][k], acc[ai][bj][m][n], 0, 0, 0); __builtin_amdgcn_s_setprio(0); } while (0)
; #define PG8_WAIT_V(n) asm volatile("s_waitcnt vmcnt(" #n ")" ::: "memory")
; #define PG8_WAIT_L(n) asm volatile("s_waitcnt lgkmcnt(" #n ")" ::: "memory")
; template <class Epi, class Sched, bool ALIGN_EPI = false, bool SP2 = false, bool PAIR_ACC = false>
; __device__ __forceinline__ void gemm_phase(PG8_LAS unsigned char* lds, const Gemm g, const Sched& S, const Epi& E) {
;     ...
;             const bool last = (t == nt - 2);
;             const char* a1 = cA + (size_t)(t + 1) * kstep;
;             const char* a2 = last ? nA : cA + (size_t)(t + 2) * kstep; const char* b2 = last ? nB : cB + (size_t)(t + 2) * kstep;
;             const char* a3 = a2 + kstep; const char* b3 = b2 + kstep;
;             if (last && has_next) S.a_ready(nxt);
;             if constexpr (SP2) {
;             PG8_LDB(B0, 0, 0); PG8_LDB(B1, 0, 1); PG8_SCHED; PG8_LDA(At, 0, 0); PG8_STAGE(PG8_SA(1, 1), a1 + hstep, voffA);
;             PG8_WAIT_V(8); PG8_WAIT_L(0); PG8_BAR; PG8_MMA(0, 0, At, B0); PG8_MMA(0, 1, At, B1); PG8_BAR; PG8_SCHED;
;             PG8_LDA(At, 0, 1); PG8_STAGE(PG8_SB(0, 0), b2, voffB); PG8_STAGE(PG8_SB(0, 1), b2 + hstep, voffB); PG8_STAGE(PG8_SA(0, 0), a2, voffA);
;             PG8_WAIT_V(8); PG8_WAIT_L(0); PG8_BAR; PG8_MMA(1, 0, At, B0); PG8_MMA(1, 1, At, B1); PG8_BAR; PG8_SCHED;
.LBB0_1630:
	v_add_u32_e32 v164, s57, v150
	ds_read_b128 v[152:155], v164
	ds_read_b128 v[156:159], v164 offset:1024
	ds_read_b128 v[160:163], v164 offset:2048
	ds_read_b128 v[170:173], v164 offset:3072
	v_add_u32_e32 v164, s58, v150
	s_add_u32 s46, s20, s44
	ds_read_b128 v[174:177], v164
	ds_read_b128 v[178:181], v164 offset:1024
	ds_read_b128 v[182:185], v164 offset:2048
	ds_read_b128 v[186:189], v164 offset:3072
	s_addc_u32 s47, s21, s45
	s_add_u32 s46, s46, 0x100
	s_addc_u32 s47, s47, 0
	s_add_u32 s63, s42, s44
	s_addc_u32 s64, s43, s45
	s_cmpk_eq_i32 s44, 0x700
	s_cselect_b32 s49, s31, s47
	s_cselect_b32 s48, s60, s46
	s_cselect_b32 s47, s29, s64
	s_cselect_b32 s46, s61, s63
	v_lshl_add_u64 v[164:165], v[146:147], 0, s[44:45]
	s_add_i32 m0, s50, 0xc000
	ds_read_b128 v[190:193], v151
	ds_read_b128 v[194:197], v151 offset:1024
	ds_read_b128 v[198:201], v151 offset:2048
	ds_read_b128 v[202:205], v151 offset:3072
	ds_read_b128 v[206:209], v151 offset:4096
	ds_read_b128 v[210:213], v151 offset:5120
	ds_read_b128 v[214:217], v151 offset:6144
	ds_read_b128 v[218:221], v151 offset:7168
	global_load_lds_dwordx4 v[164:165], off
	v_lshl_add_u64 v[164:165], v[148:149], 0, s[44:45]
	s_add_i32 m0, s50, 0xe000
	s_nop 0
	global_load_lds_dwordx4 v[164:165], off
	s_waitcnt vmcnt(8)
	s_waitcnt lgkmcnt(0)
	s_barrier
	v_mfma_f32_16x16x32_bf16 v[58:61], v[152:155], v[190:193], v[58:61]
	v_mfma_f32_16x16x32_bf16 v[62:65], v[160:163], v[190:193], v[62:65]
	v_mfma_f32_16x16x32_bf16 v[78:81], v[152:155], v[198:201], v[78:81]
	v_mfma_f32_16x16x32_bf16 v[70:73], v[160:163], v[198:201], v[70:73]
	v_mfma_f32_16x16x32_bf16 v[98:101], v[152:155], v[206:209], v[98:101]
	v_mfma_f32_16x16x32_bf16 v[90:93], v[160:163], v[206:209], v[90:93]
	v_mfma_f32_16x16x32_bf16 v[114:117], v[152:155], v[214:217], v[114:117]
	v_mfma_f32_16x16x32_bf16 v[106:109], v[160:163], v[214:217], v[106:109]
	v_mfma_f32_16x16x32_bf16 v[58:61], v[156:159], v[194:197], v[58:61]
	v_mfma_f32_16x16x32_bf16 v[62:65], v[170:173], v[194:197], v[62:65]
	v_mfma_f32_16x16x32_bf16 v[78:81], v[156:159], v[202:205], v[78:81]
	v_mfma_f32_16x16x32_bf16 v[70:73], v[170:173], v[202:205], v[70:73]
	v_mfma_f32_16x16x32_bf16 v[98:101], v[156:159], v[210:213], v[98:101]
	v_mfma_f32_16x16x32_bf16 v[90:93], v[170:173], v[210:213], v[90:93]
	v_mfma_f32_16x16x32_bf16 v[114:117], v[156:159], v[218:221], v[114:117]
	v_mfma_f32_16x16x32_bf16 v[106:109], v[170:173], v[218:221], v[106:109]
	v_mfma_f32_16x16x32_bf16 v[54:57], v[174:177], v[190:193], v[54:57]
	v_mfma_f32_16x16x32_bf16 v[46:49], v[182:185], v[190:193], v[46:49]
	v_mfma_f32_16x16x32_bf16 v[50:53], v[174:177], v[198:201], v[50:53]
	v_mfma_f32_16x16x32_bf16 v[42:45], v[182:185], v[198:201], v[42:45]
	v_mfma_f32_16x16x32_bf16 v[74:77], v[174:177], v[206:209], v[74:77]
	v_mfma_f32_16x16x32_bf16 v[66:69], v[182:185], v[206:209], v[66:69]
	v_mfma_f32_16x16x32_bf16 v[102:105], v[174:177], v[214:217], v[102:105]
	v_mfma_f32_16x16x32_bf16 v[94:97], v[182:185], v[214:217], v[94:97]
	v_mfma_f32_16x16x32_bf16 v[54:57], v[178:181], v[194:197], v[54:57]
	v_mfma_f32_16x16x32_bf16 v[46:49], v[186:189], v[194:197], v[46:49]
	v_mfma_f32_16x16x32_bf16 v[50:53], v[178:181], v[202:205], v[50:53]
	v_mfma_f32_16x16x32_bf16 v[42:45], v[186:189], v[202:205], v[42:45]
	v_mfma_f32_16x16x32_bf16 v[74:77], v[178:181], v[210:213], v[74:77]
	v_mfma_f32_16x16x32_bf16 v[66:69], v[186:189], v[210:213], v[66:69]
	v_mfma_f32_16x16x32_bf16 v[102:105], v[178:181], v[218:221], v[102:105]
	v_mfma_f32_16x16x32_bf16 v[94:97], v[186:189], v[218:221], v[94:97]
	s_barrier
	s_add_i32 s63, s57, s37
	v_lshl_add_u64 v[164:165], s[46:47], 0, v[132:133]
	s_mov_b32 m0, s63
	ds_read_b128 v[190:193], v151 offset:16384
	ds_read_b128 v[194:197], v151 offset:17408
	ds_read_b128 v[198:201], v151 offset:18432
	ds_read_b128 v[202:205], v151 offset:19456
	ds_read_b128 v[206:209], v151 offset:20480
	ds_read_b128 v[210:213], v151 offset:21504
	ds_read_b128 v[214:217], v151 offset:22528
	ds_read_b128 v[218:221], v151 offset:23552
	global_load_lds_dwordx4 v[164:165], off
	s_add_i32 m0, s63, 0x2000
	s_add_u32 s68, s46, 0x40000
	v_lshl_add_u64 v[222:223], s[46:47], 0, v[136:137]
	s_addc_u32 s69, s47, 0
	s_add_i32 s63, s58, s37
	global_load_lds_dwordx4 v[222:223], off
	v_lshl_add_u64 v[224:225], s[68:69], 0, v[132:133]
	s_mov_b32 m0, s63
	v_lshl_add_u64 v[226:227], s[48:49], 0, v[134:135]
	global_load_lds_dwordx4 v[224:225], off
	v_lshl_add_u64 v[224:225], s[68:69], 0, v[136:137]
	s_add_i32 m0, s63, 0x2000
	s_nop 0
	global_load_lds_dwordx4 v[224:225], off
	v_lshl_add_u64 v[224:225], s[48:49], 0, v[130:131]
	s_mov_b32 m0, s50
	s_nop 0
	global_load_lds_dwordx4 v[224:225], off
	s_mov_b32 m0, s51
	s_nop 0
	global_load_lds_dwordx4 v[226:227], off
	s_waitcnt vmcnt(8)
	s_waitcnt lgkmcnt(0)
	s_barrier
; #define PG8_STAGE(bufoff, gbase, voff) do { _Pragma("unroll") for (int _i = 0; _i < 2; ++_i) \
;         __builtin_amdgcn_global_load_lds((const unsigned*)((const char*)(gbase) + (voff)[_i]), (PG8_LAS unsigned*)(lds + (bufoff) + ldsw + _i * 8192), 16, 0, 0); } while (0)
; #define PG8_LDA(dst, b, h) do { _Pragma("unroll") for (int m = 0; m < 4; ++m) _Pragma("unroll") for (int k = 0; k < 2; ++k) dst[m][k] = *(const PG8_LAS bf16x8*)(lds + PG8_SA(b, h) + aoff + m * 2048 + k * 1024); } while (0)
; #define PG8_LDB(dst, b, h) do { _Pragma("unroll") for (int n = 0; n < 2; ++n) _Pragma("unroll") for (int k = 0; k < 2; ++k) dst[n][k] = *(const PG8_LAS bf16x8*)(lds + PG8_SB(b, h) + boff + n * 2048 + k * 1024); } while (0)
; #define PG8_MMA(ai, bj, At, Bt) do { __builtin_amdgcn_s_setprio(1); _Pragma("unroll") for (int m = 0; m < 4; ++m) _Pragma("unroll") for (int n = 0; n < 2; ++n) _Pragma("unroll") for (int k = 0; k < 2; ++k) \
;         acc[ai][bj][m][n] = __builtin_amdgcn_mfma_f32_16x16x32_bf16(Bt[n][k], At[m][k], acc[ai][bj][m][n], 0, 0, 0); __builtin_amdgcn_s_setprio(0); } while (0)
; #define PG8_WAIT_V(n) asm volatile("s_waitcnt vmcnt(" #n ")" ::: "memory")
; #define PG8_WAIT_L(n) asm volatile("s_waitcnt lgkmcnt(" #n ")" ::: "memory")
; #define PG8_BAR __builtin_amdgcn_s_barrier()
; #define PG8_SCHED __builtin_amdgcn_sched_barrier(0)
; template <class Epi, class Sched, bool ALIGN_EPI = false, bool SP2 = false, bool PAIR_ACC = false>
; __device__ __forceinline__ void gemm_phase(PG8_LAS unsigned char* lds, const Gemm g, const Sched& S, const Epi& E) {
;     ...
;             PG8_WAIT_V(8); PG8_WAIT_L(0); PG8_BAR; PG8_MMA(1, 0, At, B0); PG8_MMA(1, 1, At, B1); PG8_BAR; PG8_SCHED;
;             PG8_LDB(B0, 1, 0); PG8_LDB(B1, 1, 1); PG8_SCHED; PG8_LDA(At, 1, 0); PG8_STAGE(PG8_SA(0, 1), a2 + hstep, voffA);
;             PG8_WAIT_V(8); PG8_WAIT_L(0); PG8_BAR; PG8_MMA(0, 0, At, B0); PG8_MMA(0, 1, At, B1); PG8_BAR; PG8_SCHED;
	v_mfma_f32_16x16x32_bf16 v[126:129], v[152:155], v[190:193], v[126:129]
	v_mfma_f32_16x16x32_bf16 v[122:125], v[160:163], v[190:193], v[122:125]
	v_mfma_f32_16x16x32_bf16 v[86:89], v[152:155], v[198:201], v[86:89]
	v_mfma_f32_16x16x32_bf16 v[82:85], v[160:163], v[198:201], v[82:85]
	v_mfma_f32_16x16x32_bf16 v[30:33], v[152:155], v[206:209], v[30:33]
	v_mfma_f32_16x16x32_bf16 v[26:29], v[160:163], v[206:209], v[26:29]
	v_mfma_f32_16x16x32_bf16 v[14:17], v[152:155], v[214:217], v[14:17]
	v_mfma_f32_16x16x32_bf16 v[10:13], v[160:163], v[214:217], v[10:13]
	v_mfma_f32_16x16x32_bf16 v[126:129], v[156:159], v[194:197], v[126:129]
	v_mfma_f32_16x16x32_bf16 v[122:125], v[170:173], v[194:197], v[122:125]
	v_mfma_f32_16x16x32_bf16 v[86:89], v[156:159], v[202:205], v[86:89]
	v_mfma_f32_16x16x32_bf16 v[82:85], v[170:173], v[202:205], v[82:85]
	v_mfma_f32_16x16x32_bf16 v[30:33], v[156:159], v[210:213], v[30:33]
	v_mfma_f32_16x16x32_bf16 v[26:29], v[170:173], v[210:213], v[26:29]
	v_mfma_f32_16x16x32_bf16 v[14:17], v[156:159], v[218:221], v[14:17]
	v_mfma_f32_16x16x32_bf16 v[10:13], v[170:173], v[218:221], v[10:13]
	v_mfma_f32_16x16x32_bf16 v[118:121], v[174:177], v[190:193], v[118:121]
	v_mfma_f32_16x16x32_bf16 v[110:113], v[182:185], v[190:193], v[110:113]
	v_mfma_f32_16x16x32_bf16 v[38:41], v[174:177], v[198:201], v[38:41]
	v_mfma_f32_16x16x32_bf16 v[34:37], v[182:185], v[198:201], v[34:37]
	v_mfma_f32_16x16x32_bf16 v[22:25], v[174:177], v[206:209], v[22:25]
	v_mfma_f32_16x16x32_bf16 v[18:21], v[182:185], v[206:209], v[18:21]
	v_mfma_f32_16x16x32_bf16 v[6:9], v[174:177], v[214:217], v[6:9]
	v_mfma_f32_16x16x32_bf16 v[2:5], v[182:185], v[214:217], v[2:5]
	v_mfma_f32_16x16x32_bf16 v[118:121], v[178:181], v[194:197], v[118:121]
	v_mfma_f32_16x16x32_bf16 v[110:113], v[186:189], v[194:197], v[110:113]
	v_mfma_f32_16x16x32_bf16 v[38:41], v[178:181], v[202:205], v[38:41]
	v_mfma_f32_16x16x32_bf16 v[34:37], v[186:189], v[202:205], v[34:37]
	v_mfma_f32_16x16x32_bf16 v[22:25], v[178:181], v[210:213], v[22:25]
	v_mfma_f32_16x16x32_bf16 v[18:21], v[186:189], v[210:213], v[18:21]
	v_mfma_f32_16x16x32_bf16 v[6:9], v[178:181], v[218:221], v[6:9]
	v_mfma_f32_16x16x32_bf16 v[2:5], v[186:189], v[218:221], v[2:5]
	s_barrier
	s_add_i32 s63, 0, 0x18000
	v_add_u32_e32 v169, s63, v150
	s_add_i32 s64, 0, 0x1c000
	ds_read_b128 v[152:155], v169
	ds_read_b128 v[156:159], v169 offset:1024
	ds_read_b128 v[160:163], v169 offset:2048
	ds_read_b128 v[170:173], v169 offset:3072
	v_add_u32_e32 v169, s64, v150
	ds_read_b128 v[174:177], v169
	ds_read_b128 v[178:181], v169 offset:1024
	ds_read_b128 v[182:185], v169 offset:2048
	ds_read_b128 v[186:189], v169 offset:3072
	s_add_u32 s48, s48, 0x40000
	s_addc_u32 s49, s49, 0
	s_mov_b32 m0, s52
	v_lshl_add_u64 v[228:229], s[48:49], 0, v[130:131]
	ds_read_b128 v[190:193], v151 offset:32768
	ds_read_b128 v[194:197], v151 offset:33792
	ds_read_b128 v[198:201], v151 offset:34816
	ds_read_b128 v[202:205], v151 offset:35840
	ds_read_b128 v[206:209], v151 offset:36864
	ds_read_b128 v[210:213], v151 offset:37888
	ds_read_b128 v[214:217], v151 offset:38912
	ds_read_b128 v[218:221], v151 offset:39936
	global_load_lds_dwordx4 v[228:229], off
	v_lshl_add_u64 v[228:229], s[48:49], 0, v[134:135]
	s_mov_b32 m0, s53
	s_nop 0
	global_load_lds_dwordx4 v[228:229], off
	s_waitcnt vmcnt(8)
	s_waitcnt lgkmcnt(0)
	s_barrier
	v_mfma_f32_16x16x32_bf16 v[58:61], v[152:155], v[190:193], v[58:61]
	v_mfma_f32_16x16x32_bf16 v[62:65], v[160:163], v[190:193], v[62:65]
	v_mfma_f32_16x16x32_bf16 v[78:81], v[152:155], v[198:201], v[78:81]
	v_mfma_f32_16x16x32_bf16 v[70:73], v[160:163], v[198:201], v[70:73]
	v_mfma_f32_16x16x32_bf16 v[98:101], v[152:155], v[206:209], v[98:101]
	v_mfma_f32_16x16x32_bf16 v[90:93], v[160:163], v[206:209], v[90:93]
	v_mfma_f32_16x16x32_bf16 v[114:117], v[152:155], v[214:217], v[114:117]
	v_mfma_f32_16x16x32_bf16 v[106:109], v[160:163], v[214:217], v[106:109]
	v_mfma_f32_16x16x32_bf16 v[58:61], v[156:159], v[194:197], v[58:61]
	v_mfma_f32_16x16x32_bf16 v[62:65], v[170:173], v[194:197], v[62:65]
	v_mfma_f32_16x16x32_bf16 v[78:81], v[156:159], v[202:205], v[78:81]
	v_mfma_f32_16x16x32_bf16 v[70:73], v[170:173], v[202:205], v[70:73]
	v_mfma_f32_16x16x32_bf16 v[98:101], v[156:159], v[210:213], v[98:101]
	v_mfma_f32_16x16x32_bf16 v[90:93], v[170:173], v[210:213], v[90:93]
	v_mfma_f32_16x16x32_bf16 v[114:117], v[156:159], v[218:221], v[114:117]
	v_mfma_f32_16x16x32_bf16 v[106:109], v[170:173], v[218:221], v[106:109]
	v_mfma_f32_16x16x32_bf16 v[54:57], v[174:177], v[190:193], v[54:57]
	v_mfma_f32_16x16x32_bf16 v[46:49], v[182:185], v[190:193], v[46:49]
	v_mfma_f32_16x16x32_bf16 v[50:53], v[174:177], v[198:201], v[50:53]
	v_mfma_f32_16x16x32_bf16 v[42:45], v[182:185], v[198:201], v[42:45]
	v_mfma_f32_16x16x32_bf16 v[74:77], v[174:177], v[206:209], v[74:77]
	v_mfma_f32_16x16x32_bf16 v[66:69], v[182:185], v[206:209], v[66:69]
	v_mfma_f32_16x16x32_bf16 v[102:105], v[174:177], v[214:217], v[102:105]
	v_mfma_f32_16x16x32_bf16 v[94:97], v[182:185], v[214:217], v[94:97]
	v_mfma_f32_16x16x32_bf16 v[54:57], v[178:181], v[194:197], v[54:57]
	v_mfma_f32_16x16x32_bf16 v[46:49], v[186:189], v[194:197], v[46:49]
	v_mfma_f32_16x16x32_bf16 v[50:53], v[178:181], v[202:205], v[50:53]
	v_mfma_f32_16x16x32_bf16 v[42:45], v[186:189], v[202:205], v[42:45]
	v_mfma_f32_16x16x32_bf16 v[74:77], v[178:181], v[210:213], v[74:77]
	v_mfma_f32_16x16x32_bf16 v[66:69], v[186:189], v[210:213], v[66:69]
	v_mfma_f32_16x16x32_bf16 v[102:105], v[178:181], v[218:221], v[102:105]
	v_mfma_f32_16x16x32_bf16 v[94:97], v[186:189], v[218:221], v[94:97]
	s_barrier
; #define PG8_STAGE(bufoff, gbase, voff) do { _Pragma("unroll") for (int _i = 0; _i < 2; ++_i) \
;         __builtin_amdgcn_global_load_lds((const unsigned*)((const char*)(gbase) + (voff)[_i]), (PG8_LAS unsigned*)(lds + (bufoff) + ldsw + _i * 8192), 16, 0, 0); } while (0)
; #define PG8_LDA(dst, b, h) do { _Pragma("unroll") for (int m = 0; m < 4; ++m) _Pragma("unroll") for (int k = 0; k < 2; ++k) dst[m][k] = *(const PG8_LAS bf16x8*)(lds + PG8_SA(b, h) + aoff + m * 2048 + k * 1024); } while (0)
; #define PG8_MMA(ai, bj, At, Bt) do { __builtin_amdgcn_s_setprio(1); _Pragma("unroll") for (int m = 0; m < 4; ++m) _Pragma("unroll") for (int n = 0; n < 2; ++n) _Pragma("unroll") for (int k = 0; k < 2; ++k) \
;         acc[ai][bj][m][n] = __builtin_amdgcn_mfma_f32_16x16x32_bf16(Bt[n][k], At[m][k], acc[ai][bj][m][n], 0, 0, 0); __builtin_amdgcn_s_setprio(0); } while (0)
; #define PG8_WAIT_V(n) asm volatile("s_waitcnt vmcnt(" #n ")" ::: "memory")
; #define PG8_WAIT_L(n) asm volatile("s_waitcnt lgkmcnt(" #n ")" ::: "memory")
; #define PG8_BAR __builtin_amdgcn_s_barrier()
; #define PG8_SCHED __builtin_amdgcn_sched_barrier(0)
; template <class Epi, class Sched, bool ALIGN_EPI = false, bool SP2 = false, bool PAIR_ACC = false>
; __device__ __forceinline__ void gemm_phase(PG8_LAS unsigned char* lds, const Gemm g, const Sched& S, const Epi& E) {
;     ...
;             PG8_LDA(At, 1, 1); PG8_STAGE(PG8_SB(1, 0), b3, voffB); PG8_STAGE(PG8_SB(1, 1), b3 + hstep, voffB); PG8_STAGE(PG8_SA(1, 0), a3, voffA);
;             PG8_WAIT_V(8); PG8_WAIT_L(0); PG8_BAR; PG8_MMA(1, 0, At, B0); PG8_MMA(1, 1, At, B1); PG8_BAR; PG8_SCHED;
;     ...
;         if (!has_next) break;
;         if (!(PAIR_ACC && cur.pn < 4)) {
; #pragma unroll
;         for (int a = 0; a < 2; ++a)
; #pragma unroll
;             for (int b = 0; b < 2; ++b)
; #pragma unroll
;                 for (int m = 0; m < 4; ++m)
; #pragma unroll
;                     for (int n = 0; n < 2; ++n) acc[a][b][m][n] = (f32x4){0.f, 0.f, 0.f, 0.f};
;         }
	s_add_i32 s48, s63, s37
	v_lshl_add_u64 v[164:165], v[164:165], 0, s[22:23]
	s_mov_b32 m0, s48
	ds_read_b128 v[190:193], v151 offset:49152
	ds_read_b128 v[194:197], v151 offset:50176
	ds_read_b128 v[198:201], v151 offset:51200
	ds_read_b128 v[202:205], v151 offset:52224
	ds_read_b128 v[206:209], v151 offset:53248
	ds_read_b128 v[210:213], v151 offset:54272
	ds_read_b128 v[214:217], v151 offset:55296
	ds_read_b128 v[218:221], v151 offset:56320
	global_load_lds_dwordx4 v[164:165], off
	s_add_i32 m0, s48, 0x2000
	s_add_u32 s46, s46, 0x40080
	v_lshl_add_u64 v[164:165], v[222:223], 0, s[22:23]
	s_addc_u32 s47, s47, 0
	s_add_i32 s48, s64, s37
	global_load_lds_dwordx4 v[164:165], off
	v_lshl_add_u64 v[164:165], s[46:47], 0, v[132:133]
	s_mov_b32 m0, s48
	s_nop 0
	global_load_lds_dwordx4 v[164:165], off
	v_lshl_add_u64 v[164:165], s[46:47], 0, v[136:137]
	s_add_i32 m0, s48, 0x2000
	s_nop 0
	global_load_lds_dwordx4 v[164:165], off
	v_lshl_add_u64 v[164:165], v[224:225], 0, s[22:23]
	s_mov_b32 m0, s55
	s_nop 0
	global_load_lds_dwordx4 v[164:165], off
	v_lshl_add_u64 v[164:165], v[226:227], 0, s[22:23]
	s_mov_b32 m0, s56
	s_nop 0
	global_load_lds_dwordx4 v[164:165], off
	s_waitcnt vmcnt(8)
	s_waitcnt lgkmcnt(0)
	s_barrier
	v_mfma_f32_16x16x32_bf16 v[126:129], v[152:155], v[190:193], v[126:129]
	v_mfma_f32_16x16x32_bf16 v[122:125], v[160:163], v[190:193], v[122:125]
	v_mfma_f32_16x16x32_bf16 v[86:89], v[152:155], v[198:201], v[86:89]
	v_mfma_f32_16x16x32_bf16 v[82:85], v[160:163], v[198:201], v[82:85]
	v_mfma_f32_16x16x32_bf16 v[30:33], v[152:155], v[206:209], v[30:33]
	v_mfma_f32_16x16x32_bf16 v[26:29], v[160:163], v[206:209], v[26:29]
	v_mfma_f32_16x16x32_bf16 v[14:17], v[152:155], v[214:217], v[14:17]
	v_mfma_f32_16x16x32_bf16 v[10:13], v[160:163], v[214:217], v[10:13]
	v_mfma_f32_16x16x32_bf16 v[126:129], v[156:159], v[194:197], v[126:129]
	v_mfma_f32_16x16x32_bf16 v[122:125], v[170:173], v[194:197], v[122:125]
	v_mfma_f32_16x16x32_bf16 v[86:89], v[156:159], v[202:205], v[86:89]
	v_mfma_f32_16x16x32_bf16 v[82:85], v[170:173], v[202:205], v[82:85]
	v_mfma_f32_16x16x32_bf16 v[30:33], v[156:159], v[210:213], v[30:33]
	v_mfma_f32_16x16x32_bf16 v[26:29], v[170:173], v[210:213], v[26:29]
	v_mfma_f32_16x16x32_bf16 v[14:17], v[156:159], v[218:221], v[14:17]
	v_mfma_f32_16x16x32_bf16 v[10:13], v[170:173], v[218:221], v[10:13]
	v_mfma_f32_16x16x32_bf16 v[118:121], v[174:177], v[190:193], v[118:121]
	v_mfma_f32_16x16x32_bf16 v[110:113], v[182:185], v[190:193], v[110:113]
	v_mfma_f32_16x16x32_bf16 v[38:41], v[174:177], v[198:201], v[38:41]
	v_mfma_f32_16x16x32_bf16 v[34:37], v[182:185], v[198:201], v[34:37]
	v_mfma_f32_16x16x32_bf16 v[22:25], v[174:177], v[206:209], v[22:25]
	v_mfma_f32_16x16x32_bf16 v[18:21], v[182:185], v[206:209], v[18:21]
	v_mfma_f32_16x16x32_bf16 v[6:9], v[174:177], v[214:217], v[6:9]
	v_mfma_f32_16x16x32_bf16 v[2:5], v[182:185], v[214:217], v[2:5]
	v_mfma_f32_16x16x32_bf16 v[118:121], v[178:181], v[194:197], v[118:121]
	v_mfma_f32_16x16x32_bf16 v[110:113], v[186:189], v[194:197], v[110:113]
	v_mfma_f32_16x16x32_bf16 v[38:41], v[178:181], v[202:205], v[38:41]
	v_mfma_f32_16x16x32_bf16 v[34:37], v[186:189], v[202:205], v[34:37]
	v_mfma_f32_16x16x32_bf16 v[22:25], v[178:181], v[210:213], v[22:25]
	v_mfma_f32_16x16x32_bf16 v[18:21], v[186:189], v[210:213], v[18:21]
	v_mfma_f32_16x16x32_bf16 v[6:9], v[178:181], v[218:221], v[6:9]
	v_mfma_f32_16x16x32_bf16 v[2:5], v[186:189], v[218:221], v[2:5]
	s_barrier
	s_add_i32 s62, s62, 2
	s_add_u32 s44, s44, 0x100
	s_addc_u32 s45, s45, 0
	s_cmp_gt_u32 s62, 13
	s_cbranch_scc0 .LBB0_1630
	s_add_u32 s42, s42, 0xffffff00
	s_addc_u32 s43, s43, -1
	s_andn2_b64 vcc, exec, s[8:9]
	s_cbranch_vccnz .LBB0_1621
	v_mov_b32_e32 v2, 0
	s_mov_b32 s10, s28
	s_mov_b32 s18, s30
	s_mov_b64 s[20:21], s[40:41]
	s_mov_b32 s54, s59
	v_mov_b32_e32 v3, v2
	v_mov_b32_e32 v4, v2
	v_mov_b32_e32 v5, v2
	v_mov_b32_e32 v6, v2
	v_mov_b32_e32 v7, v2
	v_mov_b32_e32 v8, v2
	v_mov_b32_e32 v9, v2
	v_mov_b32_e32 v18, v2
	v_mov_b32_e32 v19, v2
	v_mov_b32_e32 v20, v2
	v_mov_b32_e32 v21, v2
	v_mov_b32_e32 v22, v2
	v_mov_b32_e32 v23, v2
	v_mov_b32_e32 v24, v2
	v_mov_b32_e32 v25, v2
	v_mov_b32_e32 v34, v2
	v_mov_b32_e32 v35, v2
	v_mov_b32_e32 v36, v2
	v_mov_b32_e32 v37, v2
	v_mov_b32_e32 v38, v2
	v_mov_b32_e32 v39, v2
	v_mov_b32_e32 v40, v2
	v_mov_b32_e32 v41, v2
	v_mov_b32_e32 v110, v2
	v_mov_b32_e32 v111, v2
	v_mov_b32_e32 v112, v2
	v_mov_b32_e32 v113, v2
	v_mov_b32_e32 v118, v2
	v_mov_b32_e32 v119, v2
	v_mov_b32_e32 v120, v2
	v_mov_b32_e32 v121, v2
	v_mov_b32_e32 v10, v2
	v_mov_b32_e32 v11, v2
	v_mov_b32_e32 v12, v2
	v_mov_b32_e32 v13, v2
	v_mov_b32_e32 v14, v2
	v_mov_b32_e32 v15, v2
	v_mov_b32_e32 v16, v2
	v_mov_b32_e32 v17, v2
	v_mov_b32_e32 v26, v2
	v_mov_b32_e32 v27, v2
	v_mov_b32_e32 v28, v2
	v_mov_b32_e32 v29, v2
	v_mov_b32_e32 v30, v2
	v_mov_b32_e32 v31, v2
	v_mov_b32_e32 v32, v2
	v_mov_b32_e32 v33, v2
	v_mov_b32_e32 v82, v2
	v_mov_b32_e32 v83, v2
	v_mov_b32_e32 v84, v2
	v_mov_b32_e32 v85, v2
	v_mov_b32_e32 v86, v2
	v_mov_b32_e32 v87, v2
	v_mov_b32_e32 v88, v2
	v_mov_b32_e32 v89, v2
	v_mov_b32_e32 v122, v2
	v_mov_b32_e32 v123, v2
	v_mov_b32_e32 v124, v2
	v_mov_b32_e32 v125, v2
	v_mov_b32_e32 v126, v2
	v_mov_b32_e32 v127, v2
	v_mov_b32_e32 v128, v2
	v_mov_b32_e32 v129, v2
	v_mov_b32_e32 v94, v2
	v_mov_b32_e32 v95, v2
	v_mov_b32_e32 v96, v2
	v_mov_b32_e32 v97, v2
	v_mov_b32_e32 v102, v2
	v_mov_b32_e32 v103, v2
	v_mov_b32_e32 v104, v2
	v_mov_b32_e32 v105, v2
	v_mov_b32_e32 v66, v2
	v_mov_b32_e32 v67, v2
	v_mov_b32_e32 v68, v2
	v_mov_b32_e32 v69, v2
	v_mov_b32_e32 v74, v2
	v_mov_b32_e32 v75, v2
	v_mov_b32_e32 v76, v2
	v_mov_b32_e32 v77, v2
	v_mov_b32_e32 v42, v2
	v_mov_b32_e32 v43, v2
	v_mov_b32_e32 v44, v2
	v_mov_b32_e32 v45, v2
	v_mov_b32_e32 v50, v2
	v_mov_b32_e32 v51, v2
	v_mov_b32_e32 v52, v2
	v_mov_b32_e32 v53, v2
	v_mov_b32_e32 v46, v2
	v_mov_b32_e32 v47, v2
	v_mov_b32_e32 v48, v2
	v_mov_b32_e32 v49, v2
	v_mov_b32_e32 v54, v2
	v_mov_b32_e32 v55, v2
	v_mov_b32_e32 v56, v2
	v_mov_b32_e32 v57, v2
	v_mov_b32_e32 v106, v2
	v_mov_b32_e32 v107, v2
	v_mov_b32_e32 v108, v2
	v_mov_b32_e32 v109, v2
	v_mov_b32_e32 v114, v2
	v_mov_b32_e32 v115, v2
	v_mov_b32_e32 v116, v2
	v_mov_b32_e32 v117, v2
	v_mov_b32_e32 v90, v2
	v_mov_b32_e32 v91, v2
	v_mov_b32_e32 v92, v2
	v_mov_b32_e32 v93, v2
	v_mov_b32_e32 v98, v2
	v_mov_b32_e32 v99, v2
	v_mov_b32_e32 v100, v2
	v_mov_b32_e32 v101, v2
	v_mov_b32_e32 v70, v2
	v_mov_b32_e32 v71, v2
	v_mov_b32_e32 v72, v2
	v_mov_b32_e32 v73, v2
	v_mov_b32_e32 v78, v2
	v_mov_b32_e32 v79, v2
	v_mov_b32_e32 v80, v2
	v_mov_b32_e32 v81, v2
	v_mov_b32_e32 v62, v2
	v_mov_b32_e32 v63, v2
	v_mov_b32_e32 v64, v2
	v_mov_b32_e32 v65, v2
	v_mov_b32_e32 v58, v2
	v_mov_b32_e32 v59, v2
	v_mov_b32_e32 v60, v2
	v_mov_b32_e32 v61, v2
	s_andn2_b64 vcc, exec, s[6:7]
	s_cbranch_vccnz .LBB0_1622

; #define PG8_STAGE(bufoff, gbase, voff) do { _Pragma("unroll") for (int _i = 0; _i < 2; ++_i) \
;         __builtin_amdgcn_global_load_lds((const unsigned*)((const char*)(gbase) + (voff)[_i]), (PG8_LAS unsigned*)(lds + (bufoff) + ldsw + _i * 8192), 16, 0, 0); } while (0)
; #define PG8_LDA(dst, b, h) do { _Pragma("unroll") for (int m = 0; m < 4; ++m) _Pragma("unroll") for (int k = 0; k < 2; ++k) dst[m][k] = *(const PG8_LAS bf16x8*)(lds + PG8_SA(b, h) + aoff + m * 2048 + k * 1024); } while (0)
; #define PG8_LDB(dst, b, h) do { _Pragma("unroll") for (int n = 0; n < 2; ++n) _Pragma("unroll") for (int k = 0; k < 2; ++k) dst[n][k] = *(const PG8_LAS bf16x8*)(lds + PG8_SB(b, h) + boff + n * 2048 + k * 1024); } while (0)
; #define PG8_WAIT_V(n) asm volatile("s_waitcnt vmcnt(" #n ")" ::: "memory")
; #define PG8_WAIT_L(n) asm volatile("s_waitcnt lgkmcnt(" #n ")" ::: "memory")
; #define PG8_BAR __builtin_amdgcn_s_barrier()
; template <class Epi, class Sched, bool ALIGN_EPI = false, bool SP2 = false, bool PAIR_ACC = false>
; __device__ __forceinline__ void gemm_phase(PG8_LAS unsigned char* lds, const Gemm g, const Sched& S, const Epi& E) {
;     ...
;         const bool has_next = S.next(ui + 1, nxt);
;         const char* nA = has_next ? (const char*)g.A + (size_t)nxt.pm * tstep + (size_t)(nxt.pn / g.a_div) * g.a_sel : cA; const char* nB = has_next ? (const char*)g.Bt + (size_t)nxt.pn * tstep : cB;
;         for (int t = 0; t < nt; t += 2) {
;             const bool last = (t == nt - 2);
;             const char* a1 = cA + (size_t)(t + 1) * kstep;
;             const char* a2 = last ? nA : cA + (size_t)(t + 2) * kstep; const char* b2 = last ? nB : cB + (size_t)(t + 2) * kstep;
;             const char* a3 = a2 + kstep; const char* b3 = b2 + kstep;
;             if (last && has_next) S.a_ready(nxt);
;             if constexpr (SP2) {
;             PG8_LDB(B0, 0, 0); PG8_LDB(B1, 0, 1); PG8_SCHED; PG8_LDA(At, 0, 0); PG8_STAGE(PG8_SA(1, 1), a1 + hstep, voffA);
;             PG8_WAIT_V(8); PG8_WAIT_L(0); PG8_BAR; PG8_MMA(0, 0, At, B0); PG8_MMA(0, 1, At, B1); PG8_BAR; PG8_SCHED;
;             PG8_LDA(At, 0, 1); PG8_STAGE(PG8_SB(0, 0), b2, voffB); PG8_STAGE(PG8_SB(0, 1), b2 + hstep, voffB); PG8_STAGE(PG8_SA(0, 0), a2, voffA);
;             PG8_WAIT_V(8); PG8_WAIT_L(0); PG8_BAR; PG8_MMA(1, 0, At, B0); PG8_MMA(1, 1, At, B1); PG8_BAR; PG8_SCHED;
.LBB0_1736:
	s_ashr_i32 s53, s52, 31
	s_lshl_b64 s[10:11], s[52:53], 19
	s_add_u32 s54, s4, s10
	s_addc_u32 s55, s5, s11
	s_and_b64 s[10:11], s[8:9], exec
	s_cselect_b32 s53, s55, s63
	s_cselect_b32 s75, s54, s62
	s_ashr_i32 s51, s50, 31
	s_lshl_b64 s[10:11], s[50:51], 19
	s_add_u32 s56, s24, s10
	s_addc_u32 s57, s25, s11
	s_and_b64 s[10:11], s[8:9], exec
	s_cselect_b32 s51, s57, s61
	s_cselect_b32 s76, s56, s60
	s_add_u32 s10, s62, 0x40080
	s_addc_u32 s11, s63, 0
	s_add_u32 s77, s60, 0x100
	s_addc_u32 s78, s61, 0
	s_mov_b32 s79, -2
	ds_read_b128 v[74:77], v196
	ds_read_b128 v[78:81], v196 offset:1024
	ds_read_b128 v[82:85], v196 offset:2048
	ds_read_b128 v[86:89], v196 offset:3072
	ds_read_b128 v[90:93], v197
	ds_read_b128 v[94:97], v197 offset:1024
	ds_read_b128 v[98:101], v197 offset:2048
	ds_read_b128 v[106:109], v197 offset:3072
	s_add_u32 s60, s10, 0xfffc0080
	s_addc_u32 s61, s11, -1
	s_cmp_eq_u32 s79, 12
	s_cselect_b32 s63, s53, s61
	s_cselect_b32 s62, s75, s60
	s_cselect_b32 s61, s51, s78
	s_cselect_b32 s60, s76, s77
	v_lshl_add_u64 v[170:171], s[10:11], 0, v[184:185]
	s_add_i32 m0, s36, 0xc000
	ds_read_b128 v[162:165], v198
	ds_read_b128 v[166:169], v198 offset:1024
	ds_read_b128 v[204:207], v198 offset:2048
	ds_read_b128 v[208:211], v198 offset:3072
	ds_read_b128 v[212:215], v198 offset:4096
	ds_read_b128 v[216:219], v198 offset:5120
	ds_read_b128 v[220:223], v198 offset:6144
	ds_read_b128 v[224:227], v198 offset:7168
	global_load_lds_dwordx4 v[170:171], off
	v_lshl_add_u64 v[170:171], s[10:11], 0, v[186:187]
	s_add_i32 m0, s36, 0xe000
	s_nop 0
	global_load_lds_dwordx4 v[170:171], off
	s_waitcnt vmcnt(8)
	s_waitcnt lgkmcnt(0)
	s_barrier
	v_mfma_f32_16x16x32_bf16 v[150:153], v[74:77], v[162:165], 0
	v_mfma_f32_16x16x32_bf16 v[146:149], v[82:85], v[162:165], 0
	v_mfma_f32_16x16x32_bf16 v[134:137], v[74:77], v[204:207], 0
	v_mfma_f32_16x16x32_bf16 v[130:133], v[82:85], v[204:207], 0
	v_mfma_f32_16x16x32_bf16 v[118:121], v[74:77], v[212:215], 0
	v_mfma_f32_16x16x32_bf16 v[110:113], v[82:85], v[212:215], 0
	v_mfma_f32_16x16x32_bf16 v[114:117], v[74:77], v[220:223], 0
	v_mfma_f32_16x16x32_bf16 v[102:105], v[82:85], v[220:223], 0
	v_mfma_f32_16x16x32_bf16 v[150:153], v[78:81], v[166:169], v[150:153]
	v_mfma_f32_16x16x32_bf16 v[146:149], v[86:89], v[166:169], v[146:149]
	v_mfma_f32_16x16x32_bf16 v[134:137], v[78:81], v[208:211], v[134:137]
	v_mfma_f32_16x16x32_bf16 v[130:133], v[86:89], v[208:211], v[130:133]
	v_mfma_f32_16x16x32_bf16 v[118:121], v[78:81], v[216:219], v[118:121]
	v_mfma_f32_16x16x32_bf16 v[110:113], v[86:89], v[216:219], v[110:113]
	v_mfma_f32_16x16x32_bf16 v[114:117], v[78:81], v[224:227], v[114:117]
	v_mfma_f32_16x16x32_bf16 v[102:105], v[86:89], v[224:227], v[102:105]
	v_mfma_f32_16x16x32_bf16 v[158:161], v[90:93], v[162:165], 0
	v_mfma_f32_16x16x32_bf16 v[154:157], v[98:101], v[162:165], 0
	v_mfma_f32_16x16x32_bf16 v[142:145], v[90:93], v[204:207], 0
	v_mfma_f32_16x16x32_bf16 v[138:141], v[98:101], v[204:207], 0
	v_mfma_f32_16x16x32_bf16 v[126:129], v[90:93], v[212:215], 0
	v_mfma_f32_16x16x32_bf16 v[122:125], v[98:101], v[212:215], 0
	v_mfma_f32_16x16x32_bf16 v[70:73], v[90:93], v[220:223], 0
	v_mfma_f32_16x16x32_bf16 v[66:69], v[98:101], v[220:223], 0
	v_mfma_f32_16x16x32_bf16 v[158:161], v[94:97], v[166:169], v[158:161]
	v_mfma_f32_16x16x32_bf16 v[154:157], v[106:109], v[166:169], v[154:157]
	v_mfma_f32_16x16x32_bf16 v[142:145], v[94:97], v[208:211], v[142:145]
	v_mfma_f32_16x16x32_bf16 v[138:141], v[106:109], v[208:211], v[138:141]
	v_mfma_f32_16x16x32_bf16 v[126:129], v[94:97], v[216:219], v[126:129]
	v_mfma_f32_16x16x32_bf16 v[122:125], v[106:109], v[216:219], v[122:125]
	v_mfma_f32_16x16x32_bf16 v[70:73], v[94:97], v[224:227], v[70:73]
	v_mfma_f32_16x16x32_bf16 v[66:69], v[106:109], v[224:227], v[66:69]
	s_barrier
	s_add_i32 s80, s70, s34
	v_lshl_add_u64 v[170:171], s[60:61], 0, v[176:177]
	s_mov_b32 m0, s80
	ds_read_b128 v[162:165], v198 offset:16384
	ds_read_b128 v[166:169], v198 offset:17408
	ds_read_b128 v[204:207], v198 offset:18432
	ds_read_b128 v[208:211], v198 offset:19456
	ds_read_b128 v[212:215], v198 offset:20480
	ds_read_b128 v[216:219], v198 offset:21504
	ds_read_b128 v[220:223], v198 offset:22528
	ds_read_b128 v[224:227], v198 offset:23552
	global_load_lds_dwordx4 v[170:171], off
	s_add_i32 m0, s80, 0x2000
	s_add_u32 s80, s60, 0x40000
	v_lshl_add_u64 v[192:193], s[60:61], 0, v[172:173]
	s_addc_u32 s81, s61, 0
	s_add_i32 s82, s71, s34
	global_load_lds_dwordx4 v[192:193], off
	v_lshl_add_u64 v[228:229], s[80:81], 0, v[176:177]
	s_mov_b32 m0, s82
	v_lshl_add_u64 v[230:231], s[62:63], 0, v[174:175]
	global_load_lds_dwordx4 v[228:229], off
	v_lshl_add_u64 v[228:229], s[80:81], 0, v[172:173]
	s_add_i32 m0, s82, 0x2000
	s_nop 0
	global_load_lds_dwordx4 v[228:229], off
	v_lshl_add_u64 v[228:229], s[62:63], 0, v[178:179]
	s_mov_b32 m0, s36
	s_nop 0
	global_load_lds_dwordx4 v[228:229], off
	s_mov_b32 m0, s37
	s_nop 0
	global_load_lds_dwordx4 v[230:231], off
	s_waitcnt vmcnt(8)
	s_waitcnt lgkmcnt(0)
	s_barrier
; #define PG8_STAGE(bufoff, gbase, voff) do { _Pragma("unroll") for (int _i = 0; _i < 2; ++_i) \
;         __builtin_amdgcn_global_load_lds((const unsigned*)((const char*)(gbase) + (voff)[_i]), (PG8_LAS unsigned*)(lds + (bufoff) + ldsw + _i * 8192), 16, 0, 0); } while (0)
; #define PG8_LDA(dst, b, h) do { _Pragma("unroll") for (int m = 0; m < 4; ++m) _Pragma("unroll") for (int k = 0; k < 2; ++k) dst[m][k] = *(const PG8_LAS bf16x8*)(lds + PG8_SA(b, h) + aoff + m * 2048 + k * 1024); } while (0)
; #define PG8_LDB(dst, b, h) do { _Pragma("unroll") for (int n = 0; n < 2; ++n) _Pragma("unroll") for (int k = 0; k < 2; ++k) dst[n][k] = *(const PG8_LAS bf16x8*)(lds + PG8_SB(b, h) + boff + n * 2048 + k * 1024); } while (0)
; #define PG8_MMA(ai, bj, At, Bt) do { __builtin_amdgcn_s_setprio(1); _Pragma("unroll") for (int m = 0; m < 4; ++m) _Pragma("unroll") for (int n = 0; n < 2; ++n) _Pragma("unroll") for (int k = 0; k < 2; ++k) \
;         acc[ai][bj][m][n] = __builtin_amdgcn_mfma_f32_16x16x32_bf16(Bt[n][k], At[m][k], acc[ai][bj][m][n], 0, 0, 0); __builtin_amdgcn_s_setprio(0); } while (0)
; #define PG8_WAIT_V(n) asm volatile("s_waitcnt vmcnt(" #n ")" ::: "memory")
; #define PG8_WAIT_L(n) asm volatile("s_waitcnt lgkmcnt(" #n ")" ::: "memory")
; #define PG8_BAR __builtin_amdgcn_s_barrier()
; #define PG8_SCHED __builtin_amdgcn_sched_barrier(0)
; template <class Epi, class Sched, bool ALIGN_EPI = false, bool SP2 = false, bool PAIR_ACC = false>
; __device__ __forceinline__ void gemm_phase(PG8_LAS unsigned char* lds, const Gemm g, const Sched& S, const Epi& E) {
;     ...
;             PG8_WAIT_V(8); PG8_WAIT_L(0); PG8_BAR; PG8_MMA(0, 0, At, B0); PG8_MMA(0, 1, At, B1); PG8_BAR; PG8_SCHED;
;             PG8_LDA(At, 0, 1); PG8_STAGE(PG8_SB(0, 0), b2, voffB); PG8_STAGE(PG8_SB(0, 1), b2 + hstep, voffB); PG8_STAGE(PG8_SA(0, 0), a2, voffA);
;             PG8_WAIT_V(8); PG8_WAIT_L(0); PG8_BAR; PG8_MMA(1, 0, At, B0); PG8_MMA(1, 1, At, B1); PG8_BAR; PG8_SCHED;
;             PG8_LDB(B0, 1, 0); PG8_LDB(B1, 1, 1); PG8_SCHED; PG8_LDA(At, 1, 0); PG8_STAGE(PG8_SA(0, 1), a2 + hstep, voffA);
;             PG8_WAIT_V(8); PG8_WAIT_L(0); PG8_BAR; PG8_MMA(0, 0, At, B0); PG8_MMA(0, 1, At, B1); PG8_BAR; PG8_SCHED;
	v_mfma_f32_16x16x32_bf16 v[54:57], v[74:77], v[162:165], 0
	v_mfma_f32_16x16x32_bf16 v[50:53], v[82:85], v[162:165], 0
	v_mfma_f32_16x16x32_bf16 v[38:41], v[74:77], v[204:207], 0
	v_mfma_f32_16x16x32_bf16 v[34:37], v[82:85], v[204:207], 0
	v_mfma_f32_16x16x32_bf16 v[22:25], v[74:77], v[212:215], 0
	v_mfma_f32_16x16x32_bf16 v[14:17], v[82:85], v[212:215], 0
	v_mfma_f32_16x16x32_bf16 v[18:21], v[74:77], v[220:223], 0
	v_mfma_f32_16x16x32_bf16 v[10:13], v[82:85], v[220:223], 0
	v_mfma_f32_16x16x32_bf16 v[54:57], v[78:81], v[166:169], v[54:57]
	v_mfma_f32_16x16x32_bf16 v[50:53], v[86:89], v[166:169], v[50:53]
	v_mfma_f32_16x16x32_bf16 v[38:41], v[78:81], v[208:211], v[38:41]
	v_mfma_f32_16x16x32_bf16 v[34:37], v[86:89], v[208:211], v[34:37]
	v_mfma_f32_16x16x32_bf16 v[22:25], v[78:81], v[216:219], v[22:25]
	v_mfma_f32_16x16x32_bf16 v[14:17], v[86:89], v[216:219], v[14:17]
	v_mfma_f32_16x16x32_bf16 v[18:21], v[78:81], v[224:227], v[18:21]
	v_mfma_f32_16x16x32_bf16 v[10:13], v[86:89], v[224:227], v[10:13]
	v_mfma_f32_16x16x32_bf16 v[62:65], v[90:93], v[162:165], 0
	v_mfma_f32_16x16x32_bf16 v[58:61], v[98:101], v[162:165], 0
	v_mfma_f32_16x16x32_bf16 v[46:49], v[90:93], v[204:207], 0
	v_mfma_f32_16x16x32_bf16 v[42:45], v[98:101], v[204:207], 0
	v_mfma_f32_16x16x32_bf16 v[30:33], v[90:93], v[212:215], 0
	v_mfma_f32_16x16x32_bf16 v[26:29], v[98:101], v[212:215], 0
	v_mfma_f32_16x16x32_bf16 v[6:9], v[90:93], v[220:223], 0
	v_mfma_f32_16x16x32_bf16 v[2:5], v[98:101], v[220:223], 0
	v_mfma_f32_16x16x32_bf16 v[62:65], v[94:97], v[166:169], v[62:65]
	v_mfma_f32_16x16x32_bf16 v[58:61], v[106:109], v[166:169], v[58:61]
	v_mfma_f32_16x16x32_bf16 v[46:49], v[94:97], v[208:211], v[46:49]
	v_mfma_f32_16x16x32_bf16 v[42:45], v[106:109], v[208:211], v[42:45]
	v_mfma_f32_16x16x32_bf16 v[30:33], v[94:97], v[216:219], v[30:33]
	v_mfma_f32_16x16x32_bf16 v[26:29], v[106:109], v[216:219], v[26:29]
	v_mfma_f32_16x16x32_bf16 v[6:9], v[94:97], v[224:227], v[6:9]
	v_mfma_f32_16x16x32_bf16 v[2:5], v[106:109], v[224:227], v[2:5]
	s_barrier
	s_branch .Lpeel_mid_1737
.LBB0_1737:
	ds_read_b128 v[74:77], v196
	ds_read_b128 v[78:81], v196 offset:1024
	ds_read_b128 v[82:85], v196 offset:2048
	ds_read_b128 v[86:89], v196 offset:3072
	ds_read_b128 v[90:93], v197
	ds_read_b128 v[94:97], v197 offset:1024
	ds_read_b128 v[98:101], v197 offset:2048
	ds_read_b128 v[106:109], v197 offset:3072
	s_add_u32 s60, s10, 0xfffc0080
	s_addc_u32 s61, s11, -1
	s_cmp_eq_u32 s79, 12
	s_cselect_b32 s63, s53, s61
	s_cselect_b32 s62, s75, s60
	s_cselect_b32 s61, s51, s78
	s_cselect_b32 s60, s76, s77
	v_lshl_add_u64 v[170:171], s[10:11], 0, v[184:185]
	s_add_i32 m0, s36, 0xc000
	ds_read_b128 v[162:165], v198
	ds_read_b128 v[166:169], v198 offset:1024
	ds_read_b128 v[204:207], v198 offset:2048
	ds_read_b128 v[208:211], v198 offset:3072
	ds_read_b128 v[212:215], v198 offset:4096
	ds_read_b128 v[216:219], v198 offset:5120
	ds_read_b128 v[220:223], v198 offset:6144
	ds_read_b128 v[224:227], v198 offset:7168
	global_load_lds_dwordx4 v[170:171], off
	v_lshl_add_u64 v[170:171], s[10:11], 0, v[186:187]
	s_add_i32 m0, s36, 0xe000
	s_nop 0
	global_load_lds_dwordx4 v[170:171], off
	s_waitcnt vmcnt(8)
	s_waitcnt lgkmcnt(0)
	s_barrier
	v_mfma_f32_16x16x32_bf16 v[150:153], v[74:77], v[162:165], v[150:153]
	v_mfma_f32_16x16x32_bf16 v[146:149], v[82:85], v[162:165], v[146:149]
	v_mfma_f32_16x16x32_bf16 v[134:137], v[74:77], v[204:207], v[134:137]
	v_mfma_f32_16x16x32_bf16 v[130:133], v[82:85], v[204:207], v[130:133]
	v_mfma_f32_16x16x32_bf16 v[118:121], v[74:77], v[212:215], v[118:121]
	v_mfma_f32_16x16x32_bf16 v[110:113], v[82:85], v[212:215], v[110:113]
	v_mfma_f32_16x16x32_bf16 v[114:117], v[74:77], v[220:223], v[114:117]
	v_mfma_f32_16x16x32_bf16 v[102:105], v[82:85], v[220:223], v[102:105]
	v_mfma_f32_16x16x32_bf16 v[150:153], v[78:81], v[166:169], v[150:153]
	v_mfma_f32_16x16x32_bf16 v[146:149], v[86:89], v[166:169], v[146:149]
	v_mfma_f32_16x16x32_bf16 v[134:137], v[78:81], v[208:211], v[134:137]
	v_mfma_f32_16x16x32_bf16 v[130:133], v[86:89], v[208:211], v[130:133]
	v_mfma_f32_16x16x32_bf16 v[118:121], v[78:81], v[216:219], v[118:121]
	v_mfma_f32_16x16x32_bf16 v[110:113], v[86:89], v[216:219], v[110:113]
	v_mfma_f32_16x16x32_bf16 v[114:117], v[78:81], v[224:227], v[114:117]
	v_mfma_f32_16x16x32_bf16 v[102:105], v[86:89], v[224:227], v[102:105]
	v_mfma_f32_16x16x32_bf16 v[158:161], v[90:93], v[162:165], v[158:161]
	v_mfma_f32_16x16x32_bf16 v[154:157], v[98:101], v[162:165], v[154:157]
	v_mfma_f32_16x16x32_bf16 v[142:145], v[90:93], v[204:207], v[142:145]
	v_mfma_f32_16x16x32_bf16 v[138:141], v[98:101], v[204:207], v[138:141]
	v_mfma_f32_16x16x32_bf16 v[126:129], v[90:93], v[212:215], v[126:129]
	v_mfma_f32_16x16x32_bf16 v[122:125], v[98:101], v[212:215], v[122:125]
	v_mfma_f32_16x16x32_bf16 v[70:73], v[90:93], v[220:223], v[70:73]
	v_mfma_f32_16x16x32_bf16 v[66:69], v[98:101], v[220:223], v[66:69]
	v_mfma_f32_16x16x32_bf16 v[158:161], v[94:97], v[166:169], v[158:161]
	v_mfma_f32_16x16x32_bf16 v[154:157], v[106:109], v[166:169], v[154:157]
	v_mfma_f32_16x16x32_bf16 v[142:145], v[94:97], v[208:211], v[142:145]
	v_mfma_f32_16x16x32_bf16 v[138:141], v[106:109], v[208:211], v[138:141]
	v_mfma_f32_16x16x32_bf16 v[126:129], v[94:97], v[216:219], v[126:129]
	v_mfma_f32_16x16x32_bf16 v[122:125], v[106:109], v[216:219], v[122:125]
	v_mfma_f32_16x16x32_bf16 v[70:73], v[94:97], v[224:227], v[70:73]
	v_mfma_f32_16x16x32_bf16 v[66:69], v[106:109], v[224:227], v[66:69]
	s_barrier
; #define PG8_STAGE(bufoff, gbase, voff) do { _Pragma("unroll") for (int _i = 0; _i < 2; ++_i) \
;         __builtin_amdgcn_global_load_lds((const unsigned*)((const char*)(gbase) + (voff)[_i]), (PG8_LAS unsigned*)(lds + (bufoff) + ldsw + _i * 8192), 16, 0, 0); } while (0)
; #define PG8_LDA(dst, b, h) do { _Pragma("unroll") for (int m = 0; m < 4; ++m) _Pragma("unroll") for (int k = 0; k < 2; ++k) dst[m][k] = *(const PG8_LAS bf16x8*)(lds + PG8_SA(b, h) + aoff + m * 2048 + k * 1024); } while (0)
; #define PG8_MMA(ai, bj, At, Bt) do { __builtin_amdgcn_s_setprio(1); _Pragma("unroll") for (int m = 0; m < 4; ++m) _Pragma("unroll") for (int n = 0; n < 2; ++n) _Pragma("unroll") for (int k = 0; k < 2; ++k) \
;         acc[ai][bj][m][n] = __builtin_amdgcn_mfma_f32_16x16x32_bf16(Bt[n][k], At[m][k], acc[ai][bj][m][n], 0, 0, 0); __builtin_amdgcn_s_setprio(0); } while (0)
; #define PG8_WAIT_V(n) asm volatile("s_waitcnt vmcnt(" #n ")" ::: "memory")
; #define PG8_WAIT_L(n) asm volatile("s_waitcnt lgkmcnt(" #n ")" ::: "memory")
; #define PG8_BAR __builtin_amdgcn_s_barrier()
; #define PG8_SCHED __builtin_amdgcn_sched_barrier(0)
; template <class Epi, class Sched, bool ALIGN_EPI = false, bool SP2 = false, bool PAIR_ACC = false>
; __device__ __forceinline__ void gemm_phase(PG8_LAS unsigned char* lds, const Gemm g, const Sched& S, const Epi& E) {
;     ...
;             PG8_LDA(At, 0, 1); PG8_STAGE(PG8_SB(0, 0), b2, voffB); PG8_STAGE(PG8_SB(0, 1), b2 + hstep, voffB); PG8_STAGE(PG8_SA(0, 0), a2, voffA);
;             PG8_WAIT_V(8); PG8_WAIT_L(0); PG8_BAR; PG8_MMA(1, 0, At, B0); PG8_MMA(1, 1, At, B1); PG8_BAR; PG8_SCHED;
	s_add_i32 s80, s70, s34
	v_lshl_add_u64 v[170:171], s[60:61], 0, v[176:177]
	s_mov_b32 m0, s80
	ds_read_b128 v[162:165], v198 offset:16384
	ds_read_b128 v[166:169], v198 offset:17408
	ds_read_b128 v[204:207], v198 offset:18432
	ds_read_b128 v[208:211], v198 offset:19456
	ds_read_b128 v[212:215], v198 offset:20480
	ds_read_b128 v[216:219], v198 offset:21504
	ds_read_b128 v[220:223], v198 offset:22528
	ds_read_b128 v[224:227], v198 offset:23552
	global_load_lds_dwordx4 v[170:171], off
	s_add_i32 m0, s80, 0x2000
	s_add_u32 s80, s60, 0x40000
	v_lshl_add_u64 v[192:193], s[60:61], 0, v[172:173]
	s_addc_u32 s81, s61, 0
	s_add_i32 s82, s71, s34
	global_load_lds_dwordx4 v[192:193], off
	v_lshl_add_u64 v[228:229], s[80:81], 0, v[176:177]
	s_mov_b32 m0, s82
	v_lshl_add_u64 v[230:231], s[62:63], 0, v[174:175]
	global_load_lds_dwordx4 v[228:229], off
	v_lshl_add_u64 v[228:229], s[80:81], 0, v[172:173]
	s_add_i32 m0, s82, 0x2000
	s_nop 0
	global_load_lds_dwordx4 v[228:229], off
	v_lshl_add_u64 v[228:229], s[62:63], 0, v[178:179]
	s_mov_b32 m0, s36
	s_nop 0
	global_load_lds_dwordx4 v[228:229], off
	s_mov_b32 m0, s37
	s_nop 0
	global_load_lds_dwordx4 v[230:231], off
	s_waitcnt vmcnt(8)
	s_waitcnt lgkmcnt(0)
	s_barrier
	v_mfma_f32_16x16x32_bf16 v[54:57], v[74:77], v[162:165], v[54:57]
	v_mfma_f32_16x16x32_bf16 v[50:53], v[82:85], v[162:165], v[50:53]
	v_mfma_f32_16x16x32_bf16 v[38:41], v[74:77], v[204:207], v[38:41]
	v_mfma_f32_16x16x32_bf16 v[34:37], v[82:85], v[204:207], v[34:37]
	v_mfma_f32_16x16x32_bf16 v[22:25], v[74:77], v[212:215], v[22:25]
	v_mfma_f32_16x16x32_bf16 v[14:17], v[82:85], v[212:215], v[14:17]
	v_mfma_f32_16x16x32_bf16 v[18:21], v[74:77], v[220:223], v[18:21]
	v_mfma_f32_16x16x32_bf16 v[10:13], v[82:85], v[220:223], v[10:13]
	v_mfma_f32_16x16x32_bf16 v[54:57], v[78:81], v[166:169], v[54:57]
	v_mfma_f32_16x16x32_bf16 v[50:53], v[86:89], v[166:169], v[50:53]
	v_mfma_f32_16x16x32_bf16 v[38:41], v[78:81], v[208:211], v[38:41]
	v_mfma_f32_16x16x32_bf16 v[34:37], v[86:89], v[208:211], v[34:37]
	v_mfma_f32_16x16x32_bf16 v[22:25], v[78:81], v[216:219], v[22:25]
	v_mfma_f32_16x16x32_bf16 v[14:17], v[86:89], v[216:219], v[14:17]
	v_mfma_f32_16x16x32_bf16 v[18:21], v[78:81], v[224:227], v[18:21]
	v_mfma_f32_16x16x32_bf16 v[10:13], v[86:89], v[224:227], v[10:13]
	v_mfma_f32_16x16x32_bf16 v[62:65], v[90:93], v[162:165], v[62:65]
	v_mfma_f32_16x16x32_bf16 v[58:61], v[98:101], v[162:165], v[58:61]
	v_mfma_f32_16x16x32_bf16 v[46:49], v[90:93], v[204:207], v[46:49]
	v_mfma_f32_16x16x32_bf16 v[42:45], v[98:101], v[204:207], v[42:45]
	v_mfma_f32_16x16x32_bf16 v[30:33], v[90:93], v[212:215], v[30:33]
	v_mfma_f32_16x16x32_bf16 v[26:29], v[98:101], v[212:215], v[26:29]
	v_mfma_f32_16x16x32_bf16 v[6:9], v[90:93], v[220:223], v[6:9]
	v_mfma_f32_16x16x32_bf16 v[2:5], v[98:101], v[220:223], v[2:5]
	v_mfma_f32_16x16x32_bf16 v[62:65], v[94:97], v[166:169], v[62:65]
	v_mfma_f32_16x16x32_bf16 v[58:61], v[106:109], v[166:169], v[58:61]
	v_mfma_f32_16x16x32_bf16 v[46:49], v[94:97], v[208:211], v[46:49]
	v_mfma_f32_16x16x32_bf16 v[42:45], v[106:109], v[208:211], v[42:45]
	v_mfma_f32_16x16x32_bf16 v[30:33], v[94:97], v[216:219], v[30:33]
	v_mfma_f32_16x16x32_bf16 v[26:29], v[106:109], v[216:219], v[26:29]
	v_mfma_f32_16x16x32_bf16 v[6:9], v[94:97], v[224:227], v[6:9]
	v_mfma_f32_16x16x32_bf16 v[2:5], v[106:109], v[224:227], v[2:5]
	s_barrier
; #define PG8_STAGE(bufoff, gbase, voff) do { _Pragma("unroll") for (int _i = 0; _i < 2; ++_i) \
;         __builtin_amdgcn_global_load_lds((const unsigned*)((const char*)(gbase) + (voff)[_i]), (PG8_LAS unsigned*)(lds + (bufoff) + ldsw + _i * 8192), 16, 0, 0); } while (0)
; #define PG8_LDA(dst, b, h) do { _Pragma("unroll") for (int m = 0; m < 4; ++m) _Pragma("unroll") for (int k = 0; k < 2; ++k) dst[m][k] = *(const PG8_LAS bf16x8*)(lds + PG8_SA(b, h) + aoff + m * 2048 + k * 1024); } while (0)
; #define PG8_WAIT_V(n) asm volatile("s_waitcnt vmcnt(" #n ")" ::: "memory")
; #define PG8_WAIT_L(n) asm volatile("s_waitcnt lgkmcnt(" #n ")" ::: "memory")
; #define PG8_BAR __builtin_amdgcn_s_barrier()
; template <class Epi, class Sched, bool ALIGN_EPI = false, bool SP2 = false, bool PAIR_ACC = false>
; __device__ __forceinline__ void gemm_phase(PG8_LAS unsigned char* lds, const Gemm g, const Sched& S, const Epi& E) {
;     ...
;         for (int t = 0; t < nt; t += 2) {
;             const bool last = (t == nt - 2);
;             const char* a1 = cA + (size_t)(t + 1) * kstep;
;             const char* a2 = last ? nA : cA + (size_t)(t + 2) * kstep; const char* b2 = last ? nB : cB + (size_t)(t + 2) * kstep;
;             const char* a3 = a2 + kstep; const char* b3 = b2 + kstep;
;             if (last && has_next) S.a_ready(nxt);
;             if constexpr (SP2) {
;             PG8_LDB(B0, 0, 0); PG8_LDB(B1, 0, 1); PG8_SCHED; PG8_LDA(At, 0, 0); PG8_STAGE(PG8_SA(1, 1), a1 + hstep, voffA);
;             PG8_WAIT_V(8); PG8_WAIT_L(0); PG8_BAR; PG8_MMA(0, 0, At, B0); PG8_MMA(0, 1, At, B1); PG8_BAR; PG8_SCHED;
;             PG8_LDA(At, 0, 1); PG8_STAGE(PG8_SB(0, 0), b2, voffB); PG8_STAGE(PG8_SB(0, 1), b2 + hstep, voffB); PG8_STAGE(PG8_SA(0, 0), a2, voffA);
;             PG8_WAIT_V(8); PG8_WAIT_L(0); PG8_BAR; PG8_MMA(1, 0, At, B0); PG8_MMA(1, 1, At, B1); PG8_BAR; PG8_SCHED;
;             PG8_LDB(B0, 1, 0); PG8_LDB(B1, 1, 1); PG8_SCHED; PG8_LDA(At, 1, 0); PG8_STAGE(PG8_SA(0, 1), a2 + hstep, voffA);
;             PG8_WAIT_V(8); PG8_WAIT_L(0); PG8_BAR; PG8_MMA(0, 0, At, B0); PG8_MMA(0, 1, At, B1); PG8_BAR; PG8_SCHED;
;             PG8_LDA(At, 1, 1); PG8_STAGE(PG8_SB(1, 0), b3, voffB); PG8_STAGE(PG8_SB(1, 1), b3 + hstep, voffB); PG8_STAGE(PG8_SA(1, 0), a3, voffA);
;             PG8_WAIT_V(8); PG8_WAIT_L(0); PG8_BAR; PG8_MMA(1, 0, At, B0); PG8_MMA(1, 1, At, B1); PG8_BAR; PG8_SCHED;
.Lpeel_mid_1737:
	s_add_i32 s80, 0, 0x18000
	s_add_i32 s81, 0, 0x1c000
	v_add_u32_e32 v86, s80, v194
	v_add_u32_e32 v106, s81, v194
	ds_read_b128 v[74:77], v86
	ds_read_b128 v[78:81], v86 offset:1024
	ds_read_b128 v[82:85], v86 offset:2048
	ds_read_b128 v[86:89], v86 offset:3072
	ds_read_b128 v[90:93], v106
	ds_read_b128 v[94:97], v106 offset:1024
	ds_read_b128 v[98:101], v106 offset:2048
	ds_read_b128 v[106:109], v106 offset:3072
	s_add_u32 s62, s62, 0x40000
	s_addc_u32 s63, s63, 0
	s_mov_b32 m0, s49
	v_lshl_add_u64 v[232:233], s[62:63], 0, v[178:179]
	ds_read_b128 v[162:165], v198 offset:32768
	ds_read_b128 v[166:169], v198 offset:33792
	ds_read_b128 v[204:207], v198 offset:34816
	ds_read_b128 v[208:211], v198 offset:35840
	ds_read_b128 v[212:215], v198 offset:36864
	ds_read_b128 v[216:219], v198 offset:37888
	ds_read_b128 v[220:223], v198 offset:38912
	ds_read_b128 v[224:227], v198 offset:39936
	global_load_lds_dwordx4 v[232:233], off
	v_lshl_add_u64 v[232:233], s[62:63], 0, v[174:175]
	s_mov_b32 m0, s64
	s_nop 0
	global_load_lds_dwordx4 v[232:233], off
	s_waitcnt vmcnt(8)
	s_waitcnt lgkmcnt(0)
	s_barrier
	v_mfma_f32_16x16x32_bf16 v[150:153], v[74:77], v[162:165], v[150:153]
	v_mfma_f32_16x16x32_bf16 v[146:149], v[82:85], v[162:165], v[146:149]
	v_mfma_f32_16x16x32_bf16 v[134:137], v[74:77], v[204:207], v[134:137]
	v_mfma_f32_16x16x32_bf16 v[130:133], v[82:85], v[204:207], v[130:133]
	v_mfma_f32_16x16x32_bf16 v[118:121], v[74:77], v[212:215], v[118:121]
	v_mfma_f32_16x16x32_bf16 v[110:113], v[82:85], v[212:215], v[110:113]
	v_mfma_f32_16x16x32_bf16 v[114:117], v[74:77], v[220:223], v[114:117]
	v_mfma_f32_16x16x32_bf16 v[102:105], v[82:85], v[220:223], v[102:105]
	v_mfma_f32_16x16x32_bf16 v[150:153], v[78:81], v[166:169], v[150:153]
	v_mfma_f32_16x16x32_bf16 v[146:149], v[86:89], v[166:169], v[146:149]
	v_mfma_f32_16x16x32_bf16 v[134:137], v[78:81], v[208:211], v[134:137]
	v_mfma_f32_16x16x32_bf16 v[130:133], v[86:89], v[208:211], v[130:133]
	v_mfma_f32_16x16x32_bf16 v[118:121], v[78:81], v[216:219], v[118:121]
	v_mfma_f32_16x16x32_bf16 v[110:113], v[86:89], v[216:219], v[110:113]
	v_mfma_f32_16x16x32_bf16 v[114:117], v[78:81], v[224:227], v[114:117]
	v_mfma_f32_16x16x32_bf16 v[102:105], v[86:89], v[224:227], v[102:105]
	v_mfma_f32_16x16x32_bf16 v[158:161], v[90:93], v[162:165], v[158:161]
	v_mfma_f32_16x16x32_bf16 v[154:157], v[98:101], v[162:165], v[154:157]
	v_mfma_f32_16x16x32_bf16 v[142:145], v[90:93], v[204:207], v[142:145]
	v_mfma_f32_16x16x32_bf16 v[138:141], v[98:101], v[204:207], v[138:141]
	v_mfma_f32_16x16x32_bf16 v[126:129], v[90:93], v[212:215], v[126:129]
	v_mfma_f32_16x16x32_bf16 v[122:125], v[98:101], v[212:215], v[122:125]
	v_mfma_f32_16x16x32_bf16 v[70:73], v[90:93], v[220:223], v[70:73]
	v_mfma_f32_16x16x32_bf16 v[66:69], v[98:101], v[220:223], v[66:69]
	v_mfma_f32_16x16x32_bf16 v[158:161], v[94:97], v[166:169], v[158:161]
	v_mfma_f32_16x16x32_bf16 v[154:157], v[106:109], v[166:169], v[154:157]
	v_mfma_f32_16x16x32_bf16 v[142:145], v[94:97], v[208:211], v[142:145]
	v_mfma_f32_16x16x32_bf16 v[138:141], v[106:109], v[208:211], v[138:141]
	v_mfma_f32_16x16x32_bf16 v[126:129], v[94:97], v[216:219], v[126:129]
	v_mfma_f32_16x16x32_bf16 v[122:125], v[106:109], v[216:219], v[122:125]
	v_mfma_f32_16x16x32_bf16 v[70:73], v[94:97], v[224:227], v[70:73]
	v_mfma_f32_16x16x32_bf16 v[66:69], v[106:109], v[224:227], v[66:69]
	s_barrier
	s_add_i32 s62, s80, s34
	v_lshl_add_u64 v[170:171], v[170:171], 0, s[30:31]
	s_mov_b32 m0, s62
	ds_read_b128 v[162:165], v198 offset:49152
	ds_read_b128 v[166:169], v198 offset:50176
	ds_read_b128 v[204:207], v198 offset:51200
	ds_read_b128 v[208:211], v198 offset:52224
	ds_read_b128 v[212:215], v198 offset:53248
	ds_read_b128 v[216:219], v198 offset:54272
	ds_read_b128 v[220:223], v198 offset:55296
	ds_read_b128 v[224:227], v198 offset:56320
	global_load_lds_dwordx4 v[170:171], off
	s_add_i32 m0, s62, 0x2000
	s_add_u32 s60, s60, 0x40080
	v_lshl_add_u64 v[170:171], v[192:193], 0, s[30:31]
	s_addc_u32 s61, s61, 0
	s_add_i32 s62, s81, s34
	global_load_lds_dwordx4 v[170:171], off
	v_lshl_add_u64 v[170:171], s[60:61], 0, v[176:177]
	s_mov_b32 m0, s62
	s_nop 0
	global_load_lds_dwordx4 v[170:171], off
	v_lshl_add_u64 v[170:171], s[60:61], 0, v[172:173]
	s_add_i32 m0, s62, 0x2000
	s_nop 0
	global_load_lds_dwordx4 v[170:171], off
	v_lshl_add_u64 v[170:171], v[228:229], 0, s[30:31]
	s_mov_b32 m0, s68
	s_nop 0
	global_load_lds_dwordx4 v[170:171], off
	v_lshl_add_u64 v[170:171], v[230:231], 0, s[30:31]
	s_mov_b32 m0, s69
	s_nop 0
	global_load_lds_dwordx4 v[170:171], off
	s_waitcnt vmcnt(8)
	s_waitcnt lgkmcnt(0)
	s_barrier
	v_mfma_f32_16x16x32_bf16 v[54:57], v[74:77], v[162:165], v[54:57]
	v_mfma_f32_16x16x32_bf16 v[50:53], v[82:85], v[162:165], v[50:53]
	v_mfma_f32_16x16x32_bf16 v[38:41], v[74:77], v[204:207], v[38:41]
	v_mfma_f32_16x16x32_bf16 v[34:37], v[82:85], v[204:207], v[34:37]
	v_mfma_f32_16x16x32_bf16 v[22:25], v[74:77], v[212:215], v[22:25]
	v_mfma_f32_16x16x32_bf16 v[14:17], v[82:85], v[212:215], v[14:17]
	v_mfma_f32_16x16x32_bf16 v[18:21], v[74:77], v[220:223], v[18:21]
	v_mfma_f32_16x16x32_bf16 v[10:13], v[82:85], v[220:223], v[10:13]
	v_mfma_f32_16x16x32_bf16 v[54:57], v[78:81], v[166:169], v[54:57]
	v_mfma_f32_16x16x32_bf16 v[50:53], v[86:89], v[166:169], v[50:53]
	v_mfma_f32_16x16x32_bf16 v[38:41], v[78:81], v[208:211], v[38:41]
	v_mfma_f32_16x16x32_bf16 v[34:37], v[86:89], v[208:211], v[34:37]
	v_mfma_f32_16x16x32_bf16 v[22:25], v[78:81], v[216:219], v[22:25]
	v_mfma_f32_16x16x32_bf16 v[14:17], v[86:89], v[216:219], v[14:17]
	v_mfma_f32_16x16x32_bf16 v[18:21], v[78:81], v[224:227], v[18:21]
	v_mfma_f32_16x16x32_bf16 v[10:13], v[86:89], v[224:227], v[10:13]
	v_mfma_f32_16x16x32_bf16 v[62:65], v[90:93], v[162:165], v[62:65]
	v_mfma_f32_16x16x32_bf16 v[58:61], v[98:101], v[162:165], v[58:61]
	v_mfma_f32_16x16x32_bf16 v[46:49], v[90:93], v[204:207], v[46:49]
	v_mfma_f32_16x16x32_bf16 v[42:45], v[98:101], v[204:207], v[42:45]
	v_mfma_f32_16x16x32_bf16 v[30:33], v[90:93], v[212:215], v[30:33]
	v_mfma_f32_16x16x32_bf16 v[26:29], v[98:101], v[212:215], v[26:29]
	v_mfma_f32_16x16x32_bf16 v[6:9], v[90:93], v[220:223], v[6:9]
	v_mfma_f32_16x16x32_bf16 v[2:5], v[98:101], v[220:223], v[2:5]
	v_mfma_f32_16x16x32_bf16 v[62:65], v[94:97], v[166:169], v[62:65]
	v_mfma_f32_16x16x32_bf16 v[58:61], v[106:109], v[166:169], v[58:61]
	v_mfma_f32_16x16x32_bf16 v[46:49], v[94:97], v[208:211], v[46:49]
	v_mfma_f32_16x16x32_bf16 v[42:45], v[106:109], v[208:211], v[42:45]
	v_mfma_f32_16x16x32_bf16 v[30:33], v[94:97], v[216:219], v[30:33]
	v_mfma_f32_16x16x32_bf16 v[26:29], v[106:109], v[216:219], v[26:29]
	v_mfma_f32_16x16x32_bf16 v[6:9], v[94:97], v[224:227], v[6:9]
	v_mfma_f32_16x16x32_bf16 v[2:5], v[106:109], v[224:227], v[2:5]
	s_barrier
	s_add_i32 s79, s79, 2
	s_add_u32 s10, s10, 0x100
	s_addc_u32 s11, s11, 0
	s_add_u32 s77, s77, 0x100
	s_addc_u32 s78, s78, 0
	s_cmp_gt_u32 s79, 13
	s_cbranch_scc0 .LBB0_1737
	s_and_b64 vcc, exec, s[38:39]
	s_cbranch_vccz .LBB0_1740
	s_barrier

; #define PG8_STAGE(bufoff, gbase, voff) do { _Pragma("unroll") for (int _i = 0; _i < 2; ++_i) \
;         __builtin_amdgcn_global_load_lds((const unsigned*)((const char*)(gbase) + (voff)[_i]), (PG8_LAS unsigned*)(lds + (bufoff) + ldsw + _i * 8192), 16, 0, 0); } while (0)
; #define PG8_LDA(dst, b, h) do { _Pragma("unroll") for (int m = 0; m < 4; ++m) _Pragma("unroll") for (int k = 0; k < 2; ++k) dst[m][k] = *(const PG8_LAS bf16x8*)(lds + PG8_SA(b, h) + aoff + m * 2048 + k * 1024); } while (0)
; #define PG8_LDB(dst, b, h) do { _Pragma("unroll") for (int n = 0; n < 2; ++n) _Pragma("unroll") for (int k = 0; k < 2; ++k) dst[n][k] = *(const PG8_LAS bf16x8*)(lds + PG8_SB(b, h) + boff + n * 2048 + k * 1024); } while (0)
; #define PG8_MMA(ai, bj, At, Bt) do { __builtin_amdgcn_s_setprio(1); _Pragma("unroll") for (int m = 0; m < 4; ++m) _Pragma("unroll") for (int n = 0; n < 2; ++n) _Pragma("unroll") for (int k = 0; k < 2; ++k) \
;         acc[ai][bj][m][n] = __builtin_amdgcn_mfma_f32_16x16x32_bf16(Bt[n][k], At[m][k], acc[ai][bj][m][n], 0, 0, 0); __builtin_amdgcn_s_setprio(0); } while (0)
; #define PG8_WAIT_V(n) asm volatile("s_waitcnt vmcnt(" #n ")" ::: "memory")
; #define PG8_WAIT_L(n) asm volatile("s_waitcnt lgkmcnt(" #n ")" ::: "memory")
; template <class Epi, class Sched, bool ALIGN_EPI = false, bool SP2 = false, bool PAIR_ACC = false>
; __device__ __forceinline__ void gemm_phase(PG8_LAS unsigned char* lds, const Gemm g, const Sched& S, const Epi& E) {
;     ...
;             const bool last = (t == nt - 2);
;             const char* a1 = cA + (size_t)(t + 1) * kstep;
;             const char* a2 = last ? nA : cA + (size_t)(t + 2) * kstep; const char* b2 = last ? nB : cB + (size_t)(t + 2) * kstep;
;             const char* a3 = a2 + kstep; const char* b3 = b2 + kstep;
;             if (last && has_next) S.a_ready(nxt);
;             if constexpr (SP2) {
;             PG8_LDB(B0, 0, 0); PG8_LDB(B1, 0, 1); PG8_SCHED; PG8_LDA(At, 0, 0); PG8_STAGE(PG8_SA(1, 1), a1 + hstep, voffA);
;             PG8_WAIT_V(8); PG8_WAIT_L(0); PG8_BAR; PG8_MMA(0, 0, At, B0); PG8_MMA(0, 1, At, B1); PG8_BAR; PG8_SCHED;
;             PG8_LDA(At, 0, 1); PG8_STAGE(PG8_SB(0, 0), b2, voffB); PG8_STAGE(PG8_SB(0, 1), b2 + hstep, voffB); PG8_STAGE(PG8_SA(0, 0), a2, voffA);
;             PG8_WAIT_V(8); PG8_WAIT_L(0); PG8_BAR; PG8_MMA(1, 0, At, B0); PG8_MMA(1, 1, At, B1); PG8_BAR; PG8_SCHED;
.LBB0_1840:
	v_add_u32_e32 v164, s45, v150
	ds_read_b128 v[152:155], v164
	ds_read_b128 v[156:159], v164 offset:1024
	ds_read_b128 v[160:163], v164 offset:2048
	ds_read_b128 v[168:171], v164 offset:3072
	v_add_u32_e32 v164, s46, v150
	s_add_u32 s26, s18, s24
	ds_read_b128 v[172:175], v164
	ds_read_b128 v[176:179], v164 offset:1024
	ds_read_b128 v[180:183], v164 offset:2048
	ds_read_b128 v[184:187], v164 offset:3072
	s_addc_u32 s27, s19, s25
	s_add_u32 s26, s26, 0x100
	s_addc_u32 s27, s27, 0
	s_add_u32 s53, s50, s24
	s_addc_u32 s54, s51, s25
	s_cmpk_eq_i32 s24, 0x1500
	s_cselect_b32 s29, s23, s27
	s_cselect_b32 s28, s22, s26
	s_cselect_b32 s27, s5, s54
	s_cselect_b32 s26, s4, s53
	v_lshl_add_u64 v[164:165], v[146:147], 0, s[24:25]
	s_add_i32 m0, s38, 0xc000
	ds_read_b128 v[188:191], v151
	ds_read_b128 v[192:195], v151 offset:1024
	ds_read_b128 v[196:199], v151 offset:2048
	ds_read_b128 v[200:203], v151 offset:3072
	ds_read_b128 v[204:207], v151 offset:4096
	ds_read_b128 v[208:211], v151 offset:5120
	ds_read_b128 v[212:215], v151 offset:6144
	ds_read_b128 v[216:219], v151 offset:7168
	global_load_lds_dwordx4 v[164:165], off
	v_lshl_add_u64 v[164:165], v[148:149], 0, s[24:25]
	s_add_i32 m0, s38, 0xe000
	s_nop 0
	global_load_lds_dwordx4 v[164:165], off
	s_waitcnt vmcnt(8)
	s_waitcnt lgkmcnt(0)
	s_barrier
	v_mfma_f32_16x16x32_bf16 v[102:105], v[152:155], v[188:191], v[102:105]
	v_mfma_f32_16x16x32_bf16 v[106:109], v[160:163], v[188:191], v[106:109]
	v_mfma_f32_16x16x32_bf16 v[114:117], v[152:155], v[196:199], v[114:117]
	v_mfma_f32_16x16x32_bf16 v[118:121], v[160:163], v[196:199], v[118:121]
	v_mfma_f32_16x16x32_bf16 v[126:129], v[152:155], v[204:207], v[126:129]
	v_mfma_f32_16x16x32_bf16 v[122:125], v[160:163], v[204:207], v[122:125]
	v_mfma_f32_16x16x32_bf16 v[78:81], v[152:155], v[212:215], v[78:81]
	v_mfma_f32_16x16x32_bf16 v[74:77], v[160:163], v[212:215], v[74:77]
	v_mfma_f32_16x16x32_bf16 v[102:105], v[156:159], v[192:195], v[102:105]
	v_mfma_f32_16x16x32_bf16 v[106:109], v[168:171], v[192:195], v[106:109]
	v_mfma_f32_16x16x32_bf16 v[114:117], v[156:159], v[200:203], v[114:117]
	v_mfma_f32_16x16x32_bf16 v[118:121], v[168:171], v[200:203], v[118:121]
	v_mfma_f32_16x16x32_bf16 v[126:129], v[156:159], v[208:211], v[126:129]
	v_mfma_f32_16x16x32_bf16 v[122:125], v[168:171], v[208:211], v[122:125]
	v_mfma_f32_16x16x32_bf16 v[78:81], v[156:159], v[216:219], v[78:81]
	v_mfma_f32_16x16x32_bf16 v[74:77], v[168:171], v[216:219], v[74:77]
	v_mfma_f32_16x16x32_bf16 v[86:89], v[172:175], v[188:191], v[86:89]
	v_mfma_f32_16x16x32_bf16 v[82:85], v[180:183], v[188:191], v[82:85]
	v_mfma_f32_16x16x32_bf16 v[94:97], v[172:175], v[196:199], v[94:97]
	v_mfma_f32_16x16x32_bf16 v[90:93], v[180:183], v[196:199], v[90:93]
	v_mfma_f32_16x16x32_bf16 v[110:113], v[172:175], v[204:207], v[110:113]
	v_mfma_f32_16x16x32_bf16 v[98:101], v[180:183], v[204:207], v[98:101]
	v_mfma_f32_16x16x32_bf16 v[70:73], v[172:175], v[212:215], v[70:73]
	v_mfma_f32_16x16x32_bf16 v[66:69], v[180:183], v[212:215], v[66:69]
	v_mfma_f32_16x16x32_bf16 v[86:89], v[176:179], v[192:195], v[86:89]
	v_mfma_f32_16x16x32_bf16 v[82:85], v[184:187], v[192:195], v[82:85]
	v_mfma_f32_16x16x32_bf16 v[94:97], v[176:179], v[200:203], v[94:97]
	v_mfma_f32_16x16x32_bf16 v[90:93], v[184:187], v[200:203], v[90:93]
	v_mfma_f32_16x16x32_bf16 v[110:113], v[176:179], v[208:211], v[110:113]
	v_mfma_f32_16x16x32_bf16 v[98:101], v[184:187], v[208:211], v[98:101]
	v_mfma_f32_16x16x32_bf16 v[70:73], v[176:179], v[216:219], v[70:73]
	v_mfma_f32_16x16x32_bf16 v[66:69], v[184:187], v[216:219], v[66:69]
	s_barrier
	s_add_i32 s53, s45, s37
	v_lshl_add_u64 v[164:165], s[26:27], 0, v[132:133]
	s_mov_b32 m0, s53
	ds_read_b128 v[188:191], v151 offset:16384
	ds_read_b128 v[192:195], v151 offset:17408
	ds_read_b128 v[196:199], v151 offset:18432
	ds_read_b128 v[200:203], v151 offset:19456
	ds_read_b128 v[204:207], v151 offset:20480
	ds_read_b128 v[208:211], v151 offset:21504
	ds_read_b128 v[212:215], v151 offset:22528
	ds_read_b128 v[216:219], v151 offset:23552
	global_load_lds_dwordx4 v[164:165], off
	s_add_i32 m0, s53, 0x2000
	s_add_u32 s54, s26, 0xb0000
	v_lshl_add_u64 v[220:221], s[26:27], 0, v[136:137]
	s_addc_u32 s55, s27, 0
	s_add_i32 s53, s46, s37
	global_load_lds_dwordx4 v[220:221], off
	v_lshl_add_u64 v[222:223], s[54:55], 0, v[132:133]
	s_mov_b32 m0, s53
	v_lshl_add_u64 v[224:225], s[28:29], 0, v[134:135]
	global_load_lds_dwordx4 v[222:223], off
	v_lshl_add_u64 v[222:223], s[54:55], 0, v[136:137]
	s_add_i32 m0, s53, 0x2000
	s_nop 0
	global_load_lds_dwordx4 v[222:223], off
	v_lshl_add_u64 v[222:223], s[28:29], 0, v[130:131]
	s_mov_b32 m0, s38
	s_nop 0
	global_load_lds_dwordx4 v[222:223], off
	s_mov_b32 m0, s39
	s_nop 0
	global_load_lds_dwordx4 v[224:225], off
	s_waitcnt vmcnt(8)
	s_waitcnt lgkmcnt(0)
	s_barrier
; #define PG8_STAGE(bufoff, gbase, voff) do { _Pragma("unroll") for (int _i = 0; _i < 2; ++_i) \
;         __builtin_amdgcn_global_load_lds((const unsigned*)((const char*)(gbase) + (voff)[_i]), (PG8_LAS unsigned*)(lds + (bufoff) + ldsw + _i * 8192), 16, 0, 0); } while (0)
; #define PG8_LDA(dst, b, h) do { _Pragma("unroll") for (int m = 0; m < 4; ++m) _Pragma("unroll") for (int k = 0; k < 2; ++k) dst[m][k] = *(const PG8_LAS bf16x8*)(lds + PG8_SA(b, h) + aoff + m * 2048 + k * 1024); } while (0)
; #define PG8_LDB(dst, b, h) do { _Pragma("unroll") for (int n = 0; n < 2; ++n) _Pragma("unroll") for (int k = 0; k < 2; ++k) dst[n][k] = *(const PG8_LAS bf16x8*)(lds + PG8_SB(b, h) + boff + n * 2048 + k * 1024); } while (0)
; #define PG8_MMA(ai, bj, At, Bt) do { __builtin_amdgcn_s_setprio(1); _Pragma("unroll") for (int m = 0; m < 4; ++m) _Pragma("unroll") for (int n = 0; n < 2; ++n) _Pragma("unroll") for (int k = 0; k < 2; ++k) \
;         acc[ai][bj][m][n] = __builtin_amdgcn_mfma_f32_16x16x32_bf16(Bt[n][k], At[m][k], acc[ai][bj][m][n], 0, 0, 0); __builtin_amdgcn_s_setprio(0); } while (0)
; #define PG8_WAIT_V(n) asm volatile("s_waitcnt vmcnt(" #n ")" ::: "memory")
; #define PG8_WAIT_L(n) asm volatile("s_waitcnt lgkmcnt(" #n ")" ::: "memory")
; #define PG8_BAR __builtin_amdgcn_s_barrier()
; #define PG8_SCHED __builtin_amdgcn_sched_barrier(0)
; template <class Epi, class Sched, bool ALIGN_EPI = false, bool SP2 = false, bool PAIR_ACC = false>
; __device__ __forceinline__ void gemm_phase(PG8_LAS unsigned char* lds, const Gemm g, const Sched& S, const Epi& E) {
;     ...
;             PG8_WAIT_V(8); PG8_WAIT_L(0); PG8_BAR; PG8_MMA(1, 0, At, B0); PG8_MMA(1, 1, At, B1); PG8_BAR; PG8_SCHED;
;             PG8_LDB(B0, 1, 0); PG8_LDB(B1, 1, 1); PG8_SCHED; PG8_LDA(At, 1, 0); PG8_STAGE(PG8_SA(0, 1), a2 + hstep, voffA);
;             PG8_WAIT_V(8); PG8_WAIT_L(0); PG8_BAR; PG8_MMA(0, 0, At, B0); PG8_MMA(0, 1, At, B1); PG8_BAR; PG8_SCHED;
	v_mfma_f32_16x16x32_bf16 v[62:65], v[152:155], v[188:191], v[62:65]
	v_mfma_f32_16x16x32_bf16 v[58:61], v[160:163], v[188:191], v[58:61]
	v_mfma_f32_16x16x32_bf16 v[46:49], v[152:155], v[196:199], v[46:49]
	v_mfma_f32_16x16x32_bf16 v[42:45], v[160:163], v[196:199], v[42:45]
	v_mfma_f32_16x16x32_bf16 v[30:33], v[152:155], v[204:207], v[30:33]
	v_mfma_f32_16x16x32_bf16 v[26:29], v[160:163], v[204:207], v[26:29]
	v_mfma_f32_16x16x32_bf16 v[14:17], v[152:155], v[212:215], v[14:17]
	v_mfma_f32_16x16x32_bf16 v[10:13], v[160:163], v[212:215], v[10:13]
	v_mfma_f32_16x16x32_bf16 v[62:65], v[156:159], v[192:195], v[62:65]
	v_mfma_f32_16x16x32_bf16 v[58:61], v[168:171], v[192:195], v[58:61]
	v_mfma_f32_16x16x32_bf16 v[46:49], v[156:159], v[200:203], v[46:49]
	v_mfma_f32_16x16x32_bf16 v[42:45], v[168:171], v[200:203], v[42:45]
	v_mfma_f32_16x16x32_bf16 v[30:33], v[156:159], v[208:211], v[30:33]
	v_mfma_f32_16x16x32_bf16 v[26:29], v[168:171], v[208:211], v[26:29]
	v_mfma_f32_16x16x32_bf16 v[14:17], v[156:159], v[216:219], v[14:17]
	v_mfma_f32_16x16x32_bf16 v[10:13], v[168:171], v[216:219], v[10:13]
	v_mfma_f32_16x16x32_bf16 v[54:57], v[172:175], v[188:191], v[54:57]
	v_mfma_f32_16x16x32_bf16 v[50:53], v[180:183], v[188:191], v[50:53]
	v_mfma_f32_16x16x32_bf16 v[38:41], v[172:175], v[196:199], v[38:41]
	v_mfma_f32_16x16x32_bf16 v[34:37], v[180:183], v[196:199], v[34:37]
	v_mfma_f32_16x16x32_bf16 v[22:25], v[172:175], v[204:207], v[22:25]
	v_mfma_f32_16x16x32_bf16 v[18:21], v[180:183], v[204:207], v[18:21]
	v_mfma_f32_16x16x32_bf16 v[6:9], v[172:175], v[212:215], v[6:9]
	v_mfma_f32_16x16x32_bf16 v[2:5], v[180:183], v[212:215], v[2:5]
	v_mfma_f32_16x16x32_bf16 v[54:57], v[176:179], v[192:195], v[54:57]
	v_mfma_f32_16x16x32_bf16 v[50:53], v[184:187], v[192:195], v[50:53]
	v_mfma_f32_16x16x32_bf16 v[38:41], v[176:179], v[200:203], v[38:41]
	v_mfma_f32_16x16x32_bf16 v[34:37], v[184:187], v[200:203], v[34:37]
	v_mfma_f32_16x16x32_bf16 v[22:25], v[176:179], v[208:211], v[22:25]
	v_mfma_f32_16x16x32_bf16 v[18:21], v[184:187], v[208:211], v[18:21]
	v_mfma_f32_16x16x32_bf16 v[6:9], v[176:179], v[216:219], v[6:9]
	v_mfma_f32_16x16x32_bf16 v[2:5], v[184:187], v[216:219], v[2:5]
	s_barrier
	s_add_i32 s53, 0, 0x18000
	s_add_i32 s54, 0, 0x1c000
	v_add_u32_e32 v168, s53, v150
	v_add_u32_e32 v184, s54, v150
	ds_read_b128 v[152:155], v168
	ds_read_b128 v[156:159], v168 offset:1024
	ds_read_b128 v[160:163], v168 offset:2048
	ds_read_b128 v[168:171], v168 offset:3072
	ds_read_b128 v[172:175], v184
	ds_read_b128 v[176:179], v184 offset:1024
	ds_read_b128 v[180:183], v184 offset:2048
	ds_read_b128 v[184:187], v184 offset:3072
	s_add_u32 s28, s28, 0xb0000
	s_addc_u32 s29, s29, 0
	s_mov_b32 m0, s40
	v_lshl_add_u64 v[226:227], s[28:29], 0, v[130:131]
	ds_read_b128 v[188:191], v151 offset:32768
	ds_read_b128 v[192:195], v151 offset:33792
	ds_read_b128 v[196:199], v151 offset:34816
	ds_read_b128 v[200:203], v151 offset:35840
	ds_read_b128 v[204:207], v151 offset:36864
	ds_read_b128 v[208:211], v151 offset:37888
	ds_read_b128 v[212:215], v151 offset:38912
	ds_read_b128 v[216:219], v151 offset:39936
	global_load_lds_dwordx4 v[226:227], off
	v_lshl_add_u64 v[226:227], s[28:29], 0, v[134:135]
	s_mov_b32 m0, s41
	s_nop 0
	global_load_lds_dwordx4 v[226:227], off
	s_waitcnt vmcnt(8)
	s_waitcnt lgkmcnt(0)
	s_barrier
	v_mfma_f32_16x16x32_bf16 v[102:105], v[152:155], v[188:191], v[102:105]
	v_mfma_f32_16x16x32_bf16 v[106:109], v[160:163], v[188:191], v[106:109]
	v_mfma_f32_16x16x32_bf16 v[114:117], v[152:155], v[196:199], v[114:117]
	v_mfma_f32_16x16x32_bf16 v[118:121], v[160:163], v[196:199], v[118:121]
	v_mfma_f32_16x16x32_bf16 v[126:129], v[152:155], v[204:207], v[126:129]
	v_mfma_f32_16x16x32_bf16 v[122:125], v[160:163], v[204:207], v[122:125]
	v_mfma_f32_16x16x32_bf16 v[78:81], v[152:155], v[212:215], v[78:81]
	v_mfma_f32_16x16x32_bf16 v[74:77], v[160:163], v[212:215], v[74:77]
	v_mfma_f32_16x16x32_bf16 v[102:105], v[156:159], v[192:195], v[102:105]
	v_mfma_f32_16x16x32_bf16 v[106:109], v[168:171], v[192:195], v[106:109]
	v_mfma_f32_16x16x32_bf16 v[114:117], v[156:159], v[200:203], v[114:117]
	v_mfma_f32_16x16x32_bf16 v[118:121], v[168:171], v[200:203], v[118:121]
	v_mfma_f32_16x16x32_bf16 v[126:129], v[156:159], v[208:211], v[126:129]
	v_mfma_f32_16x16x32_bf16 v[122:125], v[168:171], v[208:211], v[122:125]
	v_mfma_f32_16x16x32_bf16 v[78:81], v[156:159], v[216:219], v[78:81]
	v_mfma_f32_16x16x32_bf16 v[74:77], v[168:171], v[216:219], v[74:77]
	v_mfma_f32_16x16x32_bf16 v[86:89], v[172:175], v[188:191], v[86:89]
	v_mfma_f32_16x16x32_bf16 v[82:85], v[180:183], v[188:191], v[82:85]
	v_mfma_f32_16x16x32_bf16 v[94:97], v[172:175], v[196:199], v[94:97]
	v_mfma_f32_16x16x32_bf16 v[90:93], v[180:183], v[196:199], v[90:93]
	v_mfma_f32_16x16x32_bf16 v[110:113], v[172:175], v[204:207], v[110:113]
	v_mfma_f32_16x16x32_bf16 v[98:101], v[180:183], v[204:207], v[98:101]
	v_mfma_f32_16x16x32_bf16 v[70:73], v[172:175], v[212:215], v[70:73]
	v_mfma_f32_16x16x32_bf16 v[66:69], v[180:183], v[212:215], v[66:69]
	v_mfma_f32_16x16x32_bf16 v[86:89], v[176:179], v[192:195], v[86:89]
	v_mfma_f32_16x16x32_bf16 v[82:85], v[184:187], v[192:195], v[82:85]
	v_mfma_f32_16x16x32_bf16 v[94:97], v[176:179], v[200:203], v[94:97]
	v_mfma_f32_16x16x32_bf16 v[90:93], v[184:187], v[200:203], v[90:93]
	v_mfma_f32_16x16x32_bf16 v[110:113], v[176:179], v[208:211], v[110:113]
	v_mfma_f32_16x16x32_bf16 v[98:101], v[184:187], v[208:211], v[98:101]
	v_mfma_f32_16x16x32_bf16 v[70:73], v[176:179], v[216:219], v[70:73]
	v_mfma_f32_16x16x32_bf16 v[66:69], v[184:187], v[216:219], v[66:69]
	s_barrier
; #define PG8_STAGE(bufoff, gbase, voff) do { _Pragma("unroll") for (int _i = 0; _i < 2; ++_i) \
;         __builtin_amdgcn_global_load_lds((const unsigned*)((const char*)(gbase) + (voff)[_i]), (PG8_LAS unsigned*)(lds + (bufoff) + ldsw + _i * 8192), 16, 0, 0); } while (0)
; #define PG8_LDA(dst, b, h) do { _Pragma("unroll") for (int m = 0; m < 4; ++m) _Pragma("unroll") for (int k = 0; k < 2; ++k) dst[m][k] = *(const PG8_LAS bf16x8*)(lds + PG8_SA(b, h) + aoff + m * 2048 + k * 1024); } while (0)
; #define PG8_MMA(ai, bj, At, Bt) do { __builtin_amdgcn_s_setprio(1); _Pragma("unroll") for (int m = 0; m < 4; ++m) _Pragma("unroll") for (int n = 0; n < 2; ++n) _Pragma("unroll") for (int k = 0; k < 2; ++k) \
;         acc[ai][bj][m][n] = __builtin_amdgcn_mfma_f32_16x16x32_bf16(Bt[n][k], At[m][k], acc[ai][bj][m][n], 0, 0, 0); __builtin_amdgcn_s_setprio(0); } while (0)
; #define PG8_WAIT_V(n) asm volatile("s_waitcnt vmcnt(" #n ")" ::: "memory")
; #define PG8_WAIT_L(n) asm volatile("s_waitcnt lgkmcnt(" #n ")" ::: "memory")
; #define PG8_BAR __builtin_amdgcn_s_barrier()
; #define PG8_SCHED __builtin_amdgcn_sched_barrier(0)
; template <class Epi, class Sched, bool ALIGN_EPI = false, bool SP2 = false, bool PAIR_ACC = false>
; __device__ __forceinline__ void gemm_phase(PG8_LAS unsigned char* lds, const Gemm g, const Sched& S, const Epi& E) {
;     ...
;             PG8_LDA(At, 1, 1); PG8_STAGE(PG8_SB(1, 0), b3, voffB); PG8_STAGE(PG8_SB(1, 1), b3 + hstep, voffB); PG8_STAGE(PG8_SA(1, 0), a3, voffA);
;             PG8_WAIT_V(8); PG8_WAIT_L(0); PG8_BAR; PG8_MMA(1, 0, At, B0); PG8_MMA(1, 1, At, B1); PG8_BAR; PG8_SCHED;
;     ...
;         if (!has_next) break;
;         if (!(PAIR_ACC && cur.pn < 4)) {
; #pragma unroll
;         for (int a = 0; a < 2; ++a)
; #pragma unroll
;             for (int b = 0; b < 2; ++b)
; #pragma unroll
;                 for (int m = 0; m < 4; ++m)
; #pragma unroll
;                     for (int n = 0; n < 2; ++n) acc[a][b][m][n] = (f32x4){0.f, 0.f, 0.f, 0.f};
	s_add_i32 s28, s53, s37
	v_lshl_add_u64 v[164:165], v[164:165], 0, s[20:21]
	s_mov_b32 m0, s28
	ds_read_b128 v[188:191], v151 offset:49152
	ds_read_b128 v[192:195], v151 offset:50176
	ds_read_b128 v[196:199], v151 offset:51200
	ds_read_b128 v[200:203], v151 offset:52224
	ds_read_b128 v[204:207], v151 offset:53248
	ds_read_b128 v[208:211], v151 offset:54272
	ds_read_b128 v[212:215], v151 offset:55296
	ds_read_b128 v[216:219], v151 offset:56320
	global_load_lds_dwordx4 v[164:165], off
	s_add_i32 m0, s28, 0x2000
	s_add_u32 s26, s26, 0xb0080
	v_lshl_add_u64 v[164:165], v[220:221], 0, s[20:21]
	s_addc_u32 s27, s27, 0
	s_add_i32 s28, s54, s37
	global_load_lds_dwordx4 v[164:165], off
	v_lshl_add_u64 v[164:165], s[26:27], 0, v[132:133]
	s_mov_b32 m0, s28
	s_nop 0
	global_load_lds_dwordx4 v[164:165], off
	v_lshl_add_u64 v[164:165], s[26:27], 0, v[136:137]
	s_add_i32 m0, s28, 0x2000
	s_nop 0
	global_load_lds_dwordx4 v[164:165], off
	v_lshl_add_u64 v[164:165], v[222:223], 0, s[20:21]
	s_mov_b32 m0, s43
	s_nop 0
	global_load_lds_dwordx4 v[164:165], off
	v_lshl_add_u64 v[164:165], v[224:225], 0, s[20:21]
	s_mov_b32 m0, s44
	s_nop 0
	global_load_lds_dwordx4 v[164:165], off
	s_waitcnt vmcnt(8)
	s_waitcnt lgkmcnt(0)
	s_barrier
	v_mfma_f32_16x16x32_bf16 v[62:65], v[152:155], v[188:191], v[62:65]
	v_mfma_f32_16x16x32_bf16 v[58:61], v[160:163], v[188:191], v[58:61]
	v_mfma_f32_16x16x32_bf16 v[46:49], v[152:155], v[196:199], v[46:49]
	v_mfma_f32_16x16x32_bf16 v[42:45], v[160:163], v[196:199], v[42:45]
	v_mfma_f32_16x16x32_bf16 v[30:33], v[152:155], v[204:207], v[30:33]
	v_mfma_f32_16x16x32_bf16 v[26:29], v[160:163], v[204:207], v[26:29]
	v_mfma_f32_16x16x32_bf16 v[14:17], v[152:155], v[212:215], v[14:17]
	v_mfma_f32_16x16x32_bf16 v[10:13], v[160:163], v[212:215], v[10:13]
	v_mfma_f32_16x16x32_bf16 v[62:65], v[156:159], v[192:195], v[62:65]
	v_mfma_f32_16x16x32_bf16 v[58:61], v[168:171], v[192:195], v[58:61]
	v_mfma_f32_16x16x32_bf16 v[46:49], v[156:159], v[200:203], v[46:49]
	v_mfma_f32_16x16x32_bf16 v[42:45], v[168:171], v[200:203], v[42:45]
	v_mfma_f32_16x16x32_bf16 v[30:33], v[156:159], v[208:211], v[30:33]
	v_mfma_f32_16x16x32_bf16 v[26:29], v[168:171], v[208:211], v[26:29]
	v_mfma_f32_16x16x32_bf16 v[14:17], v[156:159], v[216:219], v[14:17]
	v_mfma_f32_16x16x32_bf16 v[10:13], v[168:171], v[216:219], v[10:13]
	v_mfma_f32_16x16x32_bf16 v[54:57], v[172:175], v[188:191], v[54:57]
	v_mfma_f32_16x16x32_bf16 v[50:53], v[180:183], v[188:191], v[50:53]
	v_mfma_f32_16x16x32_bf16 v[38:41], v[172:175], v[196:199], v[38:41]
	v_mfma_f32_16x16x32_bf16 v[34:37], v[180:183], v[196:199], v[34:37]
	v_mfma_f32_16x16x32_bf16 v[22:25], v[172:175], v[204:207], v[22:25]
	v_mfma_f32_16x16x32_bf16 v[18:21], v[180:183], v[204:207], v[18:21]
	v_mfma_f32_16x16x32_bf16 v[6:9], v[172:175], v[212:215], v[6:9]
	v_mfma_f32_16x16x32_bf16 v[2:5], v[180:183], v[212:215], v[2:5]
	v_mfma_f32_16x16x32_bf16 v[54:57], v[176:179], v[192:195], v[54:57]
	v_mfma_f32_16x16x32_bf16 v[50:53], v[184:187], v[192:195], v[50:53]
	v_mfma_f32_16x16x32_bf16 v[38:41], v[176:179], v[200:203], v[38:41]
	v_mfma_f32_16x16x32_bf16 v[34:37], v[184:187], v[200:203], v[34:37]
	v_mfma_f32_16x16x32_bf16 v[22:25], v[176:179], v[208:211], v[22:25]
	v_mfma_f32_16x16x32_bf16 v[18:21], v[184:187], v[208:211], v[18:21]
	v_mfma_f32_16x16x32_bf16 v[6:9], v[176:179], v[216:219], v[6:9]
	v_mfma_f32_16x16x32_bf16 v[2:5], v[184:187], v[216:219], v[2:5]
	s_barrier
	s_add_i32 s52, s52, 2
	s_add_u32 s24, s24, 0x100
	s_addc_u32 s25, s25, 0
	s_cmp_gt_u32 s52, 41
	s_cbranch_scc0 .LBB0_1840
	s_add_u32 s24, s50, 0xffffff00
	s_addc_u32 s25, s51, -1
	s_and_b64 vcc, exec, s[6:7]
	s_cbranch_vccnz .LBB0_1827
	v_mov_b32_e32 v2, 0
	s_mov_b32 s14, s47
	s_mov_b32 s31, s48
	s_mov_b64 s[18:19], s[22:23]
	s_mov_b32 s42, s49
	v_mov_b32_e32 v3, v2
	v_mov_b32_e32 v4, v2
	v_mov_b32_e32 v5, v2
	v_mov_b32_e32 v6, v2
	v_mov_b32_e32 v7, v2
	v_mov_b32_e32 v8, v2
	v_mov_b32_e32 v9, v2
	v_mov_b32_e32 v18, v2
	v_mov_b32_e32 v19, v2
	v_mov_b32_e32 v20, v2
	v_mov_b32_e32 v21, v2
	v_mov_b32_e32 v22, v2
	v_mov_b32_e32 v23, v2
	v_mov_b32_e32 v24, v2
	v_mov_b32_e32 v25, v2
	v_mov_b32_e32 v34, v2
	v_mov_b32_e32 v35, v2
	v_mov_b32_e32 v36, v2
	v_mov_b32_e32 v37, v2
	v_mov_b32_e32 v38, v2
	v_mov_b32_e32 v39, v2
	v_mov_b32_e32 v40, v2
	v_mov_b32_e32 v41, v2
	v_mov_b32_e32 v50, v2
	v_mov_b32_e32 v51, v2
	v_mov_b32_e32 v52, v2
	v_mov_b32_e32 v53, v2
	v_mov_b32_e32 v54, v2
	v_mov_b32_e32 v55, v2
	v_mov_b32_e32 v56, v2
	v_mov_b32_e32 v57, v2
	v_mov_b32_e32 v10, v2
	v_mov_b32_e32 v11, v2
	v_mov_b32_e32 v12, v2
	v_mov_b32_e32 v13, v2
	v_mov_b32_e32 v14, v2
	v_mov_b32_e32 v15, v2
	v_mov_b32_e32 v16, v2
	v_mov_b32_e32 v17, v2
	v_mov_b32_e32 v26, v2
	v_mov_b32_e32 v27, v2
	v_mov_b32_e32 v28, v2
	v_mov_b32_e32 v29, v2
	v_mov_b32_e32 v30, v2
	v_mov_b32_e32 v31, v2
	v_mov_b32_e32 v32, v2
	v_mov_b32_e32 v33, v2
	v_mov_b32_e32 v42, v2
	v_mov_b32_e32 v43, v2
	v_mov_b32_e32 v44, v2
	v_mov_b32_e32 v45, v2
	v_mov_b32_e32 v46, v2
	v_mov_b32_e32 v47, v2
	v_mov_b32_e32 v48, v2
	v_mov_b32_e32 v49, v2
	v_mov_b32_e32 v58, v2
	v_mov_b32_e32 v59, v2
	v_mov_b32_e32 v60, v2
	v_mov_b32_e32 v61, v2
	v_mov_b32_e32 v62, v2
	v_mov_b32_e32 v63, v2
	v_mov_b32_e32 v64, v2
	v_mov_b32_e32 v65, v2
	v_mov_b32_e32 v66, v2
	v_mov_b32_e32 v67, v2
	v_mov_b32_e32 v68, v2
	v_mov_b32_e32 v69, v2
	v_mov_b32_e32 v70, v2
	v_mov_b32_e32 v71, v2
	v_mov_b32_e32 v72, v2
	v_mov_b32_e32 v73, v2
	v_mov_b32_e32 v98, v2
	v_mov_b32_e32 v99, v2
	v_mov_b32_e32 v100, v2
	v_mov_b32_e32 v101, v2
	v_mov_b32_e32 v110, v2
	v_mov_b32_e32 v111, v2
	v_mov_b32_e32 v112, v2
	v_mov_b32_e32 v113, v2
	v_mov_b32_e32 v90, v2
	v_mov_b32_e32 v91, v2
	v_mov_b32_e32 v92, v2
	v_mov_b32_e32 v93, v2
	v_mov_b32_e32 v94, v2
	v_mov_b32_e32 v95, v2
	v_mov_b32_e32 v96, v2
	v_mov_b32_e32 v97, v2
	v_mov_b32_e32 v82, v2
	v_mov_b32_e32 v83, v2
	v_mov_b32_e32 v84, v2
	v_mov_b32_e32 v85, v2
	v_mov_b32_e32 v86, v2
	v_mov_b32_e32 v87, v2
	v_mov_b32_e32 v88, v2
	v_mov_b32_e32 v89, v2
	v_mov_b32_e32 v74, v2
	v_mov_b32_e32 v75, v2
	v_mov_b32_e32 v76, v2
	v_mov_b32_e32 v77, v2
	v_mov_b32_e32 v78, v2
	v_mov_b32_e32 v79, v2
	v_mov_b32_e32 v80, v2
	v_mov_b32_e32 v81, v2
	v_mov_b32_e32 v122, v2
	v_mov_b32_e32 v123, v2
	v_mov_b32_e32 v124, v2
	v_mov_b32_e32 v125, v2
	v_mov_b32_e32 v126, v2
	v_mov_b32_e32 v127, v2
	v_mov_b32_e32 v128, v2
	v_mov_b32_e32 v129, v2
	v_mov_b32_e32 v118, v2
	v_mov_b32_e32 v119, v2
	v_mov_b32_e32 v120, v2
	v_mov_b32_e32 v121, v2
	v_mov_b32_e32 v114, v2
	v_mov_b32_e32 v115, v2
	v_mov_b32_e32 v116, v2
	v_mov_b32_e32 v117, v2
	v_mov_b32_e32 v106, v2
	v_mov_b32_e32 v107, v2
	v_mov_b32_e32 v108, v2
	v_mov_b32_e32 v109, v2
	v_mov_b32_e32 v102, v2
	v_mov_b32_e32 v103, v2
	v_mov_b32_e32 v104, v2
	v_mov_b32_e32 v105, v2
	s_andn2_b64 vcc, exec, s[0:1]
	s_cbranch_vccnz .LBB0_1828
